# hoist rss loads in EpiGate/EpiIn/EpiUp epilogues, single weight wait + no store-drain waits in EpiUp, drop per-K-iter vmcnt(0) in up K-loop
# speedup vs baseline: 1.0102x; 1.0102x over previous
; __device__ __forceinline__ float sigmoid_f(float x) { return __builtin_amdgcn_rcpf(1.0f + __builtin_amdgcn_exp2f(-1.4426950409f * x)); }
; __device__ __forceinline__ u32x4 pack8(const f32x4& v0, const f32x4& v1) { u32x4 w; w.x = cvt_pk_bf16(v0[0], v0[1]); w.y = cvt_pk_bf16(v0[2], v0[3]); w.z = cvt_pk_bf16(v1[0], v1[1]); w.w = cvt_pk_bf16(v1[2], v1[3]); return w; }
; __device__ __forceinline__ float row_rstd(const float* rss, long row, int fq) {
;     const f32x4 p = *(const f32x4*)(rss + row * 16 + fq * 4); float s = (p[0] + p[1]) + (p[2] + p[3]); s += __shfl_xor(s, 16); s += __shfl_xor(s, 32);
;     return rsqrtf(s * (1.0f / 1024.0f) + 1e-6f);
;     __device__ __forceinline__ void operator()(const f32x4 (&acc)[2][2][4][2], const Unit& u, int wr, int wc, int fr, int fq) const {
;         const int t = u.pn >> 2, row0 = u.pm * BM + wr * 64 + fr, col0 = (u.pn & 3) * BM + wc * 32 + 8 * fq;
;         bf16_t* base = t ? GB : GA;
; #pragma unroll
;         for (int ai = 0; ai < 2; ++ai)
; #pragma unroll
;             for (int m = 0; m < 4; ++m) { bf16_t* rowp = base + (size_t)(row0 + ai * HALF + m * 16) * 1024 + col0; const float rn = row_rstd(rss, row0 + ai * HALF + m * 16, fq);
; #pragma unroll
;                 for (int bj = 0; bj < 2; ++bj) { f32x4 v0 = acc[ai][bj][m][0] * rn, v1 = acc[ai][bj][m][1] * rn;
; #pragma unroll
;                     for (int j = 0; j < 4; ++j) { v0[j] = sigmoid_f(v0[j]); v1[j] = sigmoid_f(v1[j]); }
;                     *(u32x4*)(rowp + bj * HALF) = pack8(v0, v1); } }
.LBB0_193:
	s_lshl_b32 s9, s31, 8
	s_and_b32 s9, s9, 0x300
	v_or_b32_e32 v143, s9, v148
	v_cmp_lt_i32_e32 vcc, v251, v246
	v_lshlrev_b32_e32 v208, 1, v143
	v_lshl_add_u32 v142, s46, 8, v146
	v_cndmask_b32_e32 v143, v245, v251, vcc
	v_cmp_lt_i32_e32 vcc, v252, v246
	s_cmp_lt_u32 s31, 4
	v_lshlrev_b32_e32 v150, 2, v143
	v_cndmask_b32_e32 v143, v245, v252, vcc
	s_cselect_b32 s47, s43, s27
	s_cselect_b32 s46, s42, s26
	v_lshlrev_b32_e32 v151, 2, v143
	v_ashrrev_i32_e32 v143, 31, v142
	v_lshl_add_u64 v[144:145], s[46:47], 0, v[208:209]
	v_lshlrev_b64 v[152:153], 11, v[142:143]
	v_lshl_add_u64 v[156:157], v[144:145], 0, v[152:153]
	v_lshlrev_b64 v[152:153], 6, v[142:143]
	v_lshl_add_u64 v[152:153], v[136:137], 0, v[152:153]
	v_mov_b32_e32 v190, v152
	v_mov_b32_e32 v191, v153
	v_add_co_u32_e32 v188, vcc, 0x2000, v152
	s_nop 1
	v_addc_co_u32_e32 v189, vcc, 0, v153, vcc
	global_load_dwordx4 v[152:155], v[152:153], off
	global_load_dwordx4 v[160:163], v[190:191], off offset:1024
	global_load_dwordx4 v[164:167], v[190:191], off offset:2048
	global_load_dwordx4 v[168:171], v[190:191], off offset:3072
	global_load_dwordx4 v[172:175], v[188:189], off
	global_load_dwordx4 v[176:179], v[188:189], off offset:1024
	global_load_dwordx4 v[180:183], v[188:189], off offset:2048
	global_load_dwordx4 v[184:187], v[188:189], off offset:3072
	s_mov_b64 s[46:47], -1
	s_waitcnt vmcnt(7)
	v_mov_b32_e32 v158, v153
	v_mov_b32_e32 v159, v154
	v_mov_b32_e32 v153, v155
	v_pk_add_f32 v[152:153], v[158:159], v[152:153]
	s_nop 0
	v_add_f32_e32 v143, v152, v153
	ds_bpermute_b32 v152, v150, v143
	s_waitcnt lgkmcnt(0)
	v_add_f32_e32 v143, v143, v152
	ds_bpermute_b32 v152, v151, v143
	s_waitcnt lgkmcnt(0)
	v_add_f32_e32 v143, v143, v152
	v_fmamk_f32 v143, v143, 0x3a800000, v210
	v_cmp_gt_f32_e32 vcc, s39, v143
	v_mul_f32_e32 v152, 0x4b800000, v143
	s_nop 0
	v_cndmask_b32_e32 v143, v143, v152, vcc
	v_rsq_f32_e32 v143, v143
	s_nop 0
	v_mul_f32_e32 v152, 0x45800000, v143
	v_cndmask_b32_e32 v152, v143, v152, vcc
	v_pk_mul_f32 v[122:123], v[122:123], v[152:153] op_sel_hi:[1,0]
	v_pk_mul_f32 v[120:121], v[120:121], v[152:153] op_sel_hi:[1,0]
	v_mul_f32_e32 v122, 0xbfb8aa3b, v122
	v_mul_f32_e32 v120, 0xbfb8aa3b, v120
	v_mul_f32_e32 v121, 0xbfb8aa3b, v121
	v_exp_f32_e32 v120, v120
	v_exp_f32_e32 v121, v121
	v_exp_f32_e32 v122, v122
	v_pk_mul_f32 v[126:127], v[126:127], v[152:153] op_sel_hi:[1,0]
	v_pk_mul_f32 v[124:125], v[124:125], v[152:153] op_sel_hi:[1,0]
	v_add_f32_e32 v120, 1.0, v120
	v_add_f32_e32 v121, 1.0, v121
	v_add_f32_e32 v122, 1.0, v122
	v_mul_f32_e32 v124, 0xbfb8aa3b, v124
	v_rcp_f32_e32 v143, v120
	v_mul_f32_e32 v120, 0xbfb8aa3b, v125
	v_rcp_f32_e32 v125, v121
	v_mul_f32_e32 v121, 0xbfb8aa3b, v126
	v_rcp_f32_e32 v126, v122
	v_mul_f32_e32 v122, 0xbfb8aa3b, v127
	v_mul_f32_e32 v123, 0xbfb8aa3b, v123
	v_exp_f32_e32 v124, v124
	v_exp_f32_e32 v120, v120
	v_exp_f32_e32 v121, v121
	v_exp_f32_e32 v122, v122
	v_exp_f32_e32 v123, v123
	v_pk_mul_f32 v[114:115], v[114:115], v[152:153] op_sel_hi:[1,0]
	v_pk_mul_f32 v[112:113], v[112:113], v[152:153] op_sel_hi:[1,0]
	v_add_f32_e32 v124, 1.0, v124
	v_add_f32_e32 v120, 1.0, v120
	v_add_f32_e32 v121, 1.0, v121
	v_add_f32_e32 v122, 1.0, v122
	v_add_f32_e32 v123, 1.0, v123
	v_mul_f32_e32 v112, 0xbfb8aa3b, v112
	v_mul_f32_e32 v113, 0xbfb8aa3b, v113
	v_mul_f32_e32 v114, 0xbfb8aa3b, v114
	v_rcp_f32_e32 v124, v124
	v_rcp_f32_e32 v120, v120
	v_rcp_f32_e32 v121, v121
	v_rcp_f32_e32 v122, v122
	v_rcp_f32_e32 v123, v123
	v_exp_f32_e32 v112, v112
	v_exp_f32_e32 v113, v113
	v_exp_f32_e32 v114, v114
	v_cvt_pk_bf16_f32 v120, v124, v120
	v_cvt_pk_bf16_f32 v121, v121, v122
	v_cvt_pk_bf16_f32 v122, v143, v125
	v_cvt_pk_bf16_f32 v123, v126, v123
	v_pk_mul_f32 v[118:119], v[118:119], v[152:153] op_sel_hi:[1,0]
	v_pk_mul_f32 v[116:117], v[116:117], v[152:153] op_sel_hi:[1,0]
	v_add_f32_e32 v112, 1.0, v112
	v_add_f32_e32 v113, 1.0, v113
	v_add_f32_e32 v114, 1.0, v114
	global_store_dwordx4 v[156:157], v[120:123], off
	v_mul_f32_e32 v116, 0xbfb8aa3b, v116
	v_mul_f32_e32 v115, 0xbfb8aa3b, v115
	v_rcp_f32_e32 v120, v112
	v_mul_f32_e32 v112, 0xbfb8aa3b, v117
	v_rcp_f32_e32 v117, v113
	v_mul_f32_e32 v113, 0xbfb8aa3b, v118
	v_rcp_f32_e32 v118, v114
	v_mul_f32_e32 v114, 0xbfb8aa3b, v119
	v_exp_f32_e32 v116, v116
	v_exp_f32_e32 v112, v112
	v_exp_f32_e32 v113, v113
	v_exp_f32_e32 v114, v114
	v_exp_f32_e32 v115, v115
	v_add_f32_e32 v116, 1.0, v116
	v_add_f32_e32 v112, 1.0, v112
	v_add_f32_e32 v113, 1.0, v113
	v_add_f32_e32 v114, 1.0, v114
	v_add_f32_e32 v115, 1.0, v115
	v_rcp_f32_e32 v116, v116
	v_rcp_f32_e32 v112, v112
	v_rcp_f32_e32 v113, v113
	v_rcp_f32_e32 v114, v114
	v_rcp_f32_e32 v115, v115
	v_cvt_pk_bf16_f32 v112, v116, v112
	v_cvt_pk_bf16_f32 v113, v113, v114
	v_cvt_pk_bf16_f32 v114, v120, v117
	v_cvt_pk_bf16_f32 v115, v118, v115
	global_store_dwordx4 v[156:157], v[112:115], off offset:256
	s_nop 1
	v_or_b32_e32 v114, 16, v142
	v_ashrrev_i32_e32 v115, 31, v114
	v_lshlrev_b64 v[112:113], 11, v[114:115]
	v_lshlrev_b64 v[114:115], 6, v[114:115]
	v_lshl_add_u64 v[112:113], v[144:145], 0, v[112:113]
	s_waitcnt vmcnt(8)
	v_mov_b32_e32 v118, v161
	v_mov_b32_e32 v119, v162
	v_mov_b32_e32 v115, v163
	v_mov_b32_e32 v114, v160
	v_pk_add_f32 v[114:115], v[118:119], v[114:115]
	s_nop 0
	v_add_f32_e32 v114, v114, v115
	ds_bpermute_b32 v115, v150, v114
	s_waitcnt lgkmcnt(0)
	v_add_f32_e32 v114, v114, v115
	ds_bpermute_b32 v115, v151, v114
	s_waitcnt lgkmcnt(0)
; __device__ __forceinline__ float sigmoid_f(float x) { return __builtin_amdgcn_rcpf(1.0f + __builtin_amdgcn_exp2f(-1.4426950409f * x)); }
; __device__ __forceinline__ u32x4 pack8(const f32x4& v0, const f32x4& v1) { u32x4 w; w.x = cvt_pk_bf16(v0[0], v0[1]); w.y = cvt_pk_bf16(v0[2], v0[3]); w.z = cvt_pk_bf16(v1[0], v1[1]); w.w = cvt_pk_bf16(v1[2], v1[3]); return w; }
; __device__ __forceinline__ float row_rstd(const float* rss, long row, int fq) {
;     const f32x4 p = *(const f32x4*)(rss + row * 16 + fq * 4); float s = (p[0] + p[1]) + (p[2] + p[3]); s += __shfl_xor(s, 16); s += __shfl_xor(s, 32);
;     return rsqrtf(s * (1.0f / 1024.0f) + 1e-6f);
;     __device__ __forceinline__ void operator()(const f32x4 (&acc)[2][2][4][2], const Unit& u, int wr, int wc, int fr, int fq) const {
;     ...
;             for (int m = 0; m < 4; ++m) { bf16_t* rowp = base + (size_t)(row0 + ai * HALF + m * 16) * 1024 + col0; const float rn = row_rstd(rss, row0 + ai * HALF + m * 16, fq);
; #pragma unroll
;                 for (int bj = 0; bj < 2; ++bj) { f32x4 v0 = acc[ai][bj][m][0] * rn, v1 = acc[ai][bj][m][1] * rn;
; #pragma unroll
;                     for (int j = 0; j < 4; ++j) { v0[j] = sigmoid_f(v0[j]); v1[j] = sigmoid_f(v1[j]); }
;                     *(u32x4*)(rowp + bj * HALF) = pack8(v0, v1); } }
	v_add_f32_e32 v114, v114, v115
	v_fmamk_f32 v114, v114, 0x3a800000, v210
	v_cmp_gt_f32_e32 vcc, s39, v114
	v_mul_f32_e32 v115, 0x4b800000, v114
	s_nop 0
	v_cndmask_b32_e32 v114, v114, v115, vcc
	v_rsq_f32_e32 v114, v114
	s_nop 0
	v_mul_f32_e32 v115, 0x45800000, v114
	v_cndmask_b32_e32 v114, v114, v115, vcc
	v_pk_mul_f32 v[106:107], v[106:107], v[114:115] op_sel_hi:[1,0]
	v_pk_mul_f32 v[104:105], v[104:105], v[114:115] op_sel_hi:[1,0]
	v_mul_f32_e32 v106, 0xbfb8aa3b, v106
	v_mul_f32_e32 v104, 0xbfb8aa3b, v104
	v_mul_f32_e32 v105, 0xbfb8aa3b, v105
	v_exp_f32_e32 v104, v104
	v_exp_f32_e32 v105, v105
	v_exp_f32_e32 v106, v106
	v_pk_mul_f32 v[110:111], v[110:111], v[114:115] op_sel_hi:[1,0]
	v_pk_mul_f32 v[108:109], v[108:109], v[114:115] op_sel_hi:[1,0]
	v_add_f32_e32 v104, 1.0, v104
	v_add_f32_e32 v105, 1.0, v105
	v_add_f32_e32 v106, 1.0, v106
	v_mul_f32_e32 v108, 0xbfb8aa3b, v108
	v_rcp_f32_e32 v115, v104
	v_mul_f32_e32 v104, 0xbfb8aa3b, v109
	v_rcp_f32_e32 v109, v105
	v_mul_f32_e32 v105, 0xbfb8aa3b, v110
	v_rcp_f32_e32 v110, v106
	v_mul_f32_e32 v106, 0xbfb8aa3b, v111
	v_mul_f32_e32 v107, 0xbfb8aa3b, v107
	v_exp_f32_e32 v108, v108
	v_exp_f32_e32 v104, v104
	v_exp_f32_e32 v105, v105
	v_exp_f32_e32 v106, v106
	v_exp_f32_e32 v107, v107
	v_pk_mul_f32 v[98:99], v[98:99], v[114:115] op_sel_hi:[1,0]
	v_pk_mul_f32 v[96:97], v[96:97], v[114:115] op_sel_hi:[1,0]
	v_add_f32_e32 v108, 1.0, v108
	v_add_f32_e32 v104, 1.0, v104
	v_add_f32_e32 v105, 1.0, v105
	v_add_f32_e32 v106, 1.0, v106
	v_add_f32_e32 v107, 1.0, v107
	v_mul_f32_e32 v96, 0xbfb8aa3b, v96
	v_mul_f32_e32 v97, 0xbfb8aa3b, v97
	v_mul_f32_e32 v98, 0xbfb8aa3b, v98
	v_rcp_f32_e32 v108, v108
	v_rcp_f32_e32 v104, v104
	v_rcp_f32_e32 v105, v105
	v_rcp_f32_e32 v106, v106
	v_rcp_f32_e32 v107, v107
	v_exp_f32_e32 v96, v96
	v_exp_f32_e32 v97, v97
	v_exp_f32_e32 v98, v98
	v_cvt_pk_bf16_f32 v104, v108, v104
	v_cvt_pk_bf16_f32 v105, v105, v106
	v_cvt_pk_bf16_f32 v106, v115, v109
	v_cvt_pk_bf16_f32 v107, v110, v107
	v_pk_mul_f32 v[102:103], v[102:103], v[114:115] op_sel_hi:[1,0]
	v_pk_mul_f32 v[100:101], v[100:101], v[114:115] op_sel_hi:[1,0]
	v_add_f32_e32 v96, 1.0, v96
	v_add_f32_e32 v97, 1.0, v97
	v_add_f32_e32 v98, 1.0, v98
	global_store_dwordx4 v[112:113], v[104:107], off
	v_mul_f32_e32 v100, 0xbfb8aa3b, v100
	v_mul_f32_e32 v99, 0xbfb8aa3b, v99
	v_rcp_f32_e32 v104, v96
	v_mul_f32_e32 v96, 0xbfb8aa3b, v101
	v_rcp_f32_e32 v101, v97
	v_mul_f32_e32 v97, 0xbfb8aa3b, v102
	v_rcp_f32_e32 v102, v98
	v_mul_f32_e32 v98, 0xbfb8aa3b, v103
	v_exp_f32_e32 v100, v100
	v_exp_f32_e32 v96, v96
	v_exp_f32_e32 v97, v97
	v_exp_f32_e32 v98, v98
	v_exp_f32_e32 v99, v99
	v_add_f32_e32 v100, 1.0, v100
	v_add_f32_e32 v96, 1.0, v96
	v_add_f32_e32 v97, 1.0, v97
	v_add_f32_e32 v98, 1.0, v98
	v_add_f32_e32 v99, 1.0, v99
	v_rcp_f32_e32 v100, v100
	v_rcp_f32_e32 v96, v96
	v_rcp_f32_e32 v97, v97
	v_rcp_f32_e32 v98, v98
	v_rcp_f32_e32 v99, v99
	v_cvt_pk_bf16_f32 v96, v100, v96
	v_cvt_pk_bf16_f32 v97, v97, v98
	v_cvt_pk_bf16_f32 v98, v104, v101
	v_cvt_pk_bf16_f32 v99, v102, v99
	global_store_dwordx4 v[112:113], v[96:99], off offset:256
	s_nop 1
	v_or_b32_e32 v98, 32, v142
	v_ashrrev_i32_e32 v99, 31, v98
	v_lshlrev_b64 v[96:97], 11, v[98:99]
	v_lshlrev_b64 v[98:99], 6, v[98:99]
	v_lshl_add_u64 v[96:97], v[144:145], 0, v[96:97]
	s_waitcnt vmcnt(9)
	v_mov_b32_e32 v102, v165
	v_mov_b32_e32 v103, v166
	v_mov_b32_e32 v99, v167
	v_mov_b32_e32 v98, v164
	v_pk_add_f32 v[98:99], v[102:103], v[98:99]
	s_nop 0
	v_add_f32_e32 v98, v98, v99
	ds_bpermute_b32 v99, v150, v98
	s_waitcnt lgkmcnt(0)
	v_add_f32_e32 v98, v98, v99
	ds_bpermute_b32 v99, v151, v98
	s_waitcnt lgkmcnt(0)
	v_add_f32_e32 v98, v98, v99
	v_fmamk_f32 v98, v98, 0x3a800000, v210
	v_cmp_gt_f32_e32 vcc, s39, v98
	v_mul_f32_e32 v99, 0x4b800000, v98
	s_nop 0
	v_cndmask_b32_e32 v98, v98, v99, vcc
	v_rsq_f32_e32 v98, v98
	s_nop 0
	v_mul_f32_e32 v99, 0x45800000, v98
	v_cndmask_b32_e32 v98, v98, v99, vcc
	v_pk_mul_f32 v[90:91], v[90:91], v[98:99] op_sel_hi:[1,0]
	v_pk_mul_f32 v[88:89], v[88:89], v[98:99] op_sel_hi:[1,0]
	v_mul_f32_e32 v90, 0xbfb8aa3b, v90
	v_mul_f32_e32 v88, 0xbfb8aa3b, v88
	v_mul_f32_e32 v89, 0xbfb8aa3b, v89
	v_exp_f32_e32 v88, v88
	v_exp_f32_e32 v89, v89
	v_exp_f32_e32 v90, v90
	v_pk_mul_f32 v[94:95], v[94:95], v[98:99] op_sel_hi:[1,0]
	v_pk_mul_f32 v[92:93], v[92:93], v[98:99] op_sel_hi:[1,0]
	v_add_f32_e32 v88, 1.0, v88
	v_add_f32_e32 v89, 1.0, v89
	v_add_f32_e32 v90, 1.0, v90
	v_mul_f32_e32 v92, 0xbfb8aa3b, v92
	v_rcp_f32_e32 v99, v88
	v_mul_f32_e32 v88, 0xbfb8aa3b, v93
	v_rcp_f32_e32 v93, v89
	v_mul_f32_e32 v89, 0xbfb8aa3b, v94
	v_rcp_f32_e32 v94, v90
	v_mul_f32_e32 v90, 0xbfb8aa3b, v95
	v_mul_f32_e32 v91, 0xbfb8aa3b, v91
	v_exp_f32_e32 v92, v92
	v_exp_f32_e32 v88, v88
	v_exp_f32_e32 v89, v89
	v_exp_f32_e32 v90, v90
	v_exp_f32_e32 v91, v91
	v_pk_mul_f32 v[82:83], v[82:83], v[98:99] op_sel_hi:[1,0]
	v_pk_mul_f32 v[80:81], v[80:81], v[98:99] op_sel_hi:[1,0]
	v_add_f32_e32 v92, 1.0, v92
	v_add_f32_e32 v88, 1.0, v88
	v_add_f32_e32 v89, 1.0, v89
	v_add_f32_e32 v90, 1.0, v90
	v_add_f32_e32 v91, 1.0, v91
	v_mul_f32_e32 v80, 0xbfb8aa3b, v80
	v_mul_f32_e32 v81, 0xbfb8aa3b, v81
	v_mul_f32_e32 v82, 0xbfb8aa3b, v82
	v_rcp_f32_e32 v92, v92
	v_rcp_f32_e32 v88, v88
	v_rcp_f32_e32 v89, v89
	v_rcp_f32_e32 v90, v90
	v_rcp_f32_e32 v91, v91
	v_exp_f32_e32 v80, v80
	v_exp_f32_e32 v81, v81
	v_exp_f32_e32 v82, v82
	v_cvt_pk_bf16_f32 v88, v92, v88
	v_cvt_pk_bf16_f32 v89, v89, v90
	v_cvt_pk_bf16_f32 v90, v99, v93
	v_cvt_pk_bf16_f32 v91, v94, v91
	v_pk_mul_f32 v[86:87], v[86:87], v[98:99] op_sel_hi:[1,0]
	v_pk_mul_f32 v[84:85], v[84:85], v[98:99] op_sel_hi:[1,0]
	v_add_f32_e32 v80, 1.0, v80
	v_add_f32_e32 v81, 1.0, v81
	v_add_f32_e32 v82, 1.0, v82
	global_store_dwordx4 v[96:97], v[88:91], off
	v_mul_f32_e32 v84, 0xbfb8aa3b, v84
	v_mul_f32_e32 v83, 0xbfb8aa3b, v83
	v_rcp_f32_e32 v88, v80
	v_mul_f32_e32 v80, 0xbfb8aa3b, v85
	v_rcp_f32_e32 v85, v81
	v_mul_f32_e32 v81, 0xbfb8aa3b, v86
	v_rcp_f32_e32 v86, v82
	v_mul_f32_e32 v82, 0xbfb8aa3b, v87
	v_exp_f32_e32 v84, v84
	v_exp_f32_e32 v80, v80
	v_exp_f32_e32 v81, v81
	v_exp_f32_e32 v82, v82
	v_exp_f32_e32 v83, v83
	v_add_f32_e32 v84, 1.0, v84
	v_add_f32_e32 v80, 1.0, v80
	v_add_f32_e32 v81, 1.0, v81
	v_add_f32_e32 v82, 1.0, v82
	v_add_f32_e32 v83, 1.0, v83
	v_rcp_f32_e32 v84, v84
	v_rcp_f32_e32 v80, v80
	v_rcp_f32_e32 v81, v81
	v_rcp_f32_e32 v82, v82
	v_rcp_f32_e32 v83, v83
	v_cvt_pk_bf16_f32 v80, v84, v80
	v_cvt_pk_bf16_f32 v81, v81, v82
	v_cvt_pk_bf16_f32 v82, v88, v85
	v_cvt_pk_bf16_f32 v83, v86, v83
	global_store_dwordx4 v[96:97], v[80:83], off offset:256
	s_nop 1
	v_or_b32_e32 v82, 48, v142
	v_ashrrev_i32_e32 v83, 31, v82
	v_lshlrev_b64 v[80:81], 11, v[82:83]
	v_lshlrev_b64 v[82:83], 6, v[82:83]
	v_lshl_add_u64 v[80:81], v[144:145], 0, v[80:81]
	s_waitcnt vmcnt(10)
; __device__ __forceinline__ float sigmoid_f(float x) { return __builtin_amdgcn_rcpf(1.0f + __builtin_amdgcn_exp2f(-1.4426950409f * x)); }
; __device__ __forceinline__ u32x4 pack8(const f32x4& v0, const f32x4& v1) { u32x4 w; w.x = cvt_pk_bf16(v0[0], v0[1]); w.y = cvt_pk_bf16(v0[2], v0[3]); w.z = cvt_pk_bf16(v1[0], v1[1]); w.w = cvt_pk_bf16(v1[2], v1[3]); return w; }
; __device__ __forceinline__ float row_rstd(const float* rss, long row, int fq) {
;     const f32x4 p = *(const f32x4*)(rss + row * 16 + fq * 4); float s = (p[0] + p[1]) + (p[2] + p[3]); s += __shfl_xor(s, 16); s += __shfl_xor(s, 32);
;     return rsqrtf(s * (1.0f / 1024.0f) + 1e-6f);
;     __device__ __forceinline__ void operator()(const f32x4 (&acc)[2][2][4][2], const Unit& u, int wr, int wc, int fr, int fq) const {
;     ...
;             for (int m = 0; m < 4; ++m) { bf16_t* rowp = base + (size_t)(row0 + ai * HALF + m * 16) * 1024 + col0; const float rn = row_rstd(rss, row0 + ai * HALF + m * 16, fq);
; #pragma unroll
;                 for (int bj = 0; bj < 2; ++bj) { f32x4 v0 = acc[ai][bj][m][0] * rn, v1 = acc[ai][bj][m][1] * rn;
; #pragma unroll
;                     for (int j = 0; j < 4; ++j) { v0[j] = sigmoid_f(v0[j]); v1[j] = sigmoid_f(v1[j]); }
;                     *(u32x4*)(rowp + bj * HALF) = pack8(v0, v1); } }
	v_mov_b32_e32 v86, v169
	v_mov_b32_e32 v87, v170
	v_mov_b32_e32 v83, v171
	v_mov_b32_e32 v82, v168
	v_pk_add_f32 v[82:83], v[86:87], v[82:83]
	s_nop 0
	v_add_f32_e32 v82, v82, v83
	ds_bpermute_b32 v83, v150, v82
	s_waitcnt lgkmcnt(0)
	v_add_f32_e32 v82, v82, v83
	ds_bpermute_b32 v83, v151, v82
	s_waitcnt lgkmcnt(0)
	v_add_f32_e32 v82, v82, v83
	v_fmamk_f32 v82, v82, 0x3a800000, v210
	v_cmp_gt_f32_e32 vcc, s39, v82
	v_mul_f32_e32 v83, 0x4b800000, v82
	s_nop 0
	v_cndmask_b32_e32 v82, v82, v83, vcc
	v_rsq_f32_e32 v82, v82
	s_nop 0
	v_mul_f32_e32 v83, 0x45800000, v82
	v_cndmask_b32_e32 v82, v82, v83, vcc
	v_pk_mul_f32 v[74:75], v[74:75], v[82:83] op_sel_hi:[1,0]
	v_pk_mul_f32 v[72:73], v[72:73], v[82:83] op_sel_hi:[1,0]
	v_mul_f32_e32 v74, 0xbfb8aa3b, v74
	v_mul_f32_e32 v72, 0xbfb8aa3b, v72
	v_mul_f32_e32 v73, 0xbfb8aa3b, v73
	v_exp_f32_e32 v72, v72
	v_exp_f32_e32 v73, v73
	v_exp_f32_e32 v74, v74
	v_pk_mul_f32 v[78:79], v[78:79], v[82:83] op_sel_hi:[1,0]
	v_pk_mul_f32 v[76:77], v[76:77], v[82:83] op_sel_hi:[1,0]
	v_add_f32_e32 v72, 1.0, v72
	v_add_f32_e32 v73, 1.0, v73
	v_add_f32_e32 v74, 1.0, v74
	v_mul_f32_e32 v76, 0xbfb8aa3b, v76
	v_rcp_f32_e32 v83, v72
	v_mul_f32_e32 v72, 0xbfb8aa3b, v77
	v_rcp_f32_e32 v77, v73
	v_mul_f32_e32 v73, 0xbfb8aa3b, v78
	v_rcp_f32_e32 v78, v74
	v_mul_f32_e32 v74, 0xbfb8aa3b, v79
	v_mul_f32_e32 v75, 0xbfb8aa3b, v75
	v_exp_f32_e32 v76, v76
	v_exp_f32_e32 v72, v72
	v_exp_f32_e32 v73, v73
	v_exp_f32_e32 v74, v74
	v_exp_f32_e32 v75, v75
	v_pk_mul_f32 v[66:67], v[66:67], v[82:83] op_sel_hi:[1,0]
	v_pk_mul_f32 v[64:65], v[64:65], v[82:83] op_sel_hi:[1,0]
	v_add_f32_e32 v76, 1.0, v76
	v_add_f32_e32 v72, 1.0, v72
	v_add_f32_e32 v73, 1.0, v73
	v_add_f32_e32 v74, 1.0, v74
	v_add_f32_e32 v75, 1.0, v75
	v_mul_f32_e32 v64, 0xbfb8aa3b, v64
	v_mul_f32_e32 v65, 0xbfb8aa3b, v65
	v_mul_f32_e32 v66, 0xbfb8aa3b, v66
	v_rcp_f32_e32 v76, v76
	v_rcp_f32_e32 v72, v72
	v_rcp_f32_e32 v73, v73
	v_rcp_f32_e32 v74, v74
	v_rcp_f32_e32 v75, v75
	v_exp_f32_e32 v64, v64
	v_exp_f32_e32 v65, v65
	v_exp_f32_e32 v66, v66
	v_cvt_pk_bf16_f32 v72, v76, v72
	v_cvt_pk_bf16_f32 v73, v73, v74
	v_cvt_pk_bf16_f32 v74, v83, v77
	v_cvt_pk_bf16_f32 v75, v78, v75
	v_pk_mul_f32 v[70:71], v[70:71], v[82:83] op_sel_hi:[1,0]
	v_pk_mul_f32 v[68:69], v[68:69], v[82:83] op_sel_hi:[1,0]
	v_add_f32_e32 v64, 1.0, v64
	v_add_f32_e32 v65, 1.0, v65
	v_add_f32_e32 v66, 1.0, v66
	global_store_dwordx4 v[80:81], v[72:75], off
	v_mul_f32_e32 v68, 0xbfb8aa3b, v68
	v_mul_f32_e32 v67, 0xbfb8aa3b, v67
	v_rcp_f32_e32 v72, v64
	v_mul_f32_e32 v64, 0xbfb8aa3b, v69
	v_rcp_f32_e32 v69, v65
	v_mul_f32_e32 v65, 0xbfb8aa3b, v70
	v_rcp_f32_e32 v70, v66
	v_mul_f32_e32 v66, 0xbfb8aa3b, v71
	v_exp_f32_e32 v68, v68
	v_exp_f32_e32 v64, v64
	v_exp_f32_e32 v65, v65
	v_exp_f32_e32 v66, v66
	v_exp_f32_e32 v67, v67
	v_add_f32_e32 v68, 1.0, v68
	v_add_f32_e32 v64, 1.0, v64
	v_add_f32_e32 v65, 1.0, v65
	v_add_f32_e32 v66, 1.0, v66
	v_add_f32_e32 v67, 1.0, v67
	v_rcp_f32_e32 v68, v68
	v_rcp_f32_e32 v64, v64
	v_rcp_f32_e32 v65, v65
	v_rcp_f32_e32 v66, v66
	v_rcp_f32_e32 v67, v67
	v_cvt_pk_bf16_f32 v64, v68, v64
	v_cvt_pk_bf16_f32 v65, v65, v66
	v_cvt_pk_bf16_f32 v66, v72, v69
	v_cvt_pk_bf16_f32 v67, v70, v67
	global_store_dwordx4 v[80:81], v[64:67], off offset:256
	s_nop 1
	v_add_u32_e32 v66, 0x80, v142
	v_ashrrev_i32_e32 v67, 31, v66
	v_lshlrev_b64 v[64:65], 11, v[66:67]
	v_lshlrev_b64 v[66:67], 6, v[66:67]
	v_lshl_add_u64 v[64:65], v[144:145], 0, v[64:65]
	s_waitcnt vmcnt(11)
	v_mov_b32_e32 v70, v173
	v_mov_b32_e32 v71, v174
	v_mov_b32_e32 v67, v175
	v_mov_b32_e32 v66, v172
	v_pk_add_f32 v[66:67], v[70:71], v[66:67]
	s_nop 0
	v_add_f32_e32 v66, v66, v67
	ds_bpermute_b32 v67, v150, v66
	s_waitcnt lgkmcnt(0)
	v_add_f32_e32 v66, v66, v67
	ds_bpermute_b32 v67, v151, v66
	s_waitcnt lgkmcnt(0)
	v_add_f32_e32 v66, v66, v67
	v_fmamk_f32 v66, v66, 0x3a800000, v210
	v_cmp_gt_f32_e32 vcc, s39, v66
	v_mul_f32_e32 v67, 0x4b800000, v66
	s_nop 0
	v_cndmask_b32_e32 v66, v66, v67, vcc
	v_rsq_f32_e32 v66, v66
	s_nop 0
	v_mul_f32_e32 v67, 0x45800000, v66
	v_cndmask_b32_e32 v66, v66, v67, vcc
	v_pk_mul_f32 v[58:59], v[58:59], v[66:67] op_sel_hi:[1,0]
	v_pk_mul_f32 v[56:57], v[56:57], v[66:67] op_sel_hi:[1,0]
	v_mul_f32_e32 v58, 0xbfb8aa3b, v58
	v_mul_f32_e32 v56, 0xbfb8aa3b, v56
	v_mul_f32_e32 v57, 0xbfb8aa3b, v57
	v_exp_f32_e32 v56, v56
	v_exp_f32_e32 v57, v57
	v_exp_f32_e32 v58, v58
	v_pk_mul_f32 v[62:63], v[62:63], v[66:67] op_sel_hi:[1,0]
	v_pk_mul_f32 v[60:61], v[60:61], v[66:67] op_sel_hi:[1,0]
	v_add_f32_e32 v56, 1.0, v56
	v_add_f32_e32 v57, 1.0, v57
	v_add_f32_e32 v58, 1.0, v58
	v_mul_f32_e32 v60, 0xbfb8aa3b, v60
	v_rcp_f32_e32 v67, v56
	v_mul_f32_e32 v56, 0xbfb8aa3b, v61
	v_rcp_f32_e32 v61, v57
	v_mul_f32_e32 v57, 0xbfb8aa3b, v62
	v_rcp_f32_e32 v62, v58
	v_mul_f32_e32 v58, 0xbfb8aa3b, v63
	v_mul_f32_e32 v59, 0xbfb8aa3b, v59
	v_exp_f32_e32 v60, v60
	v_exp_f32_e32 v56, v56
	v_exp_f32_e32 v57, v57
	v_exp_f32_e32 v58, v58
	v_exp_f32_e32 v59, v59
	v_pk_mul_f32 v[50:51], v[50:51], v[66:67] op_sel_hi:[1,0]
	v_pk_mul_f32 v[48:49], v[48:49], v[66:67] op_sel_hi:[1,0]
	v_add_f32_e32 v60, 1.0, v60
	v_add_f32_e32 v56, 1.0, v56
	v_add_f32_e32 v57, 1.0, v57
	v_add_f32_e32 v58, 1.0, v58
	v_add_f32_e32 v59, 1.0, v59
	v_mul_f32_e32 v48, 0xbfb8aa3b, v48
	v_mul_f32_e32 v49, 0xbfb8aa3b, v49
	v_mul_f32_e32 v50, 0xbfb8aa3b, v50
	v_rcp_f32_e32 v60, v60
	v_rcp_f32_e32 v56, v56
	v_rcp_f32_e32 v57, v57
	v_rcp_f32_e32 v58, v58
	v_rcp_f32_e32 v59, v59
	v_exp_f32_e32 v48, v48
	v_exp_f32_e32 v49, v49
	v_exp_f32_e32 v50, v50
	v_cvt_pk_bf16_f32 v56, v60, v56
	v_cvt_pk_bf16_f32 v57, v57, v58
	v_cvt_pk_bf16_f32 v58, v67, v61
	v_cvt_pk_bf16_f32 v59, v62, v59
	v_pk_mul_f32 v[54:55], v[54:55], v[66:67] op_sel_hi:[1,0]
	v_pk_mul_f32 v[52:53], v[52:53], v[66:67] op_sel_hi:[1,0]
	v_add_f32_e32 v48, 1.0, v48
	v_add_f32_e32 v49, 1.0, v49
	v_add_f32_e32 v50, 1.0, v50
	global_store_dwordx4 v[64:65], v[56:59], off
	v_mul_f32_e32 v52, 0xbfb8aa3b, v52
	v_mul_f32_e32 v51, 0xbfb8aa3b, v51
	v_rcp_f32_e32 v56, v48
	v_mul_f32_e32 v48, 0xbfb8aa3b, v53
	v_rcp_f32_e32 v53, v49
	v_mul_f32_e32 v49, 0xbfb8aa3b, v54
	v_rcp_f32_e32 v54, v50
	v_mul_f32_e32 v50, 0xbfb8aa3b, v55
	v_exp_f32_e32 v52, v52
	v_exp_f32_e32 v48, v48
	v_exp_f32_e32 v49, v49
	v_exp_f32_e32 v50, v50
	v_exp_f32_e32 v51, v51
	v_add_f32_e32 v52, 1.0, v52
	v_add_f32_e32 v48, 1.0, v48
	v_add_f32_e32 v49, 1.0, v49
	v_add_f32_e32 v50, 1.0, v50
	v_add_f32_e32 v51, 1.0, v51
	v_rcp_f32_e32 v52, v52
	v_rcp_f32_e32 v48, v48
	v_rcp_f32_e32 v49, v49
	v_rcp_f32_e32 v50, v50
	v_rcp_f32_e32 v51, v51
	v_cvt_pk_bf16_f32 v48, v52, v48
	v_cvt_pk_bf16_f32 v49, v49, v50
	v_cvt_pk_bf16_f32 v50, v56, v53
	v_cvt_pk_bf16_f32 v51, v54, v51
	global_store_dwordx4 v[64:65], v[48:51], off offset:256
	s_nop 1
	v_add_u32_e32 v50, 0x90, v142
	v_ashrrev_i32_e32 v51, 31, v50
	v_lshlrev_b64 v[48:49], 11, v[50:51]
	v_lshlrev_b64 v[50:51], 6, v[50:51]
	v_lshl_add_u64 v[48:49], v[144:145], 0, v[48:49]
	s_waitcnt vmcnt(12)
; __device__ __forceinline__ float sigmoid_f(float x) { return __builtin_amdgcn_rcpf(1.0f + __builtin_amdgcn_exp2f(-1.4426950409f * x)); }
; __device__ __forceinline__ u32x4 pack8(const f32x4& v0, const f32x4& v1) { u32x4 w; w.x = cvt_pk_bf16(v0[0], v0[1]); w.y = cvt_pk_bf16(v0[2], v0[3]); w.z = cvt_pk_bf16(v1[0], v1[1]); w.w = cvt_pk_bf16(v1[2], v1[3]); return w; }
; __device__ __forceinline__ float row_rstd(const float* rss, long row, int fq) {
;     const f32x4 p = *(const f32x4*)(rss + row * 16 + fq * 4); float s = (p[0] + p[1]) + (p[2] + p[3]); s += __shfl_xor(s, 16); s += __shfl_xor(s, 32);
;     return rsqrtf(s * (1.0f / 1024.0f) + 1e-6f);
;     __device__ __forceinline__ void operator()(const f32x4 (&acc)[2][2][4][2], const Unit& u, int wr, int wc, int fr, int fq) const {
;     ...
;             for (int m = 0; m < 4; ++m) { bf16_t* rowp = base + (size_t)(row0 + ai * HALF + m * 16) * 1024 + col0; const float rn = row_rstd(rss, row0 + ai * HALF + m * 16, fq);
; #pragma unroll
;                 for (int bj = 0; bj < 2; ++bj) { f32x4 v0 = acc[ai][bj][m][0] * rn, v1 = acc[ai][bj][m][1] * rn;
; #pragma unroll
;                     for (int j = 0; j < 4; ++j) { v0[j] = sigmoid_f(v0[j]); v1[j] = sigmoid_f(v1[j]); }
;                     *(u32x4*)(rowp + bj * HALF) = pack8(v0, v1); } }
	v_mov_b32_e32 v54, v177
	v_mov_b32_e32 v55, v178
	v_mov_b32_e32 v51, v179
	v_mov_b32_e32 v50, v176
	v_pk_add_f32 v[50:51], v[54:55], v[50:51]
	s_nop 0
	v_add_f32_e32 v50, v50, v51
	ds_bpermute_b32 v51, v150, v50
	s_waitcnt lgkmcnt(0)
	v_add_f32_e32 v50, v50, v51
	ds_bpermute_b32 v51, v151, v50
	s_waitcnt lgkmcnt(0)
	v_add_f32_e32 v50, v50, v51
	v_fmamk_f32 v50, v50, 0x3a800000, v210
	v_cmp_gt_f32_e32 vcc, s39, v50
	v_mul_f32_e32 v51, 0x4b800000, v50
	s_nop 0
	v_cndmask_b32_e32 v50, v50, v51, vcc
	v_rsq_f32_e32 v50, v50
	s_nop 0
	v_mul_f32_e32 v51, 0x45800000, v50
	v_cndmask_b32_e32 v50, v50, v51, vcc
	v_pk_mul_f32 v[42:43], v[42:43], v[50:51] op_sel_hi:[1,0]
	v_pk_mul_f32 v[40:41], v[40:41], v[50:51] op_sel_hi:[1,0]
	v_mul_f32_e32 v42, 0xbfb8aa3b, v42
	v_mul_f32_e32 v40, 0xbfb8aa3b, v40
	v_mul_f32_e32 v41, 0xbfb8aa3b, v41
	v_exp_f32_e32 v40, v40
	v_exp_f32_e32 v41, v41
	v_exp_f32_e32 v42, v42
	v_pk_mul_f32 v[46:47], v[46:47], v[50:51] op_sel_hi:[1,0]
	v_pk_mul_f32 v[44:45], v[44:45], v[50:51] op_sel_hi:[1,0]
	v_add_f32_e32 v40, 1.0, v40
	v_add_f32_e32 v41, 1.0, v41
	v_add_f32_e32 v42, 1.0, v42
	v_mul_f32_e32 v44, 0xbfb8aa3b, v44
	v_rcp_f32_e32 v51, v40
	v_mul_f32_e32 v40, 0xbfb8aa3b, v45
	v_rcp_f32_e32 v45, v41
	v_mul_f32_e32 v41, 0xbfb8aa3b, v46
	v_rcp_f32_e32 v46, v42
	v_mul_f32_e32 v42, 0xbfb8aa3b, v47
	v_mul_f32_e32 v43, 0xbfb8aa3b, v43
	v_exp_f32_e32 v44, v44
	v_exp_f32_e32 v40, v40
	v_exp_f32_e32 v41, v41
	v_exp_f32_e32 v42, v42
	v_exp_f32_e32 v43, v43
	v_pk_mul_f32 v[34:35], v[34:35], v[50:51] op_sel_hi:[1,0]
	v_pk_mul_f32 v[32:33], v[32:33], v[50:51] op_sel_hi:[1,0]
	v_add_f32_e32 v44, 1.0, v44
	v_add_f32_e32 v40, 1.0, v40
	v_add_f32_e32 v41, 1.0, v41
	v_add_f32_e32 v42, 1.0, v42
	v_add_f32_e32 v43, 1.0, v43
	v_mul_f32_e32 v32, 0xbfb8aa3b, v32
	v_mul_f32_e32 v33, 0xbfb8aa3b, v33
	v_mul_f32_e32 v34, 0xbfb8aa3b, v34
	v_rcp_f32_e32 v44, v44
	v_rcp_f32_e32 v40, v40
	v_rcp_f32_e32 v41, v41
	v_rcp_f32_e32 v42, v42
	v_rcp_f32_e32 v43, v43
	v_exp_f32_e32 v32, v32
	v_exp_f32_e32 v33, v33
	v_exp_f32_e32 v34, v34
	v_cvt_pk_bf16_f32 v40, v44, v40
	v_cvt_pk_bf16_f32 v41, v41, v42
	v_cvt_pk_bf16_f32 v42, v51, v45
	v_cvt_pk_bf16_f32 v43, v46, v43
	v_pk_mul_f32 v[38:39], v[38:39], v[50:51] op_sel_hi:[1,0]
	v_pk_mul_f32 v[36:37], v[36:37], v[50:51] op_sel_hi:[1,0]
	v_add_f32_e32 v32, 1.0, v32
	v_add_f32_e32 v33, 1.0, v33
	v_add_f32_e32 v34, 1.0, v34
	global_store_dwordx4 v[48:49], v[40:43], off
	v_mul_f32_e32 v36, 0xbfb8aa3b, v36
	v_mul_f32_e32 v35, 0xbfb8aa3b, v35
	v_rcp_f32_e32 v40, v32
	v_mul_f32_e32 v32, 0xbfb8aa3b, v37
	v_rcp_f32_e32 v37, v33
	v_mul_f32_e32 v33, 0xbfb8aa3b, v38
	v_rcp_f32_e32 v38, v34
	v_mul_f32_e32 v34, 0xbfb8aa3b, v39
	v_exp_f32_e32 v36, v36
	v_exp_f32_e32 v32, v32
	v_exp_f32_e32 v33, v33
	v_exp_f32_e32 v34, v34
	v_exp_f32_e32 v35, v35
	v_add_f32_e32 v36, 1.0, v36
	v_add_f32_e32 v32, 1.0, v32
	v_add_f32_e32 v33, 1.0, v33
	v_add_f32_e32 v34, 1.0, v34
	v_add_f32_e32 v35, 1.0, v35
	v_rcp_f32_e32 v36, v36
	v_rcp_f32_e32 v32, v32
	v_rcp_f32_e32 v33, v33
	v_rcp_f32_e32 v34, v34
	v_rcp_f32_e32 v35, v35
	v_cvt_pk_bf16_f32 v32, v36, v32
	v_cvt_pk_bf16_f32 v33, v33, v34
	v_cvt_pk_bf16_f32 v34, v40, v37
	v_cvt_pk_bf16_f32 v35, v38, v35
	global_store_dwordx4 v[48:49], v[32:35], off offset:256
	s_nop 1
	v_add_u32_e32 v34, 0xa0, v142
	v_ashrrev_i32_e32 v35, 31, v34
	v_lshlrev_b64 v[32:33], 11, v[34:35]
	v_lshlrev_b64 v[34:35], 6, v[34:35]
	v_lshl_add_u64 v[32:33], v[144:145], 0, v[32:33]
	s_waitcnt vmcnt(13)
	v_mov_b32_e32 v38, v181
	v_mov_b32_e32 v39, v182
	v_mov_b32_e32 v35, v183
	v_mov_b32_e32 v34, v180
	v_pk_add_f32 v[34:35], v[38:39], v[34:35]
	s_nop 0
	v_add_f32_e32 v34, v34, v35
	ds_bpermute_b32 v35, v150, v34
	s_waitcnt lgkmcnt(0)
	v_add_f32_e32 v34, v34, v35
	ds_bpermute_b32 v35, v151, v34
	s_waitcnt lgkmcnt(0)
; __device__ __forceinline__ float sigmoid_f(float x) { return __builtin_amdgcn_rcpf(1.0f + __builtin_amdgcn_exp2f(-1.4426950409f * x)); }
; __device__ __forceinline__ u32x4 pack8(const f32x4& v0, const f32x4& v1) { u32x4 w; w.x = cvt_pk_bf16(v0[0], v0[1]); w.y = cvt_pk_bf16(v0[2], v0[3]); w.z = cvt_pk_bf16(v1[0], v1[1]); w.w = cvt_pk_bf16(v1[2], v1[3]); return w; }
; #define PG8_BAR __builtin_amdgcn_s_barrier()
;     __device__ __forceinline__ void operator()(const f32x4 (&acc)[2][2][4][2], const Unit& u, int wr, int wc, int fr, int fq) const {
;     ...
;             for (int m = 0; m < 4; ++m) { bf16_t* rowp = base + (size_t)(row0 + ai * HALF + m * 16) * 1024 + col0; const float rn = row_rstd(rss, row0 + ai * HALF + m * 16, fq);
; #pragma unroll
;                 for (int bj = 0; bj < 2; ++bj) { f32x4 v0 = acc[ai][bj][m][0] * rn, v1 = acc[ai][bj][m][1] * rn;
; #pragma unroll
;                     for (int j = 0; j < 4; ++j) { v0[j] = sigmoid_f(v0[j]); v1[j] = sigmoid_f(v1[j]); }
;                     *(u32x4*)(rowp + bj * HALF) = pack8(v0, v1); } }
; template <class Epi, class Sched, bool ALIGN_EPI = false, bool SP2 = false>
; __device__ __forceinline__ void gemm_phase(PG8_LAS unsigned char* lds, const Gemm g, const Sched& S, const Epi& E) {
;     ...
;         if (!has_next) break;
; #pragma unroll
;         for (int a = 0; a < 2; ++a)
; #pragma unroll
;             for (int b = 0; b < 2; ++b)
; #pragma unroll
;                 for (int m = 0; m < 4; ++m)
; #pragma unroll
;                     for (int n = 0; n < 2; ++n) acc[a][b][m][n] = (f32x4){0.f, 0.f, 0.f, 0.f};
;         cur = nxt; cA = nA; cB = nB; ++ui;
;         if constexpr (ALIGN_EPI) { if (wr == 1) PG8_BAR; }
	v_add_f32_e32 v34, v34, v35
	v_fmamk_f32 v34, v34, 0x3a800000, v210
	v_cmp_gt_f32_e32 vcc, s39, v34
	v_mul_f32_e32 v35, 0x4b800000, v34
	s_nop 0
	v_cndmask_b32_e32 v34, v34, v35, vcc
	v_rsq_f32_e32 v34, v34
	s_nop 0
	v_mul_f32_e32 v35, 0x45800000, v34
	v_cndmask_b32_e32 v34, v34, v35, vcc
	v_pk_mul_f32 v[26:27], v[26:27], v[34:35] op_sel_hi:[1,0]
	v_pk_mul_f32 v[24:25], v[24:25], v[34:35] op_sel_hi:[1,0]
	v_mul_f32_e32 v26, 0xbfb8aa3b, v26
	v_mul_f32_e32 v24, 0xbfb8aa3b, v24
	v_mul_f32_e32 v25, 0xbfb8aa3b, v25
	v_exp_f32_e32 v24, v24
	v_exp_f32_e32 v25, v25
	v_exp_f32_e32 v26, v26
	v_pk_mul_f32 v[30:31], v[30:31], v[34:35] op_sel_hi:[1,0]
	v_pk_mul_f32 v[28:29], v[28:29], v[34:35] op_sel_hi:[1,0]
	v_add_f32_e32 v24, 1.0, v24
	v_add_f32_e32 v25, 1.0, v25
	v_add_f32_e32 v26, 1.0, v26
	v_mul_f32_e32 v28, 0xbfb8aa3b, v28
	v_rcp_f32_e32 v35, v24
	v_mul_f32_e32 v24, 0xbfb8aa3b, v29
	v_rcp_f32_e32 v29, v25
	v_mul_f32_e32 v25, 0xbfb8aa3b, v30
	v_rcp_f32_e32 v30, v26
	v_mul_f32_e32 v26, 0xbfb8aa3b, v31
	v_mul_f32_e32 v27, 0xbfb8aa3b, v27
	v_exp_f32_e32 v28, v28
	v_exp_f32_e32 v24, v24
	v_exp_f32_e32 v25, v25
	v_exp_f32_e32 v26, v26
	v_exp_f32_e32 v27, v27
	v_pk_mul_f32 v[18:19], v[18:19], v[34:35] op_sel_hi:[1,0]
	v_pk_mul_f32 v[16:17], v[16:17], v[34:35] op_sel_hi:[1,0]
	v_add_f32_e32 v28, 1.0, v28
	v_add_f32_e32 v24, 1.0, v24
	v_add_f32_e32 v25, 1.0, v25
	v_add_f32_e32 v26, 1.0, v26
	v_add_f32_e32 v27, 1.0, v27
	v_mul_f32_e32 v16, 0xbfb8aa3b, v16
	v_mul_f32_e32 v17, 0xbfb8aa3b, v17
	v_mul_f32_e32 v18, 0xbfb8aa3b, v18
	v_rcp_f32_e32 v28, v28
	v_rcp_f32_e32 v24, v24
	v_rcp_f32_e32 v25, v25
	v_rcp_f32_e32 v26, v26
	v_rcp_f32_e32 v27, v27
	v_exp_f32_e32 v16, v16
	v_exp_f32_e32 v17, v17
	v_exp_f32_e32 v18, v18
	v_cvt_pk_bf16_f32 v24, v28, v24
	v_cvt_pk_bf16_f32 v25, v25, v26
	v_cvt_pk_bf16_f32 v26, v35, v29
	v_cvt_pk_bf16_f32 v27, v30, v27
	v_pk_mul_f32 v[22:23], v[22:23], v[34:35] op_sel_hi:[1,0]
	v_pk_mul_f32 v[20:21], v[20:21], v[34:35] op_sel_hi:[1,0]
	v_add_f32_e32 v16, 1.0, v16
	v_add_f32_e32 v17, 1.0, v17
	v_add_f32_e32 v18, 1.0, v18
	global_store_dwordx4 v[32:33], v[24:27], off
	v_mul_f32_e32 v20, 0xbfb8aa3b, v20
	v_mul_f32_e32 v19, 0xbfb8aa3b, v19
	v_rcp_f32_e32 v24, v16
	v_mul_f32_e32 v16, 0xbfb8aa3b, v21
	v_rcp_f32_e32 v21, v17
	v_mul_f32_e32 v17, 0xbfb8aa3b, v22
	v_rcp_f32_e32 v22, v18
	v_mul_f32_e32 v18, 0xbfb8aa3b, v23
	v_exp_f32_e32 v20, v20
	v_exp_f32_e32 v16, v16
	v_exp_f32_e32 v17, v17
	v_exp_f32_e32 v18, v18
	v_exp_f32_e32 v19, v19
	v_add_f32_e32 v20, 1.0, v20
	v_add_f32_e32 v16, 1.0, v16
	v_add_f32_e32 v17, 1.0, v17
	v_add_f32_e32 v18, 1.0, v18
	v_add_f32_e32 v19, 1.0, v19
	v_rcp_f32_e32 v20, v20
	v_rcp_f32_e32 v16, v16
	v_rcp_f32_e32 v17, v17
	v_rcp_f32_e32 v18, v18
	v_rcp_f32_e32 v19, v19
	v_cvt_pk_bf16_f32 v16, v20, v16
	v_cvt_pk_bf16_f32 v17, v17, v18
	v_cvt_pk_bf16_f32 v18, v24, v21
	v_cvt_pk_bf16_f32 v19, v22, v19
	global_store_dwordx4 v[32:33], v[16:19], off offset:256
	s_nop 1
	v_add_u32_e32 v18, 0xb0, v142
	v_ashrrev_i32_e32 v19, 31, v18
	v_lshlrev_b64 v[16:17], 11, v[18:19]
	v_lshlrev_b64 v[18:19], 6, v[18:19]
	v_lshl_add_u64 v[16:17], v[144:145], 0, v[16:17]
	s_waitcnt vmcnt(14)
	v_mov_b32_e32 v22, v185
	v_mov_b32_e32 v23, v186
	v_mov_b32_e32 v19, v187
	v_mov_b32_e32 v18, v184
	v_pk_add_f32 v[18:19], v[22:23], v[18:19]
	s_nop 0
	v_add_f32_e32 v18, v18, v19
	ds_bpermute_b32 v19, v150, v18
	s_waitcnt lgkmcnt(0)
	v_add_f32_e32 v18, v18, v19
	ds_bpermute_b32 v19, v151, v18
	s_waitcnt lgkmcnt(0)
	v_add_f32_e32 v18, v18, v19
	v_fmamk_f32 v18, v18, 0x3a800000, v210
	v_cmp_gt_f32_e32 vcc, s39, v18
	v_mul_f32_e32 v19, 0x4b800000, v18
	s_nop 0
	v_cndmask_b32_e32 v18, v18, v19, vcc
	v_rsq_f32_e32 v18, v18
	s_nop 0
	v_mul_f32_e32 v19, 0x45800000, v18
	v_cndmask_b32_e32 v18, v18, v19, vcc
	v_pk_mul_f32 v[10:11], v[10:11], v[18:19] op_sel_hi:[1,0]
	v_pk_mul_f32 v[8:9], v[8:9], v[18:19] op_sel_hi:[1,0]
	v_mul_f32_e32 v10, 0xbfb8aa3b, v10
	v_mul_f32_e32 v8, 0xbfb8aa3b, v8
	v_mul_f32_e32 v9, 0xbfb8aa3b, v9
	v_exp_f32_e32 v8, v8
	v_exp_f32_e32 v9, v9
	v_exp_f32_e32 v10, v10
	v_pk_mul_f32 v[14:15], v[14:15], v[18:19] op_sel_hi:[1,0]
	v_pk_mul_f32 v[12:13], v[12:13], v[18:19] op_sel_hi:[1,0]
	v_add_f32_e32 v8, 1.0, v8
	v_add_f32_e32 v9, 1.0, v9
	v_add_f32_e32 v10, 1.0, v10
	v_mul_f32_e32 v12, 0xbfb8aa3b, v12
	v_rcp_f32_e32 v19, v8
	v_mul_f32_e32 v8, 0xbfb8aa3b, v13
	v_rcp_f32_e32 v13, v9
	v_mul_f32_e32 v9, 0xbfb8aa3b, v14
	v_rcp_f32_e32 v14, v10
	v_mul_f32_e32 v10, 0xbfb8aa3b, v15
	v_mul_f32_e32 v11, 0xbfb8aa3b, v11
	v_exp_f32_e32 v12, v12
	v_exp_f32_e32 v8, v8
	v_exp_f32_e32 v9, v9
	v_exp_f32_e32 v10, v10
	v_exp_f32_e32 v11, v11
	v_pk_mul_f32 v[2:3], v[2:3], v[18:19] op_sel_hi:[1,0]
	v_pk_mul_f32 v[0:1], v[0:1], v[18:19] op_sel_hi:[1,0]
	v_add_f32_e32 v12, 1.0, v12
	v_add_f32_e32 v8, 1.0, v8
	v_add_f32_e32 v9, 1.0, v9
	v_add_f32_e32 v10, 1.0, v10
	v_add_f32_e32 v11, 1.0, v11
	v_mul_f32_e32 v0, 0xbfb8aa3b, v0
	v_mul_f32_e32 v1, 0xbfb8aa3b, v1
	v_mul_f32_e32 v2, 0xbfb8aa3b, v2
	v_rcp_f32_e32 v12, v12
	v_rcp_f32_e32 v8, v8
	v_rcp_f32_e32 v9, v9
	v_rcp_f32_e32 v10, v10
	v_rcp_f32_e32 v11, v11
	v_exp_f32_e32 v0, v0
	v_exp_f32_e32 v1, v1
	v_exp_f32_e32 v2, v2
	v_cvt_pk_bf16_f32 v8, v12, v8
	v_cvt_pk_bf16_f32 v9, v9, v10
	v_cvt_pk_bf16_f32 v10, v19, v13
	v_cvt_pk_bf16_f32 v11, v14, v11
	v_pk_mul_f32 v[6:7], v[6:7], v[18:19] op_sel_hi:[1,0]
	v_pk_mul_f32 v[4:5], v[4:5], v[18:19] op_sel_hi:[1,0]
	v_add_f32_e32 v0, 1.0, v0
	v_add_f32_e32 v1, 1.0, v1
	v_add_f32_e32 v2, 1.0, v2
	global_store_dwordx4 v[16:17], v[8:11], off
	v_mul_f32_e32 v4, 0xbfb8aa3b, v4
	v_mul_f32_e32 v3, 0xbfb8aa3b, v3
	v_rcp_f32_e32 v8, v0
	v_mul_f32_e32 v0, 0xbfb8aa3b, v5
	v_rcp_f32_e32 v5, v1
	v_mul_f32_e32 v1, 0xbfb8aa3b, v6
	v_rcp_f32_e32 v6, v2
	v_mul_f32_e32 v2, 0xbfb8aa3b, v7
	v_exp_f32_e32 v4, v4
	v_exp_f32_e32 v0, v0
	v_exp_f32_e32 v1, v1
	v_exp_f32_e32 v2, v2
	v_exp_f32_e32 v3, v3
	v_add_f32_e32 v4, 1.0, v4
	v_add_f32_e32 v0, 1.0, v0
	v_add_f32_e32 v1, 1.0, v1
	v_add_f32_e32 v2, 1.0, v2
	v_add_f32_e32 v3, 1.0, v3
	v_rcp_f32_e32 v4, v4
	v_rcp_f32_e32 v0, v0
	v_rcp_f32_e32 v1, v1
	v_rcp_f32_e32 v2, v2
	v_rcp_f32_e32 v3, v3
	v_cvt_pk_bf16_f32 v0, v4, v0
	s_andn2_b64 vcc, exec, s[40:41]
	v_cvt_pk_bf16_f32 v1, v1, v2
	v_cvt_pk_bf16_f32 v2, v8, v5
	v_cvt_pk_bf16_f32 v3, v6, v3
	global_store_dwordx4 v[16:17], v[0:3], off offset:256
	s_cbranch_vccnz .LBB0_182
	s_andn2_b64 vcc, exec, s[4:5]
	s_cbranch_vccnz .LBB0_181
	s_barrier
	s_branch .LBB0_181

; #define PG8_STAGE(bufoff, gbase, voff) do { _Pragma("unroll") for (int _i = 0; _i < 2; ++_i) \
;         __builtin_amdgcn_global_load_lds((const unsigned*)((const char*)(gbase) + (voff)[_i]), (PG8_LAS unsigned*)(lds + (bufoff) + ldsw + _i * 8192), 16, 0, 0); } while (0)
; #define PG8_LDA(dst, b, h) do { _Pragma("unroll") for (int m = 0; m < 4; ++m) _Pragma("unroll") for (int k = 0; k < 2; ++k) dst[m][k] = *(const PG8_LAS bf16x8*)(lds + PG8_SA(b, h) + aoff + m * 2048 + k * 1024); } while (0)
; #define PG8_LDB(dst, b, h) do { _Pragma("unroll") for (int n = 0; n < 2; ++n) _Pragma("unroll") for (int k = 0; k < 2; ++k) dst[n][k] = *(const PG8_LAS bf16x8*)(lds + PG8_SB(b, h) + boff + n * 2048 + k * 1024); } while (0)
; #define PG8_MMA(ai, bj, At, Bt) do { __builtin_amdgcn_s_setprio(1); _Pragma("unroll") for (int m = 0; m < 4; ++m) _Pragma("unroll") for (int n = 0; n < 2; ++n) _Pragma("unroll") for (int k = 0; k < 2; ++k) \
;         acc[ai][bj][m][n] = __builtin_amdgcn_mfma_f32_16x16x32_bf16(Bt[n][k], At[m][k], acc[ai][bj][m][n], 0, 0, 0); __builtin_amdgcn_s_setprio(0); } while (0)
; #define PG8_WAIT_V(n) asm volatile("s_waitcnt vmcnt(" #n ")" ::: "memory")
; #define PG8_WAIT_L(n) asm volatile("s_waitcnt lgkmcnt(" #n ")" ::: "memory")
; #define PG8_BAR __builtin_amdgcn_s_barrier()
; #define PG8_SCHED __builtin_amdgcn_sched_barrier(0)
; template <class Epi, class Sched, bool ALIGN_EPI = false, bool SP2 = false>
; __device__ __forceinline__ void gemm_phase(PG8_LAS unsigned char* lds, const Gemm g, const Sched& S, const Epi& E) {
;     ...
;             PG8_LDB(B0, 0, 0); PG8_LDB(B1, 0, 1); PG8_SCHED; PG8_LDA(At, 0, 0); PG8_STAGE(PG8_SA(1, 1), a1 + hstep, voffA);
;             PG8_WAIT_V(8); PG8_WAIT_L(0); PG8_BAR; PG8_MMA(0, 0, At, B0); PG8_MMA(0, 1, At, B1); PG8_BAR; PG8_SCHED;
;             PG8_LDA(At, 0, 1); PG8_STAGE(PG8_SB(0, 0), b2, voffB); PG8_STAGE(PG8_SB(0, 1), b2 + hstep, voffB); PG8_STAGE(PG8_SA(0, 0), a2, voffA);
;             PG8_WAIT_V(8); PG8_WAIT_L(0); PG8_BAR; PG8_MMA(1, 0, At, B0); PG8_MMA(1, 1, At, B1); PG8_BAR; PG8_SCHED;
.LBB0_288:
	s_add_u32 s6, s4, 0xfffc0080
	s_addc_u32 s7, s5, -1
	s_add_i32 s18, 0, 0x10000
	s_cmp_eq_u32 vcc_lo, 12
	s_cselect_b32 s77, s73, s7
	s_cselect_b32 s76, s72, s6
	s_cselect_b32 s7, s9, s79
	s_cselect_b32 s6, s71, s78
	s_add_i32 vcc_hi, 0, 0x14000
	v_add_u32_e32 v76, s18, v196
	v_add_u32_e32 v100, vcc_hi, v196
	ds_read_b128 v[64:67], v76
	ds_read_b128 v[68:71], v76 offset:1024
	ds_read_b128 v[72:75], v76 offset:2048
	ds_read_b128 v[76:79], v76 offset:3072
	ds_read_b128 v[88:91], v100
	ds_read_b128 v[92:95], v100 offset:1024
	ds_read_b128 v[96:99], v100 offset:2048
	ds_read_b128 v[100:103], v100 offset:3072
	v_lshl_add_u64 v[164:165], s[4:5], 0, v[178:179]
	s_add_i32 m0, s91, 0xc000
	ds_read_b128 v[160:163], v218
	ds_read_b128 v[182:185], v218 offset:1024
	ds_read_b128 v[186:189], v218 offset:2048
	ds_read_b128 v[190:193], v218 offset:3072
	ds_read_b128 v[212:215], v218 offset:4096
	ds_read_b128 v[220:223], v218 offset:5120
	ds_read_b128 v[224:227], v218 offset:6144
	ds_read_b128 v[228:231], v218 offset:7168
	global_load_lds_dwordx4 v[164:165], off
	v_lshl_add_u64 v[164:165], s[4:5], 0, v[180:181]
	s_add_i32 m0, s91, 0xe000
	s_nop 0
	global_load_lds_dwordx4 v[164:165], off
	s_waitcnt vmcnt(8)
	s_waitcnt lgkmcnt(0)
	s_barrier
	s_setprio 1
	s_waitcnt lgkmcnt(0)
	v_mfma_f32_16x16x32_bf16 v[156:159], v[64:67], v[160:163], v[156:159]
	v_mfma_f32_16x16x32_bf16 v[152:155], v[72:75], v[160:163], v[152:155]
	v_mfma_f32_16x16x32_bf16 v[140:143], v[64:67], v[186:189], v[140:143]
	v_mfma_f32_16x16x32_bf16 v[136:139], v[72:75], v[186:189], v[136:139]
	v_mfma_f32_16x16x32_bf16 v[124:127], v[64:67], v[212:215], v[124:127]
	v_mfma_f32_16x16x32_bf16 v[120:123], v[72:75], v[212:215], v[120:123]
	v_mfma_f32_16x16x32_bf16 v[108:111], v[64:67], v[224:227], v[108:111]
	v_mfma_f32_16x16x32_bf16 v[104:107], v[72:75], v[224:227], v[104:107]
	v_mfma_f32_16x16x32_bf16 v[156:159], v[68:71], v[182:185], v[156:159]
	v_mfma_f32_16x16x32_bf16 v[152:155], v[76:79], v[182:185], v[152:155]
	v_mfma_f32_16x16x32_bf16 v[140:143], v[68:71], v[190:193], v[140:143]
	v_mfma_f32_16x16x32_bf16 v[136:139], v[76:79], v[190:193], v[136:139]
	v_mfma_f32_16x16x32_bf16 v[124:127], v[68:71], v[220:223], v[124:127]
	v_mfma_f32_16x16x32_bf16 v[120:123], v[76:79], v[220:223], v[120:123]
	v_mfma_f32_16x16x32_bf16 v[108:111], v[68:71], v[228:231], v[108:111]
	v_mfma_f32_16x16x32_bf16 v[104:107], v[76:79], v[228:231], v[104:107]
	s_setprio 0
	s_setprio 1
	v_mfma_f32_16x16x32_bf16 v[148:151], v[88:91], v[160:163], v[148:151]
	v_mfma_f32_16x16x32_bf16 v[144:147], v[96:99], v[160:163], v[144:147]
	v_mfma_f32_16x16x32_bf16 v[132:135], v[88:91], v[186:189], v[132:135]
	v_mfma_f32_16x16x32_bf16 v[128:131], v[96:99], v[186:189], v[128:131]
	v_mfma_f32_16x16x32_bf16 v[116:119], v[88:91], v[212:215], v[116:119]
	v_mfma_f32_16x16x32_bf16 v[112:115], v[96:99], v[212:215], v[112:115]
	v_mfma_f32_16x16x32_bf16 v[84:87], v[88:91], v[224:227], v[84:87]
	v_mfma_f32_16x16x32_bf16 v[80:83], v[96:99], v[224:227], v[80:83]
	v_mfma_f32_16x16x32_bf16 v[148:151], v[92:95], v[182:185], v[148:151]
	v_mfma_f32_16x16x32_bf16 v[144:147], v[100:103], v[182:185], v[144:147]
	v_mfma_f32_16x16x32_bf16 v[132:135], v[92:95], v[190:193], v[132:135]
	v_mfma_f32_16x16x32_bf16 v[128:131], v[100:103], v[190:193], v[128:131]
	v_mfma_f32_16x16x32_bf16 v[116:119], v[92:95], v[220:223], v[116:119]
	v_mfma_f32_16x16x32_bf16 v[112:115], v[100:103], v[220:223], v[112:115]
	v_mfma_f32_16x16x32_bf16 v[84:87], v[92:95], v[228:231], v[84:87]
	v_mfma_f32_16x16x32_bf16 v[80:83], v[100:103], v[228:231], v[80:83]
	s_setprio 0
	s_barrier
	s_add_i32 s18, s18, s85
	v_lshl_add_u64 v[164:165], s[6:7], 0, v[208:209]
	s_mov_b32 m0, s18
	ds_read_b128 v[160:163], v218 offset:16384
	ds_read_b128 v[182:185], v218 offset:17408
	ds_read_b128 v[186:189], v218 offset:18432
	ds_read_b128 v[190:193], v218 offset:19456
	ds_read_b128 v[212:215], v218 offset:20480
	ds_read_b128 v[220:223], v218 offset:21504
	ds_read_b128 v[224:227], v218 offset:22528
	ds_read_b128 v[228:231], v218 offset:23552
	global_load_lds_dwordx4 v[164:165], off
	s_add_i32 m0, s18, 0x2000
	s_add_u32 s18, s6, 0x40000
	v_lshl_add_u64 v[194:195], s[6:7], 0, v[170:171]
	s_addc_u32 s19, s7, 0
	s_add_i32 vcc_hi, vcc_hi, s85
	global_load_lds_dwordx4 v[194:195], off
	v_lshl_add_u64 v[232:233], s[18:19], 0, v[208:209]
	s_mov_b32 m0, vcc_hi
	v_lshl_add_u64 v[234:235], s[76:77], 0, v[168:169]
	global_load_lds_dwordx4 v[232:233], off
	v_lshl_add_u64 v[232:233], s[18:19], 0, v[170:171]
	s_add_i32 m0, vcc_hi, 0x2000
	s_nop 0
	global_load_lds_dwordx4 v[232:233], off
	v_lshl_add_u64 v[232:233], s[76:77], 0, v[166:167]
	s_mov_b32 m0, s91
	s_nop 0
	global_load_lds_dwordx4 v[232:233], off
	s_mov_b32 m0, s92
	s_nop 0
	global_load_lds_dwordx4 v[234:235], off
	s_waitcnt vmcnt(8)
	s_waitcnt lgkmcnt(0)
	s_barrier
; #define PG8_STAGE(bufoff, gbase, voff) do { _Pragma("unroll") for (int _i = 0; _i < 2; ++_i) \
;         __builtin_amdgcn_global_load_lds((const unsigned*)((const char*)(gbase) + (voff)[_i]), (PG8_LAS unsigned*)(lds + (bufoff) + ldsw + _i * 8192), 16, 0, 0); } while (0)
; #define PG8_LDA(dst, b, h) do { _Pragma("unroll") for (int m = 0; m < 4; ++m) _Pragma("unroll") for (int k = 0; k < 2; ++k) dst[m][k] = *(const PG8_LAS bf16x8*)(lds + PG8_SA(b, h) + aoff + m * 2048 + k * 1024); } while (0)
; #define PG8_LDB(dst, b, h) do { _Pragma("unroll") for (int n = 0; n < 2; ++n) _Pragma("unroll") for (int k = 0; k < 2; ++k) dst[n][k] = *(const PG8_LAS bf16x8*)(lds + PG8_SB(b, h) + boff + n * 2048 + k * 1024); } while (0)
; #define PG8_MMA(ai, bj, At, Bt) do { __builtin_amdgcn_s_setprio(1); _Pragma("unroll") for (int m = 0; m < 4; ++m) _Pragma("unroll") for (int n = 0; n < 2; ++n) _Pragma("unroll") for (int k = 0; k < 2; ++k) \
;         acc[ai][bj][m][n] = __builtin_amdgcn_mfma_f32_16x16x32_bf16(Bt[n][k], At[m][k], acc[ai][bj][m][n], 0, 0, 0); __builtin_amdgcn_s_setprio(0); } while (0)
; #define PG8_WAIT_V(n) asm volatile("s_waitcnt vmcnt(" #n ")" ::: "memory")
; #define PG8_WAIT_L(n) asm volatile("s_waitcnt lgkmcnt(" #n ")" ::: "memory")
; #define PG8_BAR __builtin_amdgcn_s_barrier()
; #define PG8_SCHED __builtin_amdgcn_sched_barrier(0)
; template <class Epi, class Sched, bool ALIGN_EPI = false, bool SP2 = false>
; __device__ __forceinline__ void gemm_phase(PG8_LAS unsigned char* lds, const Gemm g, const Sched& S, const Epi& E) {
;     ...
;             PG8_WAIT_V(8); PG8_WAIT_L(0); PG8_BAR; PG8_MMA(1, 0, At, B0); PG8_MMA(1, 1, At, B1); PG8_BAR; PG8_SCHED;
;             PG8_LDB(B0, 1, 0); PG8_LDB(B1, 1, 1); PG8_SCHED; PG8_LDA(At, 1, 0); PG8_STAGE(PG8_SA(0, 1), a2 + hstep, voffA);
;             PG8_WAIT_V(8); PG8_WAIT_L(0); PG8_BAR; PG8_MMA(0, 0, At, B0); PG8_MMA(0, 1, At, B1); PG8_BAR; PG8_SCHED;
	s_setprio 1
	s_waitcnt lgkmcnt(0)
	v_mfma_f32_16x16x32_bf16 v[60:63], v[64:67], v[160:163], v[60:63]
	v_mfma_f32_16x16x32_bf16 v[56:59], v[72:75], v[160:163], v[56:59]
	v_mfma_f32_16x16x32_bf16 v[44:47], v[64:67], v[186:189], v[44:47]
	v_mfma_f32_16x16x32_bf16 v[40:43], v[72:75], v[186:189], v[40:43]
	v_mfma_f32_16x16x32_bf16 v[28:31], v[64:67], v[212:215], v[28:31]
	v_mfma_f32_16x16x32_bf16 v[24:27], v[72:75], v[212:215], v[24:27]
	v_mfma_f32_16x16x32_bf16 v[12:15], v[64:67], v[224:227], v[12:15]
	v_mfma_f32_16x16x32_bf16 v[8:11], v[72:75], v[224:227], v[8:11]
	v_mfma_f32_16x16x32_bf16 v[60:63], v[68:71], v[182:185], v[60:63]
	v_mfma_f32_16x16x32_bf16 v[56:59], v[76:79], v[182:185], v[56:59]
	v_mfma_f32_16x16x32_bf16 v[44:47], v[68:71], v[190:193], v[44:47]
	v_mfma_f32_16x16x32_bf16 v[40:43], v[76:79], v[190:193], v[40:43]
	v_mfma_f32_16x16x32_bf16 v[28:31], v[68:71], v[220:223], v[28:31]
	v_mfma_f32_16x16x32_bf16 v[24:27], v[76:79], v[220:223], v[24:27]
	v_mfma_f32_16x16x32_bf16 v[12:15], v[68:71], v[228:231], v[12:15]
	v_mfma_f32_16x16x32_bf16 v[8:11], v[76:79], v[228:231], v[8:11]
	s_setprio 0
	s_setprio 1
	v_mfma_f32_16x16x32_bf16 v[52:55], v[88:91], v[160:163], v[52:55]
	v_mfma_f32_16x16x32_bf16 v[48:51], v[96:99], v[160:163], v[48:51]
	v_mfma_f32_16x16x32_bf16 v[36:39], v[88:91], v[186:189], v[36:39]
	v_mfma_f32_16x16x32_bf16 v[32:35], v[96:99], v[186:189], v[32:35]
	v_mfma_f32_16x16x32_bf16 v[20:23], v[88:91], v[212:215], v[20:23]
	v_mfma_f32_16x16x32_bf16 v[16:19], v[96:99], v[212:215], v[16:19]
	v_mfma_f32_16x16x32_bf16 v[4:7], v[88:91], v[224:227], v[4:7]
	v_mfma_f32_16x16x32_bf16 v[0:3], v[96:99], v[224:227], v[0:3]
	v_mfma_f32_16x16x32_bf16 v[52:55], v[92:95], v[182:185], v[52:55]
	v_mfma_f32_16x16x32_bf16 v[48:51], v[100:103], v[182:185], v[48:51]
	v_mfma_f32_16x16x32_bf16 v[36:39], v[92:95], v[190:193], v[36:39]
	v_mfma_f32_16x16x32_bf16 v[32:35], v[100:103], v[190:193], v[32:35]
	v_mfma_f32_16x16x32_bf16 v[20:23], v[92:95], v[220:223], v[20:23]
	v_mfma_f32_16x16x32_bf16 v[16:19], v[100:103], v[220:223], v[16:19]
	v_mfma_f32_16x16x32_bf16 v[4:7], v[92:95], v[228:231], v[4:7]
	v_mfma_f32_16x16x32_bf16 v[0:3], v[100:103], v[228:231], v[0:3]
	s_setprio 0
	s_barrier
	s_add_i32 vcc_hi, 0, 0x18000
	s_add_i32 s34, 0, 0x1c000
	v_add_u32_e32 v76, vcc_hi, v196
	v_add_u32_e32 v100, s34, v196
	ds_read_b128 v[64:67], v76
	ds_read_b128 v[68:71], v76 offset:1024
	ds_read_b128 v[72:75], v76 offset:2048
	ds_read_b128 v[76:79], v76 offset:3072
	ds_read_b128 v[88:91], v100
	ds_read_b128 v[92:95], v100 offset:1024
	ds_read_b128 v[96:99], v100 offset:2048
	ds_read_b128 v[100:103], v100 offset:3072
	s_add_u32 s18, s76, 0x40000
	s_addc_u32 s19, s77, 0
	s_mov_b32 m0, s93
	v_lshl_add_u64 v[236:237], s[18:19], 0, v[166:167]
	ds_read_b128 v[160:163], v218 offset:32768
	ds_read_b128 v[182:185], v218 offset:33792
	ds_read_b128 v[186:189], v218 offset:34816
	ds_read_b128 v[190:193], v218 offset:35840
	ds_read_b128 v[212:215], v218 offset:36864
	ds_read_b128 v[220:223], v218 offset:37888
	ds_read_b128 v[224:227], v218 offset:38912
	ds_read_b128 v[228:231], v218 offset:39936
	global_load_lds_dwordx4 v[236:237], off
	v_lshl_add_u64 v[236:237], s[18:19], 0, v[168:169]
	s_mov_b32 m0, s94
	s_nop 0
	global_load_lds_dwordx4 v[236:237], off
	s_waitcnt vmcnt(8)
	s_waitcnt lgkmcnt(0)
	s_barrier
	s_setprio 1
	s_waitcnt lgkmcnt(0)
	v_mfma_f32_16x16x32_bf16 v[156:159], v[64:67], v[160:163], v[156:159]
	v_mfma_f32_16x16x32_bf16 v[152:155], v[72:75], v[160:163], v[152:155]
	v_mfma_f32_16x16x32_bf16 v[140:143], v[64:67], v[186:189], v[140:143]
	v_mfma_f32_16x16x32_bf16 v[136:139], v[72:75], v[186:189], v[136:139]
	v_mfma_f32_16x16x32_bf16 v[124:127], v[64:67], v[212:215], v[124:127]
	v_mfma_f32_16x16x32_bf16 v[120:123], v[72:75], v[212:215], v[120:123]
	v_mfma_f32_16x16x32_bf16 v[108:111], v[64:67], v[224:227], v[108:111]
	v_mfma_f32_16x16x32_bf16 v[104:107], v[72:75], v[224:227], v[104:107]
	v_mfma_f32_16x16x32_bf16 v[156:159], v[68:71], v[182:185], v[156:159]
	v_mfma_f32_16x16x32_bf16 v[152:155], v[76:79], v[182:185], v[152:155]
	v_mfma_f32_16x16x32_bf16 v[140:143], v[68:71], v[190:193], v[140:143]
	v_mfma_f32_16x16x32_bf16 v[136:139], v[76:79], v[190:193], v[136:139]
	v_mfma_f32_16x16x32_bf16 v[124:127], v[68:71], v[220:223], v[124:127]
	v_mfma_f32_16x16x32_bf16 v[120:123], v[76:79], v[220:223], v[120:123]
	v_mfma_f32_16x16x32_bf16 v[108:111], v[68:71], v[228:231], v[108:111]
	v_mfma_f32_16x16x32_bf16 v[104:107], v[76:79], v[228:231], v[104:107]
	s_setprio 0
	s_setprio 1
	v_mfma_f32_16x16x32_bf16 v[148:151], v[88:91], v[160:163], v[148:151]
	v_mfma_f32_16x16x32_bf16 v[144:147], v[96:99], v[160:163], v[144:147]
	v_mfma_f32_16x16x32_bf16 v[132:135], v[88:91], v[186:189], v[132:135]
	v_mfma_f32_16x16x32_bf16 v[128:131], v[96:99], v[186:189], v[128:131]
	v_mfma_f32_16x16x32_bf16 v[116:119], v[88:91], v[212:215], v[116:119]
	v_mfma_f32_16x16x32_bf16 v[112:115], v[96:99], v[212:215], v[112:115]
	v_mfma_f32_16x16x32_bf16 v[84:87], v[88:91], v[224:227], v[84:87]
	v_mfma_f32_16x16x32_bf16 v[80:83], v[96:99], v[224:227], v[80:83]
	v_mfma_f32_16x16x32_bf16 v[148:151], v[92:95], v[182:185], v[148:151]
	v_mfma_f32_16x16x32_bf16 v[144:147], v[100:103], v[182:185], v[144:147]
	v_mfma_f32_16x16x32_bf16 v[132:135], v[92:95], v[190:193], v[132:135]
	v_mfma_f32_16x16x32_bf16 v[128:131], v[100:103], v[190:193], v[128:131]
	v_mfma_f32_16x16x32_bf16 v[116:119], v[92:95], v[220:223], v[116:119]
	v_mfma_f32_16x16x32_bf16 v[112:115], v[100:103], v[220:223], v[112:115]
	v_mfma_f32_16x16x32_bf16 v[84:87], v[92:95], v[228:231], v[84:87]
	v_mfma_f32_16x16x32_bf16 v[80:83], v[100:103], v[228:231], v[80:83]
	s_setprio 0
	s_barrier
;     __device__ __forceinline__ void operator()(const f32x4 (&acc)[2][2][4][2], const Unit& u, int wr, int wc, int fr, int fq) const {
;         const int b = u.pm / 17, i = u.pm - b * 17, fl = wc * 32 + 8 * fq, f0 = u.pn * 128 + fl;
;         float rn[2][4];
; #pragma unroll
;         for (int ai = 0; ai < 2; ++ai)
; #pragma unroll
;             for (int m = 0; m < 4; ++m) rn[ai][m] = row_rstd(rss, (long)b * 4096 + 254 * i - 2 + ai * HALF + wr * 64 + m * 16 + fr, fq);
; template <class Epi, class Sched, bool ALIGN_EPI = false, bool SP2 = false>
; __device__ __forceinline__ void gemm_phase(PG8_LAS unsigned char* lds, const Gemm g, const Sched& S, const Epi& E) {
;     ...
;             PG8_LDA(At, 1, 1); PG8_STAGE(PG8_SB(1, 0), b3, voffB); PG8_STAGE(PG8_SB(1, 1), b3 + hstep, voffB); PG8_STAGE(PG8_SA(1, 0), a3, voffA);
;             PG8_WAIT_V(8); PG8_WAIT_L(0); PG8_BAR; PG8_MMA(1, 0, At, B0); PG8_MMA(1, 1, At, B1); PG8_BAR; PG8_SCHED;
;             } else {
;             PG8_LDB(B0, 0, 0); PG8_SCHED; PG8_LDA(At, 0, 0); PG8_STAGE(PG8_SA(1, 1), a1 + hstep, voffA);
;             PG8_WAIT_L(8); PG8_BAR; PG8_WAIT_L(0); PG8_MMA(0, 0, At, B0); PG8_BAR; PG8_SCHED;
;             PG8_LDB(B1, 0, 1); PG8_STAGE(PG8_SB(0, 0), b2, voffB);
;             PG8_BAR; PG8_WAIT_L(0); PG8_MMA(0, 1, At, B1); PG8_BAR;
;             PG8_LDA(At, 0, 1); PG8_STAGE(PG8_SA(0, 0), a2, voffA);
;             PG8_BAR; PG8_WAIT_L(0); PG8_MMA(1, 0, At, B0); PG8_BAR; PG8_SCHED;
;             PG8_STAGE(PG8_SB(0, 1), b2 + hstep, voffB);
;             PG8_WAIT_V(6); PG8_BAR; PG8_MMA(1, 1, At, B1); PG8_BAR;
;             PG8_LDB(B0, 1, 0); PG8_SCHED; PG8_LDA(At, 1, 0); PG8_STAGE(PG8_SA(0, 1), a2 + hstep, voffA);
;             PG8_WAIT_L(8); PG8_BAR; PG8_WAIT_L(0); PG8_MMA(0, 0, At, B0); PG8_BAR; PG8_SCHED;
;             PG8_LDB(B1, 1, 1); PG8_STAGE(PG8_SB(1, 0), b3, voffB);
;             PG8_BAR; PG8_WAIT_L(0); PG8_MMA(0, 1, At, B1); PG8_BAR;
;             PG8_LDA(At, 1, 1); PG8_STAGE(PG8_SA(1, 0), a3, voffA);
;             PG8_BAR; PG8_WAIT_L(0); PG8_MMA(1, 0, At, B0); PG8_BAR; PG8_SCHED;
;             PG8_STAGE(PG8_SB(1, 1), b3 + hstep, voffB);
;             PG8_WAIT_V(6); PG8_BAR; PG8_MMA(1, 1, At, B1); PG8_BAR;
;             }
;         }
;         if constexpr (ALIGN_EPI) { if (wr == 0) PG8_BAR; }
;         if constexpr (!Epi::AFTER_DRAIN) { E(acc, cur, wr, wc, fr, fq); S.done(cur); }
	s_add_i32 s18, vcc_hi, s85
	v_lshl_add_u64 v[164:165], v[164:165], 0, s[24:25]
	s_mov_b32 m0, s18
	ds_read_b128 v[160:163], v218 offset:49152
	ds_read_b128 v[182:185], v218 offset:50176
	ds_read_b128 v[186:189], v218 offset:51200
	ds_read_b128 v[190:193], v218 offset:52224
	ds_read_b128 v[212:215], v218 offset:53248
	ds_read_b128 v[220:223], v218 offset:54272
	ds_read_b128 v[224:227], v218 offset:55296
	ds_read_b128 v[228:231], v218 offset:56320
	global_load_lds_dwordx4 v[164:165], off
	s_add_i32 m0, s18, 0x2000
	s_add_u32 s6, s6, 0x40080
	v_lshl_add_u64 v[164:165], v[194:195], 0, s[24:25]
	s_addc_u32 s7, s7, 0
	s_add_i32 s18, s34, s85
	global_load_lds_dwordx4 v[164:165], off
	v_lshl_add_u64 v[164:165], s[6:7], 0, v[208:209]
	s_mov_b32 m0, s18
	s_nop 0
	global_load_lds_dwordx4 v[164:165], off
	v_lshl_add_u64 v[164:165], s[6:7], 0, v[170:171]
	s_add_i32 m0, s18, 0x2000
	s_nop 0
	global_load_lds_dwordx4 v[164:165], off
	v_lshl_add_u64 v[164:165], v[232:233], 0, s[24:25]
	s_mov_b32 m0, s95
	s_nop 0
	global_load_lds_dwordx4 v[164:165], off
	v_lshl_add_u64 v[164:165], v[234:235], 0, s[24:25]
	s_mov_b32 m0, s96
	s_nop 0
	global_load_lds_dwordx4 v[164:165], off
	s_waitcnt vmcnt(8)
	s_waitcnt lgkmcnt(0)
	s_barrier
	s_setprio 1
	s_waitcnt lgkmcnt(0)
	v_mfma_f32_16x16x32_bf16 v[60:63], v[64:67], v[160:163], v[60:63]
	v_mfma_f32_16x16x32_bf16 v[56:59], v[72:75], v[160:163], v[56:59]
	v_mfma_f32_16x16x32_bf16 v[44:47], v[64:67], v[186:189], v[44:47]
	v_mfma_f32_16x16x32_bf16 v[40:43], v[72:75], v[186:189], v[40:43]
	v_mfma_f32_16x16x32_bf16 v[28:31], v[64:67], v[212:215], v[28:31]
	v_mfma_f32_16x16x32_bf16 v[24:27], v[72:75], v[212:215], v[24:27]
	v_mfma_f32_16x16x32_bf16 v[12:15], v[64:67], v[224:227], v[12:15]
	v_mfma_f32_16x16x32_bf16 v[8:11], v[72:75], v[224:227], v[8:11]
	v_mfma_f32_16x16x32_bf16 v[60:63], v[68:71], v[182:185], v[60:63]
	v_mfma_f32_16x16x32_bf16 v[56:59], v[76:79], v[182:185], v[56:59]
	v_mfma_f32_16x16x32_bf16 v[44:47], v[68:71], v[190:193], v[44:47]
	v_mfma_f32_16x16x32_bf16 v[40:43], v[76:79], v[190:193], v[40:43]
	v_mfma_f32_16x16x32_bf16 v[28:31], v[68:71], v[220:223], v[28:31]
	v_mfma_f32_16x16x32_bf16 v[24:27], v[76:79], v[220:223], v[24:27]
	v_mfma_f32_16x16x32_bf16 v[12:15], v[68:71], v[228:231], v[12:15]
	v_mfma_f32_16x16x32_bf16 v[8:11], v[76:79], v[228:231], v[8:11]
	s_setprio 0
	s_setprio 1
	v_mfma_f32_16x16x32_bf16 v[52:55], v[88:91], v[160:163], v[52:55]
	v_mfma_f32_16x16x32_bf16 v[48:51], v[96:99], v[160:163], v[48:51]
	v_mfma_f32_16x16x32_bf16 v[36:39], v[88:91], v[186:189], v[36:39]
	v_mfma_f32_16x16x32_bf16 v[32:35], v[96:99], v[186:189], v[32:35]
	v_mfma_f32_16x16x32_bf16 v[20:23], v[88:91], v[212:215], v[20:23]
	v_mfma_f32_16x16x32_bf16 v[16:19], v[96:99], v[212:215], v[16:19]
	v_mfma_f32_16x16x32_bf16 v[4:7], v[88:91], v[224:227], v[4:7]
	v_mfma_f32_16x16x32_bf16 v[0:3], v[96:99], v[224:227], v[0:3]
	v_mfma_f32_16x16x32_bf16 v[52:55], v[92:95], v[182:185], v[52:55]
	v_mfma_f32_16x16x32_bf16 v[48:51], v[100:103], v[182:185], v[48:51]
	v_mfma_f32_16x16x32_bf16 v[36:39], v[92:95], v[190:193], v[36:39]
	v_mfma_f32_16x16x32_bf16 v[32:35], v[100:103], v[190:193], v[32:35]
	v_mfma_f32_16x16x32_bf16 v[20:23], v[92:95], v[220:223], v[20:23]
	v_mfma_f32_16x16x32_bf16 v[16:19], v[100:103], v[220:223], v[16:19]
	v_mfma_f32_16x16x32_bf16 v[4:7], v[92:95], v[228:231], v[4:7]
	v_mfma_f32_16x16x32_bf16 v[0:3], v[100:103], v[228:231], v[0:3]
	s_setprio 0
	s_barrier
	s_add_i32 vcc_lo, vcc_lo, 2
	s_add_u32 s4, s4, 0x100
	s_addc_u32 s5, s5, 0
	s_add_u32 s78, s78, 0x100
	s_addc_u32 s79, s79, 0
	s_cmp_gt_u32 vcc_lo, 13
	s_cbranch_scc0 .LBB0_288
	s_and_b64 vcc, exec, s[58:59]
	s_cbranch_vccz .LBB0_291
	s_barrier
.LBB0_291:
	s_mul_hi_i32 s4, s86, 0x78787879
	s_lshr_b32 s5, s4, 31
	s_ashr_i32 s4, s4, 3
	s_add_i32 s76, s4, s5
	s_mul_i32 s4, s76, 0xffffffef
	s_add_i32 s6, s4, s86
	s_ashr_i32 s77, s76, 31
	s_lshl_b64 s[4:5], s[76:77], 12
	s_mul_i32 s77, s6, 0xfe
	s_ashr_i32 s6, s77, 31
	s_add_u32 s4, s77, s4
	s_addc_u32 s5, s6, s5
	v_cmp_lt_i32_e32 vcc, v251, v246
	v_lshl_add_u64 v[64:65], s[4:5], 0, v[174:175]
	v_lshlrev_b64 v[64:65], 6, v[64:65]
	v_cndmask_b32_e32 v66, v245, v251, vcc
	v_cmp_lt_i32_e32 vcc, v252, v246
	v_lshlrev_b32_e32 v69, 2, v66
	s_mov_b32 s78, 0x3a800000
	v_cndmask_b32_e32 v66, v245, v252, vcc
	v_lshlrev_b32_e32 v68, 2, v66
	v_lshl_add_u64 v[66:67], v[176:177], 0, v[64:65]
	v_add_co_u32_e32 v96, vcc, 0x2000, v66
	s_nop 1
	v_addc_co_u32_e32 v97, vcc, 0, v67, vcc
	global_load_dwordx4 v[220:223], v[66:67], off
	global_load_dwordx4 v[224:227], v[66:67], off offset:1024
	global_load_dwordx4 v[228:231], v[66:67], off offset:2048
	global_load_dwordx4 v[232:235], v[66:67], off offset:3072
	global_load_dwordx4 v[236:239], v[96:97], off
	global_load_dwordx4 v[240:243], v[96:97], off offset:1024
	global_load_dwordx4 v[88:91], v[96:97], off offset:2048
	global_load_dwordx4 v[92:95], v[96:97], off offset:3072
	s_movk_i32 s6, 0x2000
	s_waitcnt vmcnt(7)
	v_mov_b32_e32 v70, v220
	v_mov_b32_e32 v71, v221
	v_mov_b32_e32 v72, v222
	v_mov_b32_e32 v73, v223
	v_mov_b32_e32 v64, v71
	v_mov_b32_e32 v65, v72
	v_mov_b32_e32 v71, v73
	v_pk_add_f32 v[64:65], v[64:65], v[70:71]
	s_waitcnt vmcnt(6)
	v_mov_b32_e32 v70, v224
	v_mov_b32_e32 v71, v225
	v_mov_b32_e32 v72, v226
	v_mov_b32_e32 v73, v227
	v_mov_b32_e32 v74, v71
	v_mov_b32_e32 v75, v72
	v_mov_b32_e32 v71, v73
	v_pk_add_f32 v[70:71], v[74:75], v[70:71]
	v_mov_b32_e32 v73, v64
	v_mov_b32_e32 v72, v70
	v_mov_b32_e32 v64, v71
	v_pk_add_f32 v[64:65], v[72:73], v[64:65]
	ds_bpermute_b32 v71, v69, v65
	ds_bpermute_b32 v70, v69, v64
	s_waitcnt lgkmcnt(0)
; #define PG8_LAS __attribute__((address_space(3)))
;     __device__ __forceinline__ void operator()(const f32x4 (&acc)[2][2][4][2], const Unit& u, int wr, int wc, int fr, int fq) const {
;     ...
;             for (int m = 0; m < 4; ++m) rn[ai][m] = row_rstd(rss, (long)b * 4096 + 254 * i - 2 + ai * HALF + wr * 64 + m * 16 + fr, fq);
;         if (fr >= 14) {
; #pragma unroll
;             for (int ai = 0; ai < 2; ++ai)
; #pragma unroll
;                 for (int n = 0; n < 2; ++n) *(PG8_LAS f32x4*)(halo + ((ai * 2 + wr) * 2 + (fr - 14)) * 128 + fl + 4 * n) = acc[ai][0][3][n] * rn[ai][3];
;         }
;         asm volatile("s_waitcnt lgkmcnt(0)" ::: "memory"); __builtin_amdgcn_s_barrier(); asm volatile("" ::: "memory");
	v_pk_add_f32 v[192:193], v[64:65], v[70:71]
	ds_bpermute_b32 v195, v68, v193
	ds_bpermute_b32 v194, v68, v192
	s_waitcnt vmcnt(5)
	v_mov_b32_e32 v70, v228
	v_mov_b32_e32 v71, v229
	v_mov_b32_e32 v72, v230
	v_mov_b32_e32 v73, v231
	v_mov_b32_e32 v64, v71
	v_mov_b32_e32 v65, v72
	v_mov_b32_e32 v71, v73
	v_pk_add_f32 v[64:65], v[64:65], v[70:71]
	s_waitcnt vmcnt(4)
	v_mov_b32_e32 v70, v232
	v_mov_b32_e32 v71, v233
	v_mov_b32_e32 v72, v234
	v_mov_b32_e32 v73, v235
	v_mov_b32_e32 v74, v71
	v_mov_b32_e32 v75, v72
	v_mov_b32_e32 v71, v73
	v_pk_add_f32 v[70:71], v[74:75], v[70:71]
	v_mov_b32_e32 v73, v64
	v_mov_b32_e32 v72, v70
	v_mov_b32_e32 v64, v71
	v_pk_add_f32 v[64:65], v[72:73], v[64:65]
	ds_bpermute_b32 v71, v69, v65
	ds_bpermute_b32 v70, v69, v64
	s_waitcnt lgkmcnt(0)
	v_pk_add_f32 v[64:65], v[64:65], v[70:71]
	ds_bpermute_b32 v71, v68, v65
	ds_bpermute_b32 v70, v68, v64
	s_waitcnt lgkmcnt(0)
	v_pk_add_f32 v[70:71], v[64:65], v[70:71]
	v_mov_b64_e32 v[64:65], s[0:1]
	v_pk_fma_f32 v[186:187], v[70:71], s[78:79], v[64:65] op_sel_hi:[1,0,0]
	s_nop 0
	v_cmp_gt_f32_e32 vcc, s39, v186
	v_mul_f32_e32 v70, 0x4b800000, v186
	v_cmp_gt_f32_e64 s[4:5], s39, v187
	v_cndmask_b32_e32 v70, v186, v70, vcc
	v_rsq_f32_e32 v70, v70
	s_nop 0
	v_mul_f32_e32 v71, 0x45800000, v70
	v_cndmask_b32_e32 v186, v70, v71, vcc
	v_add_co_u32_e32 v66, vcc, s6, v66
	s_nop 1
	v_addc_co_u32_e32 v67, vcc, 0, v67, vcc
	s_waitcnt vmcnt(3)
	v_mov_b32_e32 v70, v236
	v_mov_b32_e32 v71, v237
	v_mov_b32_e32 v72, v238
	v_mov_b32_e32 v73, v239
	v_mov_b32_e32 v74, v71
	v_mov_b32_e32 v75, v72
	v_mov_b32_e32 v71, v73
	v_pk_add_f32 v[74:75], v[74:75], v[70:71]
	s_waitcnt vmcnt(2)
	v_mov_b32_e32 v70, v240
	v_mov_b32_e32 v71, v241
	v_mov_b32_e32 v72, v242
	v_mov_b32_e32 v73, v243
	v_mov_b32_e32 v76, v71
	v_mov_b32_e32 v77, v72
	v_mov_b32_e32 v71, v73
	v_pk_add_f32 v[70:71], v[76:77], v[70:71]
	v_mov_b32_e32 v73, v74
	v_mov_b32_e32 v72, v70
	v_mov_b32_e32 v74, v71
	v_pk_add_f32 v[70:71], v[72:73], v[74:75]
	ds_bpermute_b32 v73, v69, v71
	ds_bpermute_b32 v72, v69, v70
	s_waitcnt lgkmcnt(0)
	v_pk_add_f32 v[188:189], v[70:71], v[72:73]
	ds_bpermute_b32 v191, v68, v189
	ds_bpermute_b32 v190, v68, v188
	s_waitcnt vmcnt(1)
	v_mov_b32_e32 v70, v88
	v_mov_b32_e32 v71, v89
	v_mov_b32_e32 v72, v90
	v_mov_b32_e32 v73, v91
	v_mov_b32_e32 v74, v71
	v_mov_b32_e32 v75, v72
	v_mov_b32_e32 v71, v73
	v_pk_add_f32 v[74:75], v[74:75], v[70:71]
	s_waitcnt vmcnt(0)
	v_mov_b32_e32 v70, v92
	v_mov_b32_e32 v71, v93
	v_mov_b32_e32 v72, v94
	v_mov_b32_e32 v73, v95
	v_mov_b32_e32 v66, v71
	v_mov_b32_e32 v67, v72
	v_mov_b32_e32 v71, v73
	v_pk_add_f32 v[66:67], v[66:67], v[70:71]
	v_mov_b32_e32 v71, v74
	v_mov_b32_e32 v70, v66
	v_mov_b32_e32 v74, v67
	v_pk_add_f32 v[66:67], v[70:71], v[74:75]
	ds_bpermute_b32 v71, v69, v67
	ds_bpermute_b32 v70, v69, v66
	s_waitcnt lgkmcnt(0)
	v_pk_add_f32 v[66:67], v[66:67], v[70:71]
	ds_bpermute_b32 v69, v68, v67
	ds_bpermute_b32 v68, v68, v66
	s_waitcnt lgkmcnt(0)
	v_pk_add_f32 v[66:67], v[66:67], v[68:69]
	s_nop 0
	v_pk_fma_f32 v[184:185], v[66:67], s[78:79], v[64:65] op_sel_hi:[1,0,0]
	s_nop 0
	v_cmp_gt_f32_e64 s[6:7], s39, v184
	v_mul_f32_e32 v64, 0x4b800000, v184
	v_cmp_gt_f32_e32 vcc, s39, v185
	v_cndmask_b32_e64 v64, v184, v64, s[6:7]
	v_rsq_f32_e32 v64, v64
	s_nop 0
	v_mul_f32_e32 v65, 0x45800000, v64
	v_cndmask_b32_e64 v184, v64, v65, s[6:7]
	s_and_saveexec_b64 s[6:7], s[40:41]
	s_movk_i32 s34, 0x1600
	s_cbranch_execz .LBB0_293
	v_pk_mul_f32 v[66:67], v[110:111], v[186:187] op_sel_hi:[1,0]
	v_pk_mul_f32 v[64:65], v[108:109], v[186:187] op_sel_hi:[1,0]
	ds_write_b128 v204, v[64:67]
	v_pk_mul_f32 v[66:67], v[106:107], v[186:187] op_sel_hi:[1,0]
	v_pk_mul_f32 v[64:65], v[104:105], v[186:187] op_sel_hi:[1,0]
	ds_write_b128 v204, v[64:67] offset:16
	v_pk_mul_f32 v[66:67], v[14:15], v[184:185] op_sel_hi:[1,0]
	v_pk_mul_f32 v[64:65], v[12:13], v[184:185] op_sel_hi:[1,0]
	ds_write_b128 v205, v[64:67]
	v_pk_mul_f32 v[66:67], v[10:11], v[184:185] op_sel_hi:[1,0]
	v_pk_mul_f32 v[64:65], v[8:9], v[184:185] op_sel_hi:[1,0]
	ds_write_b128 v204, v[64:67] offset:2064
.LBB0_293:
	s_or_b64 exec, exec, s[6:7]
	v_lshl_or_b32 v182, s8, 7, v173
	v_ashrrev_i32_e32 v183, 31, v182
	v_lshlrev_b64 v[64:65], 2, v[182:183]
	s_waitcnt lgkmcnt(0)
	s_barrier
; #define PG8_LAS __attribute__((address_space(3)))
; __device__ __forceinline__ float dpp_ror1(float v) { return __int_as_float(__builtin_amdgcn_update_dpp(0, __float_as_int(v), 0x121, 0xf, 0xf, false)); }
; __device__ __forceinline__ float dpp_ror2(float v) { return __int_as_float(__builtin_amdgcn_update_dpp(0, __float_as_int(v), 0x122, 0xf, 0xf, false)); }
;     __device__ __forceinline__ void operator()(const f32x4 (&acc)[2][2][4][2], const Unit& u, int wr, int wc, int fr, int fq) const {
;     ...
;         f32x4 w0[2], w1[2], w2[2], bb[2];
; #pragma unroll
;         for (int n = 0; n < 2; ++n) { w0[n] = *(const f32x4*)(cw + f0 + 4 * n); w1[n] = *(const f32x4*)(cw + 2816 + f0 + 4 * n); w2[n] = *(const f32x4*)(cw + 2 * 2816 + f0 + 4 * n); bb[n] = *(const f32x4*)(cb + f0 + 4 * n); }
; #pragma unroll
;         for (int ai = 0; ai < 2; ++ai) {
;             const int blk = ai * 2 + wr;
;             f32x4 pc1[2], pc2[2];
; #pragma unroll
;             for (int n = 0; n < 2; ++n) { f32x4 hv = {0.f, 0.f, 0.f, 0.f};
;                 if (blk > 0 && fr >= 14) hv = *(const PG8_LAS f32x4*)(halo + ((blk - 1) * 2 + (fr - 14)) * 128 + fl + 4 * n);
; #pragma unroll
;                 for (int j = 0; j < 4; ++j) { pc1[n][j] = dpp_ror1(hv[j]); pc2[n][j] = dpp_ror2(hv[j]); } }
; #pragma unroll
;             for (int m = 0; m < 4; ++m) { const int r = ai * HALF + wr * 64 + m * 16 + fr, tk = 254 * i - 2 + r;
;                 f32x4 o[2];
; #pragma unroll
;                 for (int n = 0; n < 2; ++n) { f32x4 cur = acc[ai][0][m][n] * rn[ai][m]; if (tk < 0) cur = (f32x4){0.f, 0.f, 0.f, 0.f};
; #pragma unroll
;                     for (int j = 0; j < 4; ++j) { const float c1 = dpp_ror1(cur[j]), c2 = dpp_ror2(cur[j]);
;                         const float p1 = fr >= 1 ? c1 : pc1[n][j], p2 = fr >= 2 ? c2 : pc2[n][j]; pc1[n][j] = c1; pc2[n][j] = c2;
	v_lshl_add_u64 v[66:67], s[20:21], 0, v[64:65]
	v_lshl_add_u64 v[68:69], s[66:67], 0, v[64:65]
	v_lshl_add_u64 v[76:77], s[68:69], 0, v[64:65]
	v_lshl_add_u64 v[100:101], s[26:27], 0, v[64:65]
	global_load_dwordx4 v[72:75], v[66:67], off offset:16
	global_load_dwordx4 v[96:99], v[66:67], off
	s_nop 0
	global_load_dwordx4 v[64:67], v[68:69], off offset:16
	global_load_dwordx4 v[88:91], v[68:69], off
	s_nop 0
	global_load_dwordx4 v[68:71], v[76:77], off offset:16
	global_load_dwordx4 v[92:95], v[76:77], off
	s_nop 0
	global_load_dwordx4 v[76:79], v[100:101], off offset:16
	s_nop 0
	global_load_dwordx4 v[100:103], v[100:101], off
	v_mov_b32_e32 v160, 0
	v_mov_b32_e32 v162, 0
	v_mov_b32_e32 v163, 0
	v_mov_b32_e32 v164, 0
	v_mov_b32_e32 v165, 0
	s_and_saveexec_b64 s[6:7], s[60:61]
	ds_read_b128 v[162:165], v206
	s_or_b64 exec, exec, s[6:7]
	v_mov_b32_e32 v228, 0
	v_mov_b32_e32 v230, 0
	v_mov_b32_e32 v229, 0
	v_mov_b32_e32 v231, 0
	v_mov_b32_e32 v236, 0
	v_mov_b32_e32 v238, 0
	v_mov_b32_e32 v237, 0
	v_mov_b32_e32 v239, 0
	s_waitcnt lgkmcnt(0)
	v_mov_b32_dpp v228, v162 row_ror:1 row_mask:0xf bank_mask:0xf
	v_mov_b32_dpp v230, v162 row_ror:2 row_mask:0xf bank_mask:0xf
	v_mov_b32_dpp v229, v163 row_ror:1 row_mask:0xf bank_mask:0xf
	v_mov_b32_dpp v231, v163 row_ror:2 row_mask:0xf bank_mask:0xf
	v_mov_b32_dpp v236, v164 row_ror:1 row_mask:0xf bank_mask:0xf
	v_mov_b32_dpp v238, v164 row_ror:2 row_mask:0xf bank_mask:0xf
	v_mov_b32_dpp v237, v165 row_ror:1 row_mask:0xf bank_mask:0xf
	v_mov_b32_dpp v239, v165 row_ror:2 row_mask:0xf bank_mask:0xf
	v_mov_b32_e32 v161, 0
	v_mov_b32_e32 v162, 0
	v_mov_b32_e32 v163, 0
	s_and_saveexec_b64 s[6:7], s[60:61]
	ds_read_b128 v[160:163], v206 offset:16
	s_or_b64 exec, exec, s[6:7]
	v_pk_add_f32 v[164:165], v[192:193], v[194:195]
	s_add_i32 s77, s77, -2
	v_pk_fma_f32 v[164:165], v[164:165], s[78:79], v[210:211] op_sel_hi:[1,0,0]
	v_add_u32_e32 v227, s77, v172
	v_mul_f32_e32 v192, 0x4b800000, v165
	v_cmp_gt_f32_e64 s[8:9], s39, v165
	v_mov_b32_e32 v240, v209
	v_mov_b32_e32 v242, v209
	v_cndmask_b32_e64 v165, v165, v192, s[8:9]
	v_rsq_f32_e32 v165, v165
	v_mov_b32_e32 v241, v209
	v_mov_b32_e32 v243, v209
	s_waitcnt lgkmcnt(0)
	v_mov_b32_dpp v240, v160 row_ror:1 row_mask:0xf bank_mask:0xf
	v_mul_f32_e32 v192, 0x45800000, v165
	v_cndmask_b32_e64 v192, v165, v192, s[8:9]
	v_pk_mul_f32 v[156:157], v[156:157], v[192:193] op_sel_hi:[1,0]
	v_cmp_gt_i32_e64 s[8:9], 0, v227
	v_pk_mul_f32 v[158:159], v[158:159], v[192:193] op_sel_hi:[1,0]
	v_mov_b32_e32 v193, v209
	v_cndmask_b32_e64 v157, v157, 0, s[8:9]
	v_mov_b32_dpp v242, v160 row_ror:2 row_mask:0xf bank_mask:0xf
	v_mov_b32_dpp v241, v161 row_ror:1 row_mask:0xf bank_mask:0xf
	v_mov_b32_dpp v193, v157 row_ror:1 row_mask:0xf bank_mask:0xf
	v_mov_b32_dpp v243, v161 row_ror:2 row_mask:0xf bank_mask:0xf
	v_mov_b32_e32 v232, v209
	v_mov_b32_e32 v234, v209
	v_mov_b32_e32 v233, v209
	v_mov_b32_e32 v235, v209
	v_pk_mul_f32 v[160:161], v[152:153], v[192:193] op_sel_hi:[1,0]
	v_pk_mul_f32 v[152:153], v[154:155], v[192:193] op_sel_hi:[1,0]
	v_mov_b32_dpp v232, v162 row_ror:1 row_mask:0xf bank_mask:0xf
	v_mov_b32_dpp v234, v162 row_ror:2 row_mask:0xf bank_mask:0xf
	v_mov_b32_dpp v233, v163 row_ror:1 row_mask:0xf bank_mask:0xf
	v_mov_b32_dpp v235, v163 row_ror:2 row_mask:0xf bank_mask:0xf
	v_cndmask_b32_e64 v159, v159, 0, s[8:9]
	v_cndmask_b32_e64 v158, v158, 0, s[8:9]
	v_cndmask_b32_e64 v156, v156, 0, s[8:9]
	v_mov_b32_e32 v165, v209
	v_mov_b32_e32 v194, v209
	v_mov_b32_e32 v195, v209
	v_mov_b32_e32 v219, v209
	v_mov_b32_e32 v221, v209
	v_mov_b32_e32 v220, v209
	v_mov_b32_e32 v222, v209
	v_cndmask_b32_e64 v153, v153, 0, s[8:9]
	v_cndmask_b32_e64 v152, v152, 0, s[8:9]
	v_cndmask_b32_e64 v155, v161, 0, s[8:9]
	v_cndmask_b32_e64 v154, v160, 0, s[8:9]
	v_mov_b32_e32 v223, v209
	v_mov_b32_e32 v225, v209
	v_mov_b32_e32 v224, v209
	v_mov_b32_e32 v226, v209
	v_mov_b32_e32 v160, v209
	v_mov_b32_e32 v162, v209
	v_mov_b32_e32 v161, v209
	v_mov_b32_e32 v163, v209
	v_cmp_gt_i32_e64 s[8:9], s83, v227
	s_lshl_b32 s71, s76, 12
	v_cmp_gt_f32_e64 s[6:7], s39, v164
	v_mov_b32_dpp v165, v156 row_ror:1 row_mask:0xf bank_mask:0xf
	v_mov_b32_dpp v194, v156 row_ror:2 row_mask:0xf bank_mask:0xf
	v_mov_b32_dpp v195, v157 row_ror:2 row_mask:0xf bank_mask:0xf
	v_mov_b32_dpp v219, v158 row_ror:1 row_mask:0xf bank_mask:0xf
	v_mov_b32_dpp v221, v158 row_ror:2 row_mask:0xf bank_mask:0xf
	v_mov_b32_dpp v220, v159 row_ror:1 row_mask:0xf bank_mask:0xf
	v_mov_b32_dpp v222, v159 row_ror:2 row_mask:0xf bank_mask:0xf
	v_mov_b32_dpp v223, v154 row_ror:1 row_mask:0xf bank_mask:0xf
	v_mov_b32_dpp v225, v154 row_ror:2 row_mask:0xf bank_mask:0xf
	v_mov_b32_dpp v224, v155 row_ror:1 row_mask:0xf bank_mask:0xf
	v_mov_b32_dpp v226, v155 row_ror:2 row_mask:0xf bank_mask:0xf
	v_mov_b32_dpp v160, v152 row_ror:1 row_mask:0xf bank_mask:0xf
	v_mov_b32_dpp v162, v152 row_ror:2 row_mask:0xf bank_mask:0xf
	v_mov_b32_dpp v161, v153 row_ror:1 row_mask:0xf bank_mask:0xf
	v_mov_b32_dpp v163, v153 row_ror:2 row_mask:0xf bank_mask:0xf
	s_and_b64 s[18:19], s[46:47], s[8:9]
	s_waitcnt vmcnt(0)
	s_and_saveexec_b64 s[8:9], s[18:19]
	s_cbranch_execz .LBB0_299
; __device__ __forceinline__ u32x4 pack8(const f32x4& v0, const f32x4& v1) { u32x4 w; w.x = cvt_pk_bf16(v0[0], v0[1]); w.y = cvt_pk_bf16(v0[2], v0[3]); w.z = cvt_pk_bf16(v1[0], v1[1]); w.w = cvt_pk_bf16(v1[2], v1[3]); return w; }
; __device__ __forceinline__ float dpp_ror1(float v) { return __int_as_float(__builtin_amdgcn_update_dpp(0, __float_as_int(v), 0x121, 0xf, 0xf, false)); }
; __device__ __forceinline__ float dpp_ror2(float v) { return __int_as_float(__builtin_amdgcn_update_dpp(0, __float_as_int(v), 0x122, 0xf, 0xf, false)); }
;     __device__ __forceinline__ void operator()(const f32x4 (&acc)[2][2][4][2], const Unit& u, int wr, int wc, int fr, int fq) const {
;     ...
;                     for (int j = 0; j < 4; ++j) { const float c1 = dpp_ror1(cur[j]), c2 = dpp_ror2(cur[j]);
;                         const float p1 = fr >= 1 ? c1 : pc1[n][j], p2 = fr >= 2 ? c2 : pc2[n][j]; pc1[n][j] = c1; pc2[n][j] = c2;
;                         const float cv = bb[n][j] + w0[n][j] * p2 + w1[n][j] * p1 + w2[n][j] * cur[j];
;                         o[n][j] = gelu_t(cv) * (acc[ai][1][m][n][j] * rn[ai][m]); } }
;                 if (r >= 2 && tk < 4096) *(u32x4*)(ACT + (size_t)(b * 4096 + tk) * 2816 + f0) = pack8(o[0], o[1]); }
	v_cndmask_b32_e64 v213, v243, v226, s[44:45]
	v_cndmask_b32_e64 v212, v242, v225, s[44:45]
	v_pk_fma_f32 v[212:213], v[72:73], v[212:213], v[76:77]
	v_cndmask_b32_e64 v215, v224, v241, s[42:43]
	v_cndmask_b32_e64 v214, v223, v240, s[42:43]
	v_pk_fma_f32 v[212:213], v[64:65], v[214:215], v[212:213]
	v_pk_mul_f32 v[144:145], v[144:145], v[192:193] op_sel_hi:[1,0]
	v_pk_fma_f32 v[154:155], v[154:155], v[68:69], v[212:213]
	v_pk_mul_f32 v[150:151], v[150:151], v[192:193] op_sel_hi:[1,0]
	v_mul_f32_e32 v212, 0x3d122279, v154
	v_mul_f32_e32 v213, 0x3d122279, v155
	v_fmaak_f32 v212, v154, v212, 0x3f4c422a
	v_fmaak_f32 v213, v155, v213, 0x3f4c422a
	v_mul_f32_e32 v212, v154, v212
	v_mul_f32_e32 v213, v155, v213
	v_mul_f32_e32 v212, 0xc038aa3b, v212
	v_mul_f32_e32 v213, 0xc038aa3b, v213
	v_exp_f32_e32 v212, v212
	v_exp_f32_e32 v213, v213
	v_pk_mul_f32 v[148:149], v[148:149], v[192:193] op_sel_hi:[1,0]
	v_pk_mul_f32 v[146:147], v[146:147], v[192:193] op_sel_hi:[1,0]
	v_add_f32_e32 v212, 1.0, v212
	v_add_f32_e32 v213, 1.0, v213
	v_rcp_f32_e32 v212, v212
	v_rcp_f32_e32 v213, v213
	s_nop 0
	v_pk_mul_f32 v[154:155], v[154:155], v[212:213]
	s_nop 0
	v_pk_mul_f32 v[154:155], v[144:145], v[154:155]
	v_cndmask_b32_e64 v145, v239, v222, s[44:45]
	v_cndmask_b32_e64 v144, v238, v221, s[44:45]
	v_pk_fma_f32 v[144:145], v[98:99], v[144:145], v[102:103]
	v_cndmask_b32_e64 v213, v220, v237, s[42:43]
	v_cndmask_b32_e64 v212, v219, v236, s[42:43]
	v_pk_fma_f32 v[144:145], v[90:91], v[212:213], v[144:145]
	s_nop 0
	v_pk_fma_f32 v[144:145], v[158:159], v[94:95], v[144:145]
	s_nop 0
	v_mul_f32_e32 v158, 0x3d122279, v144
	v_mul_f32_e32 v159, 0x3d122279, v145
	v_fmaak_f32 v158, v144, v158, 0x3f4c422a
	v_fmaak_f32 v159, v145, v159, 0x3f4c422a
	v_mul_f32_e32 v158, v144, v158
	v_mul_f32_e32 v159, v145, v159
	v_mul_f32_e32 v158, 0xc038aa3b, v158
	v_mul_f32_e32 v159, 0xc038aa3b, v159
	v_exp_f32_e32 v158, v158
	v_exp_f32_e32 v159, v159
	v_add_f32_e32 v158, 1.0, v158
	v_add_f32_e32 v159, 1.0, v159
	v_rcp_f32_e32 v158, v158
	v_rcp_f32_e32 v159, v159
	s_nop 0
	v_pk_mul_f32 v[144:145], v[144:145], v[158:159]
	s_nop 0
	v_pk_mul_f32 v[150:151], v[150:151], v[144:145]
	v_cndmask_b32_e64 v145, v231, v195, s[44:45]
	v_cndmask_b32_e64 v144, v230, v194, s[44:45]
	v_pk_fma_f32 v[144:145], v[96:97], v[144:145], v[100:101]
	v_cndmask_b32_e64 v159, v193, v229, s[42:43]
	v_cndmask_b32_e64 v158, v165, v228, s[42:43]
	v_pk_fma_f32 v[144:145], v[88:89], v[158:159], v[144:145]
	s_nop 0
	v_pk_fma_f32 v[144:145], v[156:157], v[92:93], v[144:145]
	s_nop 0
	v_mul_f32_e32 v156, 0x3d122279, v144
	v_mul_f32_e32 v157, 0x3d122279, v145
	v_fmaak_f32 v156, v144, v156, 0x3f4c422a
	v_fmaak_f32 v157, v145, v157, 0x3f4c422a
	v_mul_f32_e32 v156, v144, v156
	v_mul_f32_e32 v157, v145, v157
	v_mul_f32_e32 v156, 0xc038aa3b, v156
	v_mul_f32_e32 v157, 0xc038aa3b, v157
	v_exp_f32_e32 v156, v156
	v_exp_f32_e32 v157, v157
	v_add_f32_e32 v156, 1.0, v156
	v_add_f32_e32 v157, 1.0, v157
	v_rcp_f32_e32 v156, v156
	v_rcp_f32_e32 v157, v157
	s_nop 0
	v_pk_mul_f32 v[144:145], v[144:145], v[156:157]
	s_nop 0
	v_pk_mul_f32 v[144:145], v[148:149], v[144:145]
	v_cndmask_b32_e64 v149, v235, v163, s[44:45]
	v_cndmask_b32_e64 v148, v234, v162, s[44:45]
	v_cndmask_b32_e64 v157, v161, v233, s[42:43]
	v_cndmask_b32_e64 v156, v160, v232, s[42:43]
	v_pk_fma_f32 v[148:149], v[74:75], v[148:149], v[78:79]
	v_cvt_pk_bf16_f32 v144, v144, v145
	v_pk_fma_f32 v[148:149], v[66:67], v[156:157], v[148:149]
	v_cvt_pk_bf16_f32 v145, v150, v151
	v_pk_fma_f32 v[148:149], v[152:153], v[70:71], v[148:149]
	v_add_u32_e32 v150, s71, v227
	v_mul_f32_e32 v152, 0x3d122279, v148
	v_mul_f32_e32 v153, 0x3d122279, v149
	v_fmaak_f32 v152, v148, v152, 0x3f4c422a
	v_fmaak_f32 v153, v149, v153, 0x3f4c422a
	v_mul_f32_e32 v152, v148, v152
	v_mul_f32_e32 v153, v149, v153
	v_mul_f32_e32 v152, 0xc038aa3b, v152
	v_mul_f32_e32 v153, 0xc038aa3b, v153
	v_exp_f32_e32 v152, v152
	v_exp_f32_e32 v153, v153
	v_add_f32_e32 v152, 1.0, v152
	v_add_f32_e32 v153, 1.0, v153
	v_rcp_f32_e32 v152, v152
	v_rcp_f32_e32 v153, v153
	s_nop 0
	v_pk_mul_f32 v[148:149], v[148:149], v[152:153]
	s_nop 0
	v_pk_mul_f32 v[148:149], v[146:147], v[148:149]
	v_cvt_pk_bf16_f32 v146, v154, v155
	v_cvt_pk_bf16_f32 v147, v148, v149
	v_mov_b64_e32 v[148:149], s[12:13]
	v_mad_i64_i32 v[148:149], s[18:19], v150, s34, v[148:149]
	v_lshl_add_u64 v[148:149], v[182:183], 1, v[148:149]
	global_store_dwordx4 v[148:149], v[144:147], off
; __device__ __forceinline__ u32x4 pack8(const f32x4& v0, const f32x4& v1) { u32x4 w; w.x = cvt_pk_bf16(v0[0], v0[1]); w.y = cvt_pk_bf16(v0[2], v0[3]); w.z = cvt_pk_bf16(v1[0], v1[1]); w.w = cvt_pk_bf16(v1[2], v1[3]); return w; }
; __device__ __forceinline__ float dpp_ror1(float v) { return __int_as_float(__builtin_amdgcn_update_dpp(0, __float_as_int(v), 0x121, 0xf, 0xf, false)); }
; __device__ __forceinline__ float dpp_ror2(float v) { return __int_as_float(__builtin_amdgcn_update_dpp(0, __float_as_int(v), 0x122, 0xf, 0xf, false)); }
;     __device__ __forceinline__ void operator()(const f32x4 (&acc)[2][2][4][2], const Unit& u, int wr, int wc, int fr, int fq) const {
;     ...
;             for (int m = 0; m < 4; ++m) { const int r = ai * HALF + wr * 64 + m * 16 + fr, tk = 254 * i - 2 + r;
;                 f32x4 o[2];
; #pragma unroll
;                 for (int n = 0; n < 2; ++n) { f32x4 cur = acc[ai][0][m][n] * rn[ai][m]; if (tk < 0) cur = (f32x4){0.f, 0.f, 0.f, 0.f};
; #pragma unroll
;                     for (int j = 0; j < 4; ++j) { const float c1 = dpp_ror1(cur[j]), c2 = dpp_ror2(cur[j]);
;                         const float p1 = fr >= 1 ? c1 : pc1[n][j], p2 = fr >= 2 ? c2 : pc2[n][j]; pc1[n][j] = c1; pc2[n][j] = c2;
;                         const float cv = bb[n][j] + w0[n][j] * p2 + w1[n][j] * p1 + w2[n][j] * cur[j];
;                         o[n][j] = gelu_t(cv) * (acc[ai][1][m][n][j] * rn[ai][m]); } }
;                 if (r >= 2 && tk < 4096) *(u32x4*)(ACT + (size_t)(b * 4096 + tk) * 2816 + f0) = pack8(o[0], o[1]); }
.LBB0_299:
	s_or_b64 exec, exec, s[8:9]
	s_nop 0
	v_mul_f32_e32 v144, 0x4b800000, v164
	v_cndmask_b32_e64 v144, v164, v144, s[6:7]
	v_rsq_f32_e32 v144, v144
	v_add_u32_e32 v192, s77, v197
	v_mov_b32_e32 v149, v209
	v_mov_b32_e32 v151, v209
	v_mul_f32_e32 v145, 0x45800000, v144
	v_cndmask_b32_e64 v144, v144, v145, s[6:7]
	v_pk_mul_f32 v[140:141], v[140:141], v[144:145] op_sel_hi:[1,0]
	v_pk_mul_f32 v[142:143], v[142:143], v[144:145] op_sel_hi:[1,0]
	v_cmp_gt_i32_e64 s[6:7], 0, v192
	v_pk_mul_f32 v[146:147], v[136:137], v[144:145] op_sel_hi:[1,0]
	v_pk_mul_f32 v[136:137], v[138:139], v[144:145] op_sel_hi:[1,0]
	v_cndmask_b32_e64 v143, v143, 0, s[6:7]
	v_cndmask_b32_e64 v142, v142, 0, s[6:7]
	v_cndmask_b32_e64 v141, v141, 0, s[6:7]
	v_cndmask_b32_e64 v140, v140, 0, s[6:7]
	v_mov_b32_e32 v150, v209
	v_mov_b32_e32 v152, v209
	v_mov_b32_e32 v153, v209
	v_mov_b32_e32 v155, v209
	v_mov_b32_e32 v154, v209
	v_mov_b32_e32 v156, v209
	v_cndmask_b32_e64 v137, v137, 0, s[6:7]
	v_cndmask_b32_e64 v136, v136, 0, s[6:7]
	v_cndmask_b32_e64 v139, v147, 0, s[6:7]
	v_cndmask_b32_e64 v138, v146, 0, s[6:7]
	v_mov_b32_e32 v157, v209
	v_mov_b32_e32 v159, v209
	v_mov_b32_e32 v158, v209
	v_mov_b32_e32 v164, v209
	v_mov_b32_e32 v145, v209
	v_mov_b32_e32 v147, v209
	v_mov_b32_e32 v146, v209
	v_mov_b32_e32 v148, v209
	v_cmp_gt_i32_e64 s[6:7], s83, v192
	v_mov_b32_dpp v149, v140 row_ror:1 row_mask:0xf bank_mask:0xf
	v_mov_b32_dpp v151, v140 row_ror:2 row_mask:0xf bank_mask:0xf
	v_mov_b32_dpp v150, v141 row_ror:1 row_mask:0xf bank_mask:0xf
	v_mov_b32_dpp v152, v141 row_ror:2 row_mask:0xf bank_mask:0xf
	v_mov_b32_dpp v153, v142 row_ror:1 row_mask:0xf bank_mask:0xf
	v_mov_b32_dpp v155, v142 row_ror:2 row_mask:0xf bank_mask:0xf
	v_mov_b32_dpp v154, v143 row_ror:1 row_mask:0xf bank_mask:0xf
	v_mov_b32_dpp v156, v143 row_ror:2 row_mask:0xf bank_mask:0xf
	v_mov_b32_dpp v157, v138 row_ror:1 row_mask:0xf bank_mask:0xf
	v_mov_b32_dpp v159, v138 row_ror:2 row_mask:0xf bank_mask:0xf
	v_mov_b32_dpp v158, v139 row_ror:1 row_mask:0xf bank_mask:0xf
	v_mov_b32_dpp v164, v139 row_ror:2 row_mask:0xf bank_mask:0xf
	v_mov_b32_dpp v145, v136 row_ror:1 row_mask:0xf bank_mask:0xf
	v_mov_b32_dpp v147, v136 row_ror:2 row_mask:0xf bank_mask:0xf
	v_mov_b32_dpp v146, v137 row_ror:1 row_mask:0xf bank_mask:0xf
	v_mov_b32_dpp v148, v137 row_ror:2 row_mask:0xf bank_mask:0xf
	s_and_b64 s[8:9], s[62:63], s[6:7]
	s_and_saveexec_b64 s[6:7], s[8:9]
	s_cbranch_execz .LBB0_301
	v_cndmask_b32_e64 v213, v226, v164, s[44:45]
	v_cndmask_b32_e64 v212, v225, v159, s[44:45]
	v_pk_fma_f32 v[212:213], v[72:73], v[212:213], v[76:77]
	v_cndmask_b32_e64 v215, v158, v224, s[42:43]
	v_cndmask_b32_e64 v214, v157, v223, s[42:43]
	v_pk_fma_f32 v[212:213], v[64:65], v[214:215], v[212:213]
	v_pk_mul_f32 v[128:129], v[128:129], v[144:145] op_sel_hi:[1,0]
	v_pk_fma_f32 v[138:139], v[138:139], v[68:69], v[212:213]
	v_pk_mul_f32 v[134:135], v[134:135], v[144:145] op_sel_hi:[1,0]
	v_mul_f32_e32 v212, 0x3d122279, v138
	v_mul_f32_e32 v213, 0x3d122279, v139
	v_fmaak_f32 v212, v138, v212, 0x3f4c422a
	v_fmaak_f32 v213, v139, v213, 0x3f4c422a
	v_mul_f32_e32 v212, v138, v212
	v_mul_f32_e32 v213, v139, v213
	v_mul_f32_e32 v212, 0xc038aa3b, v212
	v_mul_f32_e32 v213, 0xc038aa3b, v213
	v_exp_f32_e32 v212, v212
	v_exp_f32_e32 v213, v213
	v_pk_mul_f32 v[132:133], v[132:133], v[144:145] op_sel_hi:[1,0]
	v_pk_mul_f32 v[130:131], v[130:131], v[144:145] op_sel_hi:[1,0]
	v_add_f32_e32 v212, 1.0, v212
	v_add_f32_e32 v213, 1.0, v213
	v_rcp_f32_e32 v212, v212
	v_rcp_f32_e32 v213, v213
	s_nop 0
	v_pk_mul_f32 v[138:139], v[138:139], v[212:213]
	s_nop 0
	v_pk_mul_f32 v[138:139], v[128:129], v[138:139]
	v_cndmask_b32_e64 v129, v222, v156, s[44:45]
	v_cndmask_b32_e64 v128, v221, v155, s[44:45]
	v_pk_fma_f32 v[128:129], v[98:99], v[128:129], v[102:103]
	v_cndmask_b32_e64 v213, v154, v220, s[42:43]
	v_cndmask_b32_e64 v212, v153, v219, s[42:43]
	v_pk_fma_f32 v[128:129], v[90:91], v[212:213], v[128:129]
	s_nop 0
	v_pk_fma_f32 v[128:129], v[142:143], v[94:95], v[128:129]
	s_nop 0
	v_mul_f32_e32 v142, 0x3d122279, v128
	v_mul_f32_e32 v143, 0x3d122279, v129
	v_fmaak_f32 v142, v128, v142, 0x3f4c422a
	v_fmaak_f32 v143, v129, v143, 0x3f4c422a
	v_mul_f32_e32 v142, v128, v142
	v_mul_f32_e32 v143, v129, v143
	v_mul_f32_e32 v142, 0xc038aa3b, v142
	v_mul_f32_e32 v143, 0xc038aa3b, v143
	v_exp_f32_e32 v142, v142
	v_exp_f32_e32 v143, v143
	v_add_f32_e32 v142, 1.0, v142
	v_add_f32_e32 v143, 1.0, v143
	v_rcp_f32_e32 v142, v142
	v_rcp_f32_e32 v143, v143
	s_nop 0
	v_pk_mul_f32 v[128:129], v[128:129], v[142:143]
	s_nop 0
	v_pk_mul_f32 v[134:135], v[134:135], v[128:129]
	v_cndmask_b32_e64 v129, v195, v152, s[44:45]
	v_cndmask_b32_e64 v128, v194, v151, s[44:45]
	v_pk_fma_f32 v[128:129], v[96:97], v[128:129], v[100:101]
	v_cndmask_b32_e64 v143, v150, v193, s[42:43]
	v_cndmask_b32_e64 v142, v149, v165, s[42:43]
	v_pk_fma_f32 v[128:129], v[88:89], v[142:143], v[128:129]
	s_nop 0
	v_pk_fma_f32 v[128:129], v[140:141], v[92:93], v[128:129]
	s_nop 0
	v_mul_f32_e32 v140, 0x3d122279, v128
	v_mul_f32_e32 v141, 0x3d122279, v129
	v_fmaak_f32 v140, v128, v140, 0x3f4c422a
	v_fmaak_f32 v141, v129, v141, 0x3f4c422a
	v_mul_f32_e32 v140, v128, v140
	v_mul_f32_e32 v141, v129, v141
	v_mul_f32_e32 v140, 0xc038aa3b, v140
	v_mul_f32_e32 v141, 0xc038aa3b, v141
	v_exp_f32_e32 v140, v140
	v_exp_f32_e32 v141, v141
	v_add_f32_e32 v140, 1.0, v140
	v_add_f32_e32 v141, 1.0, v141
	v_rcp_f32_e32 v140, v140
	v_rcp_f32_e32 v141, v141
	s_nop 0
	v_pk_mul_f32 v[128:129], v[128:129], v[140:141]
	s_nop 0
	v_pk_mul_f32 v[128:129], v[132:133], v[128:129]
	v_cndmask_b32_e64 v133, v163, v148, s[44:45]
	v_cndmask_b32_e64 v132, v162, v147, s[44:45]
	v_cndmask_b32_e64 v141, v146, v161, s[42:43]
	v_cndmask_b32_e64 v140, v145, v160, s[42:43]
	v_pk_fma_f32 v[132:133], v[74:75], v[132:133], v[78:79]
	v_cvt_pk_bf16_f32 v128, v128, v129
	v_pk_fma_f32 v[132:133], v[66:67], v[140:141], v[132:133]
	v_cvt_pk_bf16_f32 v129, v134, v135
	v_pk_fma_f32 v[132:133], v[136:137], v[70:71], v[132:133]
	v_add_u32_e32 v134, s71, v192
	v_mul_f32_e32 v136, 0x3d122279, v132
	v_mul_f32_e32 v137, 0x3d122279, v133
	v_fmaak_f32 v136, v132, v136, 0x3f4c422a
	v_fmaak_f32 v137, v133, v137, 0x3f4c422a
	v_mul_f32_e32 v136, v132, v136
	v_mul_f32_e32 v137, v133, v137
	v_mul_f32_e32 v136, 0xc038aa3b, v136
	v_mul_f32_e32 v137, 0xc038aa3b, v137
	v_exp_f32_e32 v136, v136
	v_exp_f32_e32 v137, v137
	v_add_f32_e32 v136, 1.0, v136
	v_add_f32_e32 v137, 1.0, v137
	v_rcp_f32_e32 v136, v136
	v_rcp_f32_e32 v137, v137
	s_nop 0
	v_pk_mul_f32 v[132:133], v[132:133], v[136:137]
	s_nop 0
	v_pk_mul_f32 v[132:133], v[130:131], v[132:133]
	v_cvt_pk_bf16_f32 v130, v138, v139
	v_cvt_pk_bf16_f32 v131, v132, v133
	v_mov_b64_e32 v[132:133], s[12:13]
	v_mad_i64_i32 v[132:133], s[8:9], v134, s34, v[132:133]
	v_lshl_add_u64 v[132:133], v[182:183], 1, v[132:133]
	global_store_dwordx4 v[132:133], v[128:131], off
; __device__ __forceinline__ u32x4 pack8(const f32x4& v0, const f32x4& v1) { u32x4 w; w.x = cvt_pk_bf16(v0[0], v0[1]); w.y = cvt_pk_bf16(v0[2], v0[3]); w.z = cvt_pk_bf16(v1[0], v1[1]); w.w = cvt_pk_bf16(v1[2], v1[3]); return w; }
; __device__ __forceinline__ float dpp_ror1(float v) { return __int_as_float(__builtin_amdgcn_update_dpp(0, __float_as_int(v), 0x121, 0xf, 0xf, false)); }
; __device__ __forceinline__ float dpp_ror2(float v) { return __int_as_float(__builtin_amdgcn_update_dpp(0, __float_as_int(v), 0x122, 0xf, 0xf, false)); }
;     __device__ __forceinline__ void operator()(const f32x4 (&acc)[2][2][4][2], const Unit& u, int wr, int wc, int fr, int fq) const {
;     ...
;             for (int m = 0; m < 4; ++m) { const int r = ai * HALF + wr * 64 + m * 16 + fr, tk = 254 * i - 2 + r;
;                 f32x4 o[2];
; #pragma unroll
;                 for (int n = 0; n < 2; ++n) { f32x4 cur = acc[ai][0][m][n] * rn[ai][m]; if (tk < 0) cur = (f32x4){0.f, 0.f, 0.f, 0.f};
; #pragma unroll
;                     for (int j = 0; j < 4; ++j) { const float c1 = dpp_ror1(cur[j]), c2 = dpp_ror2(cur[j]);
;                         const float p1 = fr >= 1 ? c1 : pc1[n][j], p2 = fr >= 2 ? c2 : pc2[n][j]; pc1[n][j] = c1; pc2[n][j] = c2;
;                         const float cv = bb[n][j] + w0[n][j] * p2 + w1[n][j] * p1 + w2[n][j] * cur[j];
;                         o[n][j] = gelu_t(cv) * (acc[ai][1][m][n][j] * rn[ai][m]); } }
;                 if (r >= 2 && tk < 4096) *(u32x4*)(ACT + (size_t)(b * 4096 + tk) * 2816 + f0) = pack8(o[0], o[1]); }
.LBB0_301:
	s_or_b64 exec, exec, s[6:7]
	s_nop 0
	v_mul_f32_e32 v128, 0x4b800000, v187
	v_cndmask_b32_e64 v128, v187, v128, s[4:5]
	v_rsq_f32_e32 v128, v128
	v_add_u32_e32 v160, s77, v198
	v_mov_b32_e32 v133, v209
	v_mov_b32_e32 v135, v209
	v_mul_f32_e32 v129, 0x45800000, v128
	v_cndmask_b32_e64 v128, v128, v129, s[4:5]
	v_pk_mul_f32 v[124:125], v[124:125], v[128:129] op_sel_hi:[1,0]
	v_pk_mul_f32 v[126:127], v[126:127], v[128:129] op_sel_hi:[1,0]
	v_cmp_gt_i32_e64 s[4:5], 0, v160
	v_pk_mul_f32 v[130:131], v[120:121], v[128:129] op_sel_hi:[1,0]
	v_pk_mul_f32 v[120:121], v[122:123], v[128:129] op_sel_hi:[1,0]
	v_cndmask_b32_e64 v127, v127, 0, s[4:5]
	v_cndmask_b32_e64 v126, v126, 0, s[4:5]
	v_cndmask_b32_e64 v125, v125, 0, s[4:5]
	v_cndmask_b32_e64 v124, v124, 0, s[4:5]
	v_mov_b32_e32 v134, v209
	v_mov_b32_e32 v136, v209
	v_mov_b32_e32 v137, v209
	v_mov_b32_e32 v139, v209
	v_mov_b32_e32 v138, v209
	v_mov_b32_e32 v140, v209
	v_cndmask_b32_e64 v121, v121, 0, s[4:5]
	v_cndmask_b32_e64 v120, v120, 0, s[4:5]
	v_cndmask_b32_e64 v123, v131, 0, s[4:5]
	v_cndmask_b32_e64 v122, v130, 0, s[4:5]
	v_mov_b32_e32 v141, v209
	v_mov_b32_e32 v143, v209
	v_mov_b32_e32 v142, v209
	v_mov_b32_e32 v144, v209
	v_mov_b32_e32 v129, v209
	v_mov_b32_e32 v131, v209
	v_mov_b32_e32 v130, v209
	v_mov_b32_e32 v132, v209
	v_cmp_gt_i32_e64 s[4:5], s83, v160
	v_mov_b32_dpp v133, v124 row_ror:1 row_mask:0xf bank_mask:0xf
	v_mov_b32_dpp v135, v124 row_ror:2 row_mask:0xf bank_mask:0xf
	v_mov_b32_dpp v134, v125 row_ror:1 row_mask:0xf bank_mask:0xf
	v_mov_b32_dpp v136, v125 row_ror:2 row_mask:0xf bank_mask:0xf
	v_mov_b32_dpp v137, v126 row_ror:1 row_mask:0xf bank_mask:0xf
	v_mov_b32_dpp v139, v126 row_ror:2 row_mask:0xf bank_mask:0xf
	v_mov_b32_dpp v138, v127 row_ror:1 row_mask:0xf bank_mask:0xf
	v_mov_b32_dpp v140, v127 row_ror:2 row_mask:0xf bank_mask:0xf
	v_mov_b32_dpp v141, v122 row_ror:1 row_mask:0xf bank_mask:0xf
	v_mov_b32_dpp v143, v122 row_ror:2 row_mask:0xf bank_mask:0xf
	v_mov_b32_dpp v142, v123 row_ror:1 row_mask:0xf bank_mask:0xf
	v_mov_b32_dpp v144, v123 row_ror:2 row_mask:0xf bank_mask:0xf
	v_mov_b32_dpp v129, v120 row_ror:1 row_mask:0xf bank_mask:0xf
	v_mov_b32_dpp v131, v120 row_ror:2 row_mask:0xf bank_mask:0xf
	v_mov_b32_dpp v130, v121 row_ror:1 row_mask:0xf bank_mask:0xf
	v_mov_b32_dpp v132, v121 row_ror:2 row_mask:0xf bank_mask:0xf
	s_and_b64 s[6:7], s[62:63], s[4:5]
	s_and_saveexec_b64 s[4:5], s[6:7]
	s_cbranch_execz .LBB0_303
	v_cndmask_b32_e64 v163, v164, v144, s[44:45]
	v_cndmask_b32_e64 v162, v159, v143, s[44:45]
	v_pk_fma_f32 v[162:163], v[72:73], v[162:163], v[76:77]
	v_cndmask_b32_e64 v159, v142, v158, s[42:43]
	v_cndmask_b32_e64 v158, v141, v157, s[42:43]
	v_pk_fma_f32 v[158:159], v[64:65], v[158:159], v[162:163]
	v_pk_mul_f32 v[112:113], v[112:113], v[128:129] op_sel_hi:[1,0]
	v_pk_fma_f32 v[122:123], v[122:123], v[68:69], v[158:159]
	v_pk_mul_f32 v[118:119], v[118:119], v[128:129] op_sel_hi:[1,0]
	v_mul_f32_e32 v157, 0x3d122279, v122
	v_fmaak_f32 v157, v122, v157, 0x3f4c422a
	v_mul_f32_e32 v157, v122, v157
	v_mul_f32_e32 v157, 0xc038aa3b, v157
	v_exp_f32_e32 v157, v157
	v_pk_mul_f32 v[116:117], v[116:117], v[128:129] op_sel_hi:[1,0]
	v_pk_mul_f32 v[114:115], v[114:115], v[128:129] op_sel_hi:[1,0]
	v_add_f32_e32 v157, 1.0, v157
	v_rcp_f32_e32 v158, v157
	v_mul_f32_e32 v157, 0x3d122279, v123
	v_fmaak_f32 v157, v123, v157, 0x3f4c422a
	v_mul_f32_e32 v157, v123, v157
	v_mul_f32_e32 v157, 0xc038aa3b, v157
	v_exp_f32_e32 v157, v157
	s_nop 0
	v_add_f32_e32 v157, 1.0, v157
	v_rcp_f32_e32 v159, v157
	s_nop 0
	v_pk_mul_f32 v[122:123], v[122:123], v[158:159]
	s_nop 0
	v_pk_mul_f32 v[122:123], v[112:113], v[122:123]
	v_cndmask_b32_e64 v113, v156, v140, s[44:45]
	v_cndmask_b32_e64 v112, v155, v139, s[44:45]
	v_pk_fma_f32 v[112:113], v[98:99], v[112:113], v[102:103]
	v_cndmask_b32_e64 v155, v138, v154, s[42:43]
	v_cndmask_b32_e64 v154, v137, v153, s[42:43]
	v_pk_fma_f32 v[112:113], v[90:91], v[154:155], v[112:113]
	s_nop 0
	v_pk_fma_f32 v[112:113], v[126:127], v[94:95], v[112:113]
	s_nop 0
	v_mul_f32_e32 v126, 0x3d122279, v112
	v_mul_f32_e32 v127, 0x3d122279, v113
	v_fmaak_f32 v126, v112, v126, 0x3f4c422a
	v_fmaak_f32 v127, v113, v127, 0x3f4c422a
	v_mul_f32_e32 v126, v112, v126
	v_mul_f32_e32 v127, v113, v127
	v_mul_f32_e32 v126, 0xc038aa3b, v126
	v_mul_f32_e32 v127, 0xc038aa3b, v127
	v_exp_f32_e32 v126, v126
	v_exp_f32_e32 v127, v127
	v_add_f32_e32 v126, 1.0, v126
	v_add_f32_e32 v127, 1.0, v127
	v_rcp_f32_e32 v126, v126
	v_rcp_f32_e32 v127, v127
	s_nop 0
	v_pk_mul_f32 v[112:113], v[112:113], v[126:127]
	s_nop 0
	v_pk_mul_f32 v[118:119], v[118:119], v[112:113]
	v_cndmask_b32_e64 v113, v152, v136, s[44:45]
	v_cndmask_b32_e64 v112, v151, v135, s[44:45]
	v_pk_fma_f32 v[112:113], v[96:97], v[112:113], v[100:101]
	v_cndmask_b32_e64 v127, v134, v150, s[42:43]
	v_cndmask_b32_e64 v126, v133, v149, s[42:43]
	v_pk_fma_f32 v[112:113], v[88:89], v[126:127], v[112:113]
	s_nop 0
	v_pk_fma_f32 v[112:113], v[124:125], v[92:93], v[112:113]
	s_nop 0
	v_mul_f32_e32 v124, 0x3d122279, v112
	v_mul_f32_e32 v125, 0x3d122279, v113
	v_fmaak_f32 v124, v112, v124, 0x3f4c422a
	v_fmaak_f32 v125, v113, v125, 0x3f4c422a
	v_mul_f32_e32 v124, v112, v124
	v_mul_f32_e32 v125, v113, v125
	v_mul_f32_e32 v124, 0xc038aa3b, v124
	v_mul_f32_e32 v125, 0xc038aa3b, v125
	v_exp_f32_e32 v124, v124
	v_exp_f32_e32 v125, v125
	v_add_f32_e32 v124, 1.0, v124
	v_add_f32_e32 v125, 1.0, v125
	v_rcp_f32_e32 v124, v124
	v_rcp_f32_e32 v125, v125
	s_nop 0
	v_pk_mul_f32 v[112:113], v[112:113], v[124:125]
	s_nop 0
	v_pk_mul_f32 v[112:113], v[116:117], v[112:113]
	v_cndmask_b32_e64 v117, v148, v132, s[44:45]
	v_cndmask_b32_e64 v116, v147, v131, s[44:45]
	v_cndmask_b32_e64 v125, v130, v146, s[42:43]
	v_cndmask_b32_e64 v124, v129, v145, s[42:43]
	v_pk_fma_f32 v[116:117], v[74:75], v[116:117], v[78:79]
	v_cvt_pk_bf16_f32 v112, v112, v113
	v_pk_fma_f32 v[116:117], v[66:67], v[124:125], v[116:117]
	v_cvt_pk_bf16_f32 v113, v118, v119
	v_pk_fma_f32 v[116:117], v[120:121], v[70:71], v[116:117]
	v_add_u32_e32 v118, s71, v160
	v_mul_f32_e32 v120, 0x3d122279, v116
	v_mul_f32_e32 v121, 0x3d122279, v117
	v_fmaak_f32 v120, v116, v120, 0x3f4c422a
	v_fmaak_f32 v121, v117, v121, 0x3f4c422a
	v_mul_f32_e32 v120, v116, v120
	v_mul_f32_e32 v121, v117, v121
	v_mul_f32_e32 v120, 0xc038aa3b, v120
	v_mul_f32_e32 v121, 0xc038aa3b, v121
	v_exp_f32_e32 v120, v120
	v_exp_f32_e32 v121, v121
	v_add_f32_e32 v120, 1.0, v120
	v_add_f32_e32 v121, 1.0, v121
	v_rcp_f32_e32 v120, v120
	v_rcp_f32_e32 v121, v121
	s_nop 0
	v_pk_mul_f32 v[116:117], v[116:117], v[120:121]
	s_nop 0
	v_pk_mul_f32 v[116:117], v[114:115], v[116:117]
	v_cvt_pk_bf16_f32 v114, v122, v123
	v_cvt_pk_bf16_f32 v115, v116, v117
	v_mov_b64_e32 v[116:117], s[12:13]
	v_mad_i64_i32 v[116:117], s[6:7], v118, s34, v[116:117]
	v_lshl_add_u64 v[116:117], v[182:183], 1, v[116:117]
	global_store_dwordx4 v[116:117], v[112:115], off
; __device__ __forceinline__ u32x4 pack8(const f32x4& v0, const f32x4& v1) { u32x4 w; w.x = cvt_pk_bf16(v0[0], v0[1]); w.y = cvt_pk_bf16(v0[2], v0[3]); w.z = cvt_pk_bf16(v1[0], v1[1]); w.w = cvt_pk_bf16(v1[2], v1[3]); return w; }
; __device__ __forceinline__ float dpp_ror1(float v) { return __int_as_float(__builtin_amdgcn_update_dpp(0, __float_as_int(v), 0x121, 0xf, 0xf, false)); }
; __device__ __forceinline__ float dpp_ror2(float v) { return __int_as_float(__builtin_amdgcn_update_dpp(0, __float_as_int(v), 0x122, 0xf, 0xf, false)); }
;     __device__ __forceinline__ void operator()(const f32x4 (&acc)[2][2][4][2], const Unit& u, int wr, int wc, int fr, int fq) const {
;     ...
;             for (int m = 0; m < 4; ++m) { const int r = ai * HALF + wr * 64 + m * 16 + fr, tk = 254 * i - 2 + r;
;                 f32x4 o[2];
; #pragma unroll
;                 for (int n = 0; n < 2; ++n) { f32x4 cur = acc[ai][0][m][n] * rn[ai][m]; if (tk < 0) cur = (f32x4){0.f, 0.f, 0.f, 0.f};
; #pragma unroll
;                     for (int j = 0; j < 4; ++j) { const float c1 = dpp_ror1(cur[j]), c2 = dpp_ror2(cur[j]);
;                         const float p1 = fr >= 1 ? c1 : pc1[n][j], p2 = fr >= 2 ? c2 : pc2[n][j]; pc1[n][j] = c1; pc2[n][j] = c2;
;                         const float cv = bb[n][j] + w0[n][j] * p2 + w1[n][j] * p1 + w2[n][j] * cur[j];
;                         o[n][j] = gelu_t(cv) * (acc[ai][1][m][n][j] * rn[ai][m]); } }
;                 if (r >= 2 && tk < 4096) *(u32x4*)(ACT + (size_t)(b * 4096 + tk) * 2816 + f0) = pack8(o[0], o[1]); }
.LBB0_303:
	s_or_b64 exec, exec, s[4:5]
	s_nop 0
	v_add_u32_e32 v112, s77, v199
	v_pk_mul_f32 v[110:111], v[110:111], v[186:187] op_sel_hi:[1,0]
	v_pk_mul_f32 v[108:109], v[108:109], v[186:187] op_sel_hi:[1,0]
	v_cmp_gt_i32_e64 s[4:5], 0, v112
	v_pk_mul_f32 v[114:115], v[106:107], v[186:187] op_sel_hi:[1,0]
	v_pk_mul_f32 v[104:105], v[104:105], v[186:187] op_sel_hi:[1,0]
	v_cndmask_b32_e64 v109, v109, 0, s[4:5]
	v_cndmask_b32_e64 v108, v108, 0, s[4:5]
	v_cndmask_b32_e64 v111, v111, 0, s[4:5]
	v_cndmask_b32_e64 v110, v110, 0, s[4:5]
	v_mov_b32_e32 v117, v209
	v_mov_b32_e32 v119, v209
	v_mov_b32_e32 v118, v209
	v_mov_b32_e32 v120, v209
	v_mov_b32_e32 v121, v209
	v_mov_b32_e32 v123, v209
	v_mov_b32_e32 v122, v209
	v_mov_b32_e32 v124, v209
	v_cndmask_b32_e64 v107, v105, 0, s[4:5]
	v_cndmask_b32_e64 v106, v104, 0, s[4:5]
	v_cndmask_b32_e64 v105, v115, 0, s[4:5]
	v_cndmask_b32_e64 v104, v114, 0, s[4:5]
	v_mov_b32_e32 v125, v209
	v_mov_b32_e32 v127, v209
	v_mov_b32_e32 v126, v209
	v_mov_b32_e32 v128, v209
	v_mov_b32_e32 v113, v209
	v_mov_b32_e32 v115, v209
	v_mov_b32_e32 v114, v209
	v_mov_b32_e32 v116, v209
	v_cmp_gt_i32_e64 s[4:5], s83, v112
	v_mov_b32_dpp v117, v108 row_ror:1 row_mask:0xf bank_mask:0xf
	v_mov_b32_dpp v119, v108 row_ror:2 row_mask:0xf bank_mask:0xf
	v_mov_b32_dpp v118, v109 row_ror:1 row_mask:0xf bank_mask:0xf
	v_mov_b32_dpp v120, v109 row_ror:2 row_mask:0xf bank_mask:0xf
	v_mov_b32_dpp v121, v110 row_ror:1 row_mask:0xf bank_mask:0xf
	v_mov_b32_dpp v123, v110 row_ror:2 row_mask:0xf bank_mask:0xf
	v_mov_b32_dpp v122, v111 row_ror:1 row_mask:0xf bank_mask:0xf
	v_mov_b32_dpp v124, v111 row_ror:2 row_mask:0xf bank_mask:0xf
	v_mov_b32_dpp v125, v106 row_ror:1 row_mask:0xf bank_mask:0xf
	v_mov_b32_dpp v127, v106 row_ror:2 row_mask:0xf bank_mask:0xf
	v_mov_b32_dpp v126, v107 row_ror:1 row_mask:0xf bank_mask:0xf
	v_mov_b32_dpp v128, v107 row_ror:2 row_mask:0xf bank_mask:0xf
	v_mov_b32_dpp v113, v104 row_ror:1 row_mask:0xf bank_mask:0xf
	v_mov_b32_dpp v115, v104 row_ror:2 row_mask:0xf bank_mask:0xf
	v_mov_b32_dpp v114, v105 row_ror:1 row_mask:0xf bank_mask:0xf
	v_mov_b32_dpp v116, v105 row_ror:2 row_mask:0xf bank_mask:0xf
	s_and_b64 s[6:7], s[62:63], s[4:5]
	s_and_saveexec_b64 s[4:5], s[6:7]
	s_cbranch_execz .LBB0_305
	v_cndmask_b32_e64 v145, v144, v128, s[44:45]
	v_cndmask_b32_e64 v144, v143, v127, s[44:45]
	v_pk_fma_f32 v[144:145], v[72:73], v[144:145], v[76:77]
	v_cndmask_b32_e64 v127, v126, v142, s[42:43]
	v_cndmask_b32_e64 v126, v125, v141, s[42:43]
	v_pk_fma_f32 v[126:127], v[64:65], v[126:127], v[144:145]
	v_pk_mul_f32 v[80:81], v[80:81], v[186:187] op_sel_hi:[1,0]
	v_pk_fma_f32 v[106:107], v[106:107], v[68:69], v[126:127]
	v_pk_mul_f32 v[86:87], v[86:87], v[186:187] op_sel_hi:[1,0]
	v_mul_f32_e32 v125, 0x3d122279, v106
	v_fmaak_f32 v125, v106, v125, 0x3f4c422a
	v_mul_f32_e32 v125, v106, v125
	v_mul_f32_e32 v125, 0xc038aa3b, v125
	v_exp_f32_e32 v125, v125
	v_pk_mul_f32 v[84:85], v[84:85], v[186:187] op_sel_hi:[1,0]
	v_pk_mul_f32 v[82:83], v[82:83], v[186:187] op_sel_hi:[1,0]
	v_add_f32_e32 v125, 1.0, v125
	v_rcp_f32_e32 v126, v125
	v_mul_f32_e32 v125, 0x3d122279, v107
	v_fmaak_f32 v125, v107, v125, 0x3f4c422a
	v_mul_f32_e32 v125, v107, v125
	v_mul_f32_e32 v125, 0xc038aa3b, v125
	v_exp_f32_e32 v125, v125
	s_nop 0
	v_add_f32_e32 v125, 1.0, v125
	v_rcp_f32_e32 v127, v125
	s_nop 0
	v_pk_mul_f32 v[106:107], v[106:107], v[126:127]
	s_nop 0
	v_pk_mul_f32 v[106:107], v[80:81], v[106:107]
	v_cndmask_b32_e64 v81, v140, v124, s[44:45]
	v_cndmask_b32_e64 v80, v139, v123, s[44:45]
	v_pk_fma_f32 v[80:81], v[98:99], v[80:81], v[102:103]
	v_cndmask_b32_e64 v123, v122, v138, s[42:43]
	v_cndmask_b32_e64 v122, v121, v137, s[42:43]
	v_pk_fma_f32 v[80:81], v[90:91], v[122:123], v[80:81]
	s_nop 0
	v_pk_fma_f32 v[80:81], v[110:111], v[94:95], v[80:81]
	s_nop 0
	v_mul_f32_e32 v110, 0x3d122279, v80
	v_mul_f32_e32 v111, 0x3d122279, v81
	v_fmaak_f32 v110, v80, v110, 0x3f4c422a
	v_fmaak_f32 v111, v81, v111, 0x3f4c422a
	v_mul_f32_e32 v110, v80, v110
	v_mul_f32_e32 v111, v81, v111
	v_mul_f32_e32 v110, 0xc038aa3b, v110
	v_mul_f32_e32 v111, 0xc038aa3b, v111
	v_exp_f32_e32 v110, v110
	v_exp_f32_e32 v111, v111
	v_add_f32_e32 v110, 1.0, v110
	v_add_f32_e32 v111, 1.0, v111
	v_rcp_f32_e32 v110, v110
	v_rcp_f32_e32 v111, v111
	s_nop 0
	v_pk_mul_f32 v[80:81], v[80:81], v[110:111]
	s_nop 0
	v_pk_mul_f32 v[86:87], v[86:87], v[80:81]
	v_cndmask_b32_e64 v81, v136, v120, s[44:45]
	v_cndmask_b32_e64 v80, v135, v119, s[44:45]
	v_pk_fma_f32 v[80:81], v[96:97], v[80:81], v[100:101]
	v_cndmask_b32_e64 v111, v118, v134, s[42:43]
	v_cndmask_b32_e64 v110, v117, v133, s[42:43]
	v_pk_fma_f32 v[80:81], v[88:89], v[110:111], v[80:81]
	s_nop 0
	v_pk_fma_f32 v[80:81], v[108:109], v[92:93], v[80:81]
	s_nop 0
	v_mul_f32_e32 v108, 0x3d122279, v80
	v_mul_f32_e32 v109, 0x3d122279, v81
	v_fmaak_f32 v108, v80, v108, 0x3f4c422a
	v_fmaak_f32 v109, v81, v109, 0x3f4c422a
	v_mul_f32_e32 v108, v80, v108
	v_mul_f32_e32 v109, v81, v109
	v_mul_f32_e32 v108, 0xc038aa3b, v108
	v_mul_f32_e32 v109, 0xc038aa3b, v109
	v_exp_f32_e32 v108, v108
	v_exp_f32_e32 v109, v109
	v_add_f32_e32 v108, 1.0, v108
	v_add_f32_e32 v109, 1.0, v109
	v_rcp_f32_e32 v108, v108
	v_rcp_f32_e32 v109, v109
	s_nop 0
	v_pk_mul_f32 v[80:81], v[80:81], v[108:109]
	s_nop 0
	v_pk_mul_f32 v[80:81], v[84:85], v[80:81]
	v_cndmask_b32_e64 v85, v132, v116, s[44:45]
	v_cndmask_b32_e64 v84, v131, v115, s[44:45]
	v_cndmask_b32_e64 v109, v114, v130, s[42:43]
	v_cndmask_b32_e64 v108, v113, v129, s[42:43]
	v_pk_fma_f32 v[84:85], v[74:75], v[84:85], v[78:79]
	v_cvt_pk_bf16_f32 v80, v80, v81
	v_pk_fma_f32 v[84:85], v[66:67], v[108:109], v[84:85]
	v_cvt_pk_bf16_f32 v81, v86, v87
	v_pk_fma_f32 v[84:85], v[104:105], v[70:71], v[84:85]
	v_add_u32_e32 v86, s71, v112
	v_mul_f32_e32 v104, 0x3d122279, v84
	v_mul_f32_e32 v105, 0x3d122279, v85
	v_fmaak_f32 v104, v84, v104, 0x3f4c422a
	v_fmaak_f32 v105, v85, v105, 0x3f4c422a
	v_mul_f32_e32 v104, v84, v104
	v_mul_f32_e32 v105, v85, v105
	v_mul_f32_e32 v104, 0xc038aa3b, v104
	v_mul_f32_e32 v105, 0xc038aa3b, v105
	v_exp_f32_e32 v104, v104
	v_exp_f32_e32 v105, v105
	v_add_f32_e32 v104, 1.0, v104
	v_add_f32_e32 v105, 1.0, v105
	v_rcp_f32_e32 v104, v104
	v_rcp_f32_e32 v105, v105
	s_nop 0
	v_pk_mul_f32 v[84:85], v[84:85], v[104:105]
	s_nop 0
	v_pk_mul_f32 v[84:85], v[82:83], v[84:85]
	v_cvt_pk_bf16_f32 v82, v106, v107
	v_cvt_pk_bf16_f32 v83, v84, v85
	v_mov_b64_e32 v[84:85], s[12:13]
	v_mad_i64_i32 v[84:85], s[6:7], v86, s34, v[84:85]
	v_lshl_add_u64 v[84:85], v[182:183], 1, v[84:85]
	global_store_dwordx4 v[84:85], v[80:83], off
; #define PG8_LAS __attribute__((address_space(3)))
; __device__ __forceinline__ float dpp_ror1(float v) { return __int_as_float(__builtin_amdgcn_update_dpp(0, __float_as_int(v), 0x121, 0xf, 0xf, false)); }
; __device__ __forceinline__ float dpp_ror2(float v) { return __int_as_float(__builtin_amdgcn_update_dpp(0, __float_as_int(v), 0x122, 0xf, 0xf, false)); }
;     __device__ __forceinline__ void operator()(const f32x4 (&acc)[2][2][4][2], const Unit& u, int wr, int wc, int fr, int fq) const {
;     ...
;         for (int ai = 0; ai < 2; ++ai) {
;             const int blk = ai * 2 + wr;
;             f32x4 pc1[2], pc2[2];
; #pragma unroll
;             for (int n = 0; n < 2; ++n) { f32x4 hv = {0.f, 0.f, 0.f, 0.f};
;                 if (blk > 0 && fr >= 14) hv = *(const PG8_LAS f32x4*)(halo + ((blk - 1) * 2 + (fr - 14)) * 128 + fl + 4 * n);
; #pragma unroll
;                 for (int j = 0; j < 4; ++j) { pc1[n][j] = dpp_ror1(hv[j]); pc2[n][j] = dpp_ror2(hv[j]); } }
; #pragma unroll
;             for (int m = 0; m < 4; ++m) { const int r = ai * HALF + wr * 64 + m * 16 + fr, tk = 254 * i - 2 + r;
;                 f32x4 o[2];
; #pragma unroll
;                 for (int n = 0; n < 2; ++n) { f32x4 cur = acc[ai][0][m][n] * rn[ai][m]; if (tk < 0) cur = (f32x4){0.f, 0.f, 0.f, 0.f};
.LBB0_305:
	s_or_b64 exec, exec, s[4:5]
	s_nop 0
	v_mov_b32_e32 v80, 0
	v_mov_b32_e32 v82, 0
	v_mov_b32_e32 v83, 0
	v_mov_b32_e32 v84, 0
	v_mov_b32_e32 v85, 0
	s_and_saveexec_b64 s[4:5], s[64:65]
	ds_read_b128 v[82:85], v207
	s_or_b64 exec, exec, s[4:5]
	v_mov_b32_e32 v115, 0
	v_mov_b32_e32 v120, 0
	v_mov_b32_e32 v117, 0
	v_mov_b32_e32 v122, 0
	v_mov_b32_e32 v123, 0
	v_mov_b32_e32 v125, 0
	v_mov_b32_e32 v124, 0
	v_mov_b32_e32 v126, 0
	s_waitcnt lgkmcnt(0)
	v_mov_b32_dpp v115, v82 row_ror:1 row_mask:0xf bank_mask:0xf
	v_mov_b32_dpp v120, v82 row_ror:2 row_mask:0xf bank_mask:0xf
	v_mov_b32_dpp v117, v83 row_ror:1 row_mask:0xf bank_mask:0xf
	v_mov_b32_dpp v122, v83 row_ror:2 row_mask:0xf bank_mask:0xf
	v_mov_b32_dpp v123, v84 row_ror:1 row_mask:0xf bank_mask:0xf
	v_mov_b32_dpp v125, v84 row_ror:2 row_mask:0xf bank_mask:0xf
	v_mov_b32_dpp v124, v85 row_ror:1 row_mask:0xf bank_mask:0xf
	v_mov_b32_dpp v126, v85 row_ror:2 row_mask:0xf bank_mask:0xf
	v_mov_b32_e32 v81, 0
	v_mov_b32_e32 v82, 0
	v_mov_b32_e32 v83, 0
	s_and_saveexec_b64 s[4:5], s[64:65]
	ds_read_b128 v[80:83], v207 offset:16
	s_or_b64 exec, exec, s[4:5]
	v_pk_add_f32 v[84:85], v[188:189], v[190:191]
	v_add_u32_e32 v114, s77, v200
	v_pk_fma_f32 v[84:85], v[84:85], s[78:79], v[210:211] op_sel_hi:[1,0,0]
	v_mov_b32_e32 v127, v209
	v_mul_f32_e32 v86, 0x4b800000, v85
	v_cmp_gt_f32_e64 s[6:7], s39, v85
	v_mov_b32_e32 v129, v209
	v_mov_b32_e32 v128, v209
	v_cndmask_b32_e64 v85, v85, v86, s[6:7]
	v_rsq_f32_e32 v85, v85
	v_mov_b32_e32 v130, v209
	s_waitcnt lgkmcnt(0)
	v_mov_b32_dpp v127, v80 row_ror:1 row_mask:0xf bank_mask:0xf
	v_mov_b32_dpp v129, v80 row_ror:2 row_mask:0xf bank_mask:0xf
	v_mul_f32_e32 v86, 0x45800000, v85
	v_cndmask_b32_e64 v86, v85, v86, s[6:7]
	v_pk_mul_f32 v[60:61], v[60:61], v[86:87] op_sel_hi:[1,0]
	v_cmp_gt_i32_e64 s[6:7], 0, v114
	v_pk_mul_f32 v[62:63], v[62:63], v[86:87] op_sel_hi:[1,0]
	v_mov_b32_e32 v87, v209
	v_cndmask_b32_e64 v61, v61, 0, s[6:7]
	v_mov_b32_dpp v128, v81 row_ror:1 row_mask:0xf bank_mask:0xf
	v_mov_b32_dpp v130, v81 row_ror:2 row_mask:0xf bank_mask:0xf
	v_mov_b32_dpp v87, v61 row_ror:1 row_mask:0xf bank_mask:0xf
	v_mov_b32_e32 v116, v209
	v_mov_b32_e32 v119, v209
	v_mov_b32_e32 v118, v209
	v_mov_b32_e32 v121, v209
	v_pk_mul_f32 v[80:81], v[56:57], v[86:87] op_sel_hi:[1,0]
	v_pk_mul_f32 v[56:57], v[58:59], v[86:87] op_sel_hi:[1,0]
	v_mov_b32_dpp v116, v82 row_ror:1 row_mask:0xf bank_mask:0xf
	v_mov_b32_dpp v119, v82 row_ror:2 row_mask:0xf bank_mask:0xf
	v_mov_b32_dpp v118, v83 row_ror:1 row_mask:0xf bank_mask:0xf
	v_mov_b32_dpp v121, v83 row_ror:2 row_mask:0xf bank_mask:0xf
	v_cndmask_b32_e64 v63, v63, 0, s[6:7]
	v_cndmask_b32_e64 v62, v62, 0, s[6:7]
	v_cndmask_b32_e64 v60, v60, 0, s[6:7]
	v_mov_b32_e32 v85, v209
	v_mov_b32_e32 v104, v209
	v_mov_b32_e32 v105, v209
	v_mov_b32_e32 v106, v209
	v_mov_b32_e32 v108, v209
	v_mov_b32_e32 v107, v209
	v_mov_b32_e32 v109, v209
	v_cndmask_b32_e64 v57, v57, 0, s[6:7]
	v_cndmask_b32_e64 v56, v56, 0, s[6:7]
	v_cndmask_b32_e64 v59, v81, 0, s[6:7]
	v_cndmask_b32_e64 v58, v80, 0, s[6:7]
	v_mov_b32_e32 v110, v209
	v_mov_b32_e32 v112, v209
	v_mov_b32_e32 v111, v209
	v_mov_b32_e32 v113, v209
	v_mov_b32_e32 v80, v209
	v_mov_b32_e32 v82, v209
	v_mov_b32_e32 v81, v209
	v_mov_b32_e32 v83, v209
	v_cmp_gt_i32_e64 s[6:7], s83, v114
	v_cmp_gt_f32_e64 s[4:5], s39, v84
	v_mov_b32_dpp v85, v60 row_ror:1 row_mask:0xf bank_mask:0xf
	v_mov_b32_dpp v104, v60 row_ror:2 row_mask:0xf bank_mask:0xf
	v_mov_b32_dpp v105, v61 row_ror:2 row_mask:0xf bank_mask:0xf
	v_mov_b32_dpp v106, v62 row_ror:1 row_mask:0xf bank_mask:0xf
	v_mov_b32_dpp v108, v62 row_ror:2 row_mask:0xf bank_mask:0xf
	v_mov_b32_dpp v107, v63 row_ror:1 row_mask:0xf bank_mask:0xf
	v_mov_b32_dpp v109, v63 row_ror:2 row_mask:0xf bank_mask:0xf
	v_mov_b32_dpp v110, v58 row_ror:1 row_mask:0xf bank_mask:0xf
	v_mov_b32_dpp v112, v58 row_ror:2 row_mask:0xf bank_mask:0xf
	v_mov_b32_dpp v111, v59 row_ror:1 row_mask:0xf bank_mask:0xf
	v_mov_b32_dpp v113, v59 row_ror:2 row_mask:0xf bank_mask:0xf
	v_mov_b32_dpp v80, v56 row_ror:1 row_mask:0xf bank_mask:0xf
	v_mov_b32_dpp v82, v56 row_ror:2 row_mask:0xf bank_mask:0xf
	v_mov_b32_dpp v81, v57 row_ror:1 row_mask:0xf bank_mask:0xf
	v_mov_b32_dpp v83, v57 row_ror:2 row_mask:0xf bank_mask:0xf
	s_and_b64 s[8:9], s[48:49], s[6:7]
	s_and_saveexec_b64 s[6:7], s[8:9]
	s_cbranch_execz .LBB0_311
; __device__ __forceinline__ u32x4 pack8(const f32x4& v0, const f32x4& v1) { u32x4 w; w.x = cvt_pk_bf16(v0[0], v0[1]); w.y = cvt_pk_bf16(v0[2], v0[3]); w.z = cvt_pk_bf16(v1[0], v1[1]); w.w = cvt_pk_bf16(v1[2], v1[3]); return w; }
; __device__ __forceinline__ float dpp_ror1(float v) { return __int_as_float(__builtin_amdgcn_update_dpp(0, __float_as_int(v), 0x121, 0xf, 0xf, false)); }
; __device__ __forceinline__ float dpp_ror2(float v) { return __int_as_float(__builtin_amdgcn_update_dpp(0, __float_as_int(v), 0x122, 0xf, 0xf, false)); }
;     __device__ __forceinline__ void operator()(const f32x4 (&acc)[2][2][4][2], const Unit& u, int wr, int wc, int fr, int fq) const {
;     ...
;             for (int m = 0; m < 4; ++m) { const int r = ai * HALF + wr * 64 + m * 16 + fr, tk = 254 * i - 2 + r;
;                 f32x4 o[2];
; #pragma unroll
;                 for (int n = 0; n < 2; ++n) { f32x4 cur = acc[ai][0][m][n] * rn[ai][m]; if (tk < 0) cur = (f32x4){0.f, 0.f, 0.f, 0.f};
; #pragma unroll
;                     for (int j = 0; j < 4; ++j) { const float c1 = dpp_ror1(cur[j]), c2 = dpp_ror2(cur[j]);
;                         const float p1 = fr >= 1 ? c1 : pc1[n][j], p2 = fr >= 2 ? c2 : pc2[n][j]; pc1[n][j] = c1; pc2[n][j] = c2;
;                         const float cv = bb[n][j] + w0[n][j] * p2 + w1[n][j] * p1 + w2[n][j] * cur[j];
;                         o[n][j] = gelu_t(cv) * (acc[ai][1][m][n][j] * rn[ai][m]); } }
;                 if (r >= 2 && tk < 4096) *(u32x4*)(ACT + (size_t)(b * 4096 + tk) * 2816 + f0) = pack8(o[0], o[1]); }
	v_cndmask_b32_e64 v131, v130, v113, s[44:45]
	v_cndmask_b32_e64 v130, v129, v112, s[44:45]
	v_pk_fma_f32 v[130:131], v[72:73], v[130:131], v[76:77]
	v_cndmask_b32_e64 v129, v111, v128, s[42:43]
	v_cndmask_b32_e64 v128, v110, v127, s[42:43]
	v_pk_fma_f32 v[128:129], v[64:65], v[128:129], v[130:131]
	v_pk_mul_f32 v[48:49], v[48:49], v[86:87] op_sel_hi:[1,0]
	v_pk_fma_f32 v[58:59], v[58:59], v[68:69], v[128:129]
	v_pk_mul_f32 v[54:55], v[54:55], v[86:87] op_sel_hi:[1,0]
	v_mul_f32_e32 v127, 0x3d122279, v58
	v_fmaak_f32 v127, v58, v127, 0x3f4c422a
	v_mul_f32_e32 v127, v58, v127
	v_mul_f32_e32 v127, 0xc038aa3b, v127
	v_exp_f32_e32 v127, v127
	v_pk_mul_f32 v[52:53], v[52:53], v[86:87] op_sel_hi:[1,0]
	v_pk_mul_f32 v[50:51], v[50:51], v[86:87] op_sel_hi:[1,0]
	v_add_f32_e32 v127, 1.0, v127
	v_rcp_f32_e32 v128, v127
	v_mul_f32_e32 v127, 0x3d122279, v59
	v_fmaak_f32 v127, v59, v127, 0x3f4c422a
	v_mul_f32_e32 v127, v59, v127
	v_mul_f32_e32 v127, 0xc038aa3b, v127
	v_exp_f32_e32 v127, v127
	s_nop 0
	v_add_f32_e32 v127, 1.0, v127
	v_rcp_f32_e32 v129, v127
	s_nop 0
	v_pk_mul_f32 v[58:59], v[58:59], v[128:129]
	s_nop 0
	v_pk_mul_f32 v[58:59], v[48:49], v[58:59]
	v_cndmask_b32_e64 v49, v126, v109, s[44:45]
	v_cndmask_b32_e64 v48, v125, v108, s[44:45]
	v_pk_fma_f32 v[48:49], v[98:99], v[48:49], v[102:103]
	v_cndmask_b32_e64 v125, v107, v124, s[42:43]
	v_cndmask_b32_e64 v124, v106, v123, s[42:43]
	v_pk_fma_f32 v[48:49], v[90:91], v[124:125], v[48:49]
	s_nop 0
	v_pk_fma_f32 v[48:49], v[62:63], v[94:95], v[48:49]
	s_nop 0
	v_mul_f32_e32 v62, 0x3d122279, v48
	v_mul_f32_e32 v63, 0x3d122279, v49
	v_fmaak_f32 v62, v48, v62, 0x3f4c422a
	v_fmaak_f32 v63, v49, v63, 0x3f4c422a
	v_mul_f32_e32 v62, v48, v62
	v_mul_f32_e32 v63, v49, v63
	v_mul_f32_e32 v62, 0xc038aa3b, v62
	v_mul_f32_e32 v63, 0xc038aa3b, v63
	v_exp_f32_e32 v62, v62
	v_exp_f32_e32 v63, v63
	v_add_f32_e32 v62, 1.0, v62
	v_add_f32_e32 v63, 1.0, v63
	v_rcp_f32_e32 v62, v62
	v_rcp_f32_e32 v63, v63
	s_nop 0
	v_pk_mul_f32 v[48:49], v[48:49], v[62:63]
	s_nop 0
	v_pk_mul_f32 v[54:55], v[54:55], v[48:49]
	v_cndmask_b32_e64 v49, v122, v105, s[44:45]
	v_cndmask_b32_e64 v48, v120, v104, s[44:45]
	v_pk_fma_f32 v[48:49], v[96:97], v[48:49], v[100:101]
	v_cndmask_b32_e64 v63, v87, v117, s[42:43]
	v_cndmask_b32_e64 v62, v85, v115, s[42:43]
	v_pk_fma_f32 v[48:49], v[88:89], v[62:63], v[48:49]
	s_nop 0
	v_pk_fma_f32 v[48:49], v[60:61], v[92:93], v[48:49]
	s_nop 0
	v_mul_f32_e32 v60, 0x3d122279, v48
	v_mul_f32_e32 v61, 0x3d122279, v49
	v_fmaak_f32 v60, v48, v60, 0x3f4c422a
	v_fmaak_f32 v61, v49, v61, 0x3f4c422a
	v_mul_f32_e32 v60, v48, v60
	v_mul_f32_e32 v61, v49, v61
	v_mul_f32_e32 v60, 0xc038aa3b, v60
	v_mul_f32_e32 v61, 0xc038aa3b, v61
	v_exp_f32_e32 v60, v60
	v_exp_f32_e32 v61, v61
	v_add_f32_e32 v60, 1.0, v60
	v_add_f32_e32 v61, 1.0, v61
	v_rcp_f32_e32 v60, v60
	v_rcp_f32_e32 v61, v61
	s_nop 0
	v_pk_mul_f32 v[48:49], v[48:49], v[60:61]
	s_nop 0
	v_pk_mul_f32 v[48:49], v[52:53], v[48:49]
	v_cndmask_b32_e64 v53, v121, v83, s[44:45]
	v_cndmask_b32_e64 v52, v119, v82, s[44:45]
	v_cndmask_b32_e64 v61, v81, v118, s[42:43]
	v_cndmask_b32_e64 v60, v80, v116, s[42:43]
	v_pk_fma_f32 v[52:53], v[74:75], v[52:53], v[78:79]
	v_cvt_pk_bf16_f32 v48, v48, v49
	v_pk_fma_f32 v[52:53], v[66:67], v[60:61], v[52:53]
	v_cvt_pk_bf16_f32 v49, v54, v55
	v_pk_fma_f32 v[52:53], v[56:57], v[70:71], v[52:53]
	v_add_u32_e32 v54, s71, v114
	v_mul_f32_e32 v56, 0x3d122279, v52
	v_mul_f32_e32 v57, 0x3d122279, v53
	v_fmaak_f32 v56, v52, v56, 0x3f4c422a
	v_fmaak_f32 v57, v53, v57, 0x3f4c422a
	v_mul_f32_e32 v56, v52, v56
	v_mul_f32_e32 v57, v53, v57
	v_mul_f32_e32 v56, 0xc038aa3b, v56
	v_mul_f32_e32 v57, 0xc038aa3b, v57
	v_exp_f32_e32 v56, v56
	v_exp_f32_e32 v57, v57
	v_add_f32_e32 v56, 1.0, v56
	v_add_f32_e32 v57, 1.0, v57
	v_rcp_f32_e32 v56, v56
	v_rcp_f32_e32 v57, v57
	s_nop 0
	v_pk_mul_f32 v[52:53], v[52:53], v[56:57]
	s_nop 0
	v_pk_mul_f32 v[52:53], v[50:51], v[52:53]
	v_cvt_pk_bf16_f32 v50, v58, v59
	v_cvt_pk_bf16_f32 v51, v52, v53
	v_mov_b64_e32 v[52:53], s[12:13]
	v_mad_i64_i32 v[52:53], s[8:9], v54, s34, v[52:53]
	v_lshl_add_u64 v[52:53], v[182:183], 1, v[52:53]
	global_store_dwordx4 v[52:53], v[48:51], off
.LBB0_311:
	s_or_b64 exec, exec, s[6:7]
	s_nop 0
	v_mul_f32_e32 v48, 0x4b800000, v84
	v_cndmask_b32_e64 v48, v84, v48, s[4:5]
	v_rsq_f32_e32 v48, v48
	v_add_u32_e32 v86, s77, v201
	v_mov_b32_e32 v53, v209
	v_mov_b32_e32 v55, v209
	v_mul_f32_e32 v49, 0x45800000, v48
	v_cndmask_b32_e64 v48, v48, v49, s[4:5]
	v_pk_mul_f32 v[44:45], v[44:45], v[48:49] op_sel_hi:[1,0]
	v_pk_mul_f32 v[46:47], v[46:47], v[48:49] op_sel_hi:[1,0]
	v_cmp_gt_i32_e64 s[4:5], 0, v86
	v_pk_mul_f32 v[50:51], v[40:41], v[48:49] op_sel_hi:[1,0]
	v_pk_mul_f32 v[40:41], v[42:43], v[48:49] op_sel_hi:[1,0]
	v_cndmask_b32_e64 v47, v47, 0, s[4:5]
	v_cndmask_b32_e64 v46, v46, 0, s[4:5]
	v_cndmask_b32_e64 v45, v45, 0, s[4:5]
	v_cndmask_b32_e64 v44, v44, 0, s[4:5]
	v_mov_b32_e32 v54, v209
	v_mov_b32_e32 v56, v209
	v_mov_b32_e32 v57, v209
	v_mov_b32_e32 v59, v209
	v_mov_b32_e32 v58, v209
	v_mov_b32_e32 v60, v209
	v_cndmask_b32_e64 v41, v41, 0, s[4:5]
	v_cndmask_b32_e64 v40, v40, 0, s[4:5]
	v_cndmask_b32_e64 v43, v51, 0, s[4:5]
	v_cndmask_b32_e64 v42, v50, 0, s[4:5]
	v_mov_b32_e32 v61, v209
	v_mov_b32_e32 v63, v209
	v_mov_b32_e32 v62, v209
	v_mov_b32_e32 v84, v209
	v_mov_b32_e32 v49, v209
	v_mov_b32_e32 v51, v209
	v_mov_b32_e32 v50, v209
	v_mov_b32_e32 v52, v209
	v_cmp_gt_i32_e64 s[4:5], s83, v86
	v_mov_b32_dpp v53, v44 row_ror:1 row_mask:0xf bank_mask:0xf
	v_mov_b32_dpp v55, v44 row_ror:2 row_mask:0xf bank_mask:0xf
	v_mov_b32_dpp v54, v45 row_ror:1 row_mask:0xf bank_mask:0xf
	v_mov_b32_dpp v56, v45 row_ror:2 row_mask:0xf bank_mask:0xf
	v_mov_b32_dpp v57, v46 row_ror:1 row_mask:0xf bank_mask:0xf
	v_mov_b32_dpp v59, v46 row_ror:2 row_mask:0xf bank_mask:0xf
	v_mov_b32_dpp v58, v47 row_ror:1 row_mask:0xf bank_mask:0xf
	v_mov_b32_dpp v60, v47 row_ror:2 row_mask:0xf bank_mask:0xf
	v_mov_b32_dpp v61, v42 row_ror:1 row_mask:0xf bank_mask:0xf
	v_mov_b32_dpp v63, v42 row_ror:2 row_mask:0xf bank_mask:0xf
	v_mov_b32_dpp v62, v43 row_ror:1 row_mask:0xf bank_mask:0xf
	v_mov_b32_dpp v84, v43 row_ror:2 row_mask:0xf bank_mask:0xf
	v_mov_b32_dpp v49, v40 row_ror:1 row_mask:0xf bank_mask:0xf
	v_mov_b32_dpp v51, v40 row_ror:2 row_mask:0xf bank_mask:0xf
	v_mov_b32_dpp v50, v41 row_ror:1 row_mask:0xf bank_mask:0xf
	v_mov_b32_dpp v52, v41 row_ror:2 row_mask:0xf bank_mask:0xf
	s_and_b64 s[6:7], s[50:51], s[4:5]
	s_and_saveexec_b64 s[4:5], s[6:7]
	s_cbranch_execz .LBB0_313
; __device__ __forceinline__ u32x4 pack8(const f32x4& v0, const f32x4& v1) { u32x4 w; w.x = cvt_pk_bf16(v0[0], v0[1]); w.y = cvt_pk_bf16(v0[2], v0[3]); w.z = cvt_pk_bf16(v1[0], v1[1]); w.w = cvt_pk_bf16(v1[2], v1[3]); return w; }
; __device__ __forceinline__ float dpp_ror1(float v) { return __int_as_float(__builtin_amdgcn_update_dpp(0, __float_as_int(v), 0x121, 0xf, 0xf, false)); }
; __device__ __forceinline__ float dpp_ror2(float v) { return __int_as_float(__builtin_amdgcn_update_dpp(0, __float_as_int(v), 0x122, 0xf, 0xf, false)); }
;     __device__ __forceinline__ void operator()(const f32x4 (&acc)[2][2][4][2], const Unit& u, int wr, int wc, int fr, int fq) const {
;     ...
;             for (int m = 0; m < 4; ++m) { const int r = ai * HALF + wr * 64 + m * 16 + fr, tk = 254 * i - 2 + r;
;                 f32x4 o[2];
; #pragma unroll
;                 for (int n = 0; n < 2; ++n) { f32x4 cur = acc[ai][0][m][n] * rn[ai][m]; if (tk < 0) cur = (f32x4){0.f, 0.f, 0.f, 0.f};
; #pragma unroll
;                     for (int j = 0; j < 4; ++j) { const float c1 = dpp_ror1(cur[j]), c2 = dpp_ror2(cur[j]);
;                         const float p1 = fr >= 1 ? c1 : pc1[n][j], p2 = fr >= 2 ? c2 : pc2[n][j]; pc1[n][j] = c1; pc2[n][j] = c2;
;                         const float cv = bb[n][j] + w0[n][j] * p2 + w1[n][j] * p1 + w2[n][j] * cur[j];
;                         o[n][j] = gelu_t(cv) * (acc[ai][1][m][n][j] * rn[ai][m]); } }
;                 if (r >= 2 && tk < 4096) *(u32x4*)(ACT + (size_t)(b * 4096 + tk) * 2816 + f0) = pack8(o[0], o[1]); }
	v_cndmask_b32_e64 v113, v113, v84, s[44:45]
	v_cndmask_b32_e64 v112, v112, v63, s[44:45]
	v_pk_fma_f32 v[112:113], v[72:73], v[112:113], v[76:77]
	v_cndmask_b32_e64 v111, v62, v111, s[42:43]
	v_cndmask_b32_e64 v110, v61, v110, s[42:43]
	v_pk_fma_f32 v[110:111], v[64:65], v[110:111], v[112:113]
	v_pk_mul_f32 v[32:33], v[32:33], v[48:49] op_sel_hi:[1,0]
	v_pk_fma_f32 v[42:43], v[42:43], v[68:69], v[110:111]
	v_cndmask_b32_e64 v107, v58, v107, s[42:43]
	v_mul_f32_e32 v110, 0x3d122279, v42
	v_mul_f32_e32 v111, 0x3d122279, v43
	v_fmaak_f32 v110, v42, v110, 0x3f4c422a
	v_fmaak_f32 v111, v43, v111, 0x3f4c422a
	v_mul_f32_e32 v110, v42, v110
	v_mul_f32_e32 v111, v43, v111
	v_mul_f32_e32 v110, 0xc038aa3b, v110
	v_mul_f32_e32 v111, 0xc038aa3b, v111
	v_exp_f32_e32 v110, v110
	v_exp_f32_e32 v111, v111
	v_cndmask_b32_e64 v106, v57, v106, s[42:43]
	v_pk_mul_f32 v[38:39], v[38:39], v[48:49] op_sel_hi:[1,0]
	v_add_f32_e32 v110, 1.0, v110
	v_add_f32_e32 v111, 1.0, v111
	v_rcp_f32_e32 v110, v110
	v_rcp_f32_e32 v111, v111
	v_pk_mul_f32 v[36:37], v[36:37], v[48:49] op_sel_hi:[1,0]
	v_pk_mul_f32 v[34:35], v[34:35], v[48:49] op_sel_hi:[1,0]
	v_pk_mul_f32 v[42:43], v[42:43], v[110:111]
	s_nop 0
	v_pk_mul_f32 v[42:43], v[32:33], v[42:43]
	v_cndmask_b32_e64 v33, v109, v60, s[44:45]
	v_cndmask_b32_e64 v32, v108, v59, s[44:45]
	v_pk_fma_f32 v[32:33], v[98:99], v[32:33], v[102:103]
	s_nop 0
	v_pk_fma_f32 v[32:33], v[90:91], v[106:107], v[32:33]
	s_nop 0
	v_pk_fma_f32 v[32:33], v[46:47], v[94:95], v[32:33]
	s_nop 0
	v_mul_f32_e32 v46, 0x3d122279, v32
	v_mul_f32_e32 v47, 0x3d122279, v33
	v_fmaak_f32 v46, v32, v46, 0x3f4c422a
	v_fmaak_f32 v47, v33, v47, 0x3f4c422a
	v_mul_f32_e32 v46, v32, v46
	v_mul_f32_e32 v47, v33, v47
	v_mul_f32_e32 v46, 0xc038aa3b, v46
	v_mul_f32_e32 v47, 0xc038aa3b, v47
	v_exp_f32_e32 v46, v46
	v_exp_f32_e32 v47, v47
	v_add_f32_e32 v46, 1.0, v46
	v_add_f32_e32 v47, 1.0, v47
	v_rcp_f32_e32 v46, v46
	v_rcp_f32_e32 v47, v47
	s_nop 0
	v_pk_mul_f32 v[32:33], v[32:33], v[46:47]
	s_nop 0
	v_pk_mul_f32 v[38:39], v[38:39], v[32:33]
	v_cndmask_b32_e64 v33, v105, v56, s[44:45]
	v_cndmask_b32_e64 v32, v104, v55, s[44:45]
	v_pk_fma_f32 v[32:33], v[96:97], v[32:33], v[100:101]
	v_cndmask_b32_e64 v47, v54, v87, s[42:43]
	v_cndmask_b32_e64 v46, v53, v85, s[42:43]
	v_pk_fma_f32 v[32:33], v[88:89], v[46:47], v[32:33]
	s_nop 0
	v_pk_fma_f32 v[32:33], v[44:45], v[92:93], v[32:33]
	s_nop 0
	v_mul_f32_e32 v44, 0x3d122279, v32
	v_mul_f32_e32 v45, 0x3d122279, v33
	v_fmaak_f32 v44, v32, v44, 0x3f4c422a
	v_fmaak_f32 v45, v33, v45, 0x3f4c422a
	v_mul_f32_e32 v44, v32, v44
	v_mul_f32_e32 v45, v33, v45
	v_mul_f32_e32 v44, 0xc038aa3b, v44
	v_mul_f32_e32 v45, 0xc038aa3b, v45
	v_exp_f32_e32 v44, v44
	v_exp_f32_e32 v45, v45
	v_add_f32_e32 v44, 1.0, v44
	v_add_f32_e32 v45, 1.0, v45
	v_rcp_f32_e32 v44, v44
	v_rcp_f32_e32 v45, v45
	s_nop 0
	v_pk_mul_f32 v[32:33], v[32:33], v[44:45]
	s_nop 0
	v_pk_mul_f32 v[32:33], v[36:37], v[32:33]
	v_cndmask_b32_e64 v37, v83, v52, s[44:45]
	v_cndmask_b32_e64 v36, v82, v51, s[44:45]
	v_cndmask_b32_e64 v45, v50, v81, s[42:43]
	v_cndmask_b32_e64 v44, v49, v80, s[42:43]
	v_pk_fma_f32 v[36:37], v[74:75], v[36:37], v[78:79]
	v_cvt_pk_bf16_f32 v32, v32, v33
	v_pk_fma_f32 v[36:37], v[66:67], v[44:45], v[36:37]
	v_cvt_pk_bf16_f32 v33, v38, v39
	v_pk_fma_f32 v[36:37], v[40:41], v[70:71], v[36:37]
	v_add_u32_e32 v38, s71, v86
	v_mul_f32_e32 v40, 0x3d122279, v36
	v_mul_f32_e32 v41, 0x3d122279, v37
	v_fmaak_f32 v40, v36, v40, 0x3f4c422a
	v_fmaak_f32 v41, v37, v41, 0x3f4c422a
	v_mul_f32_e32 v40, v36, v40
	v_mul_f32_e32 v41, v37, v41
	v_mul_f32_e32 v40, 0xc038aa3b, v40
	v_mul_f32_e32 v41, 0xc038aa3b, v41
	v_exp_f32_e32 v40, v40
	v_exp_f32_e32 v41, v41
	v_add_f32_e32 v40, 1.0, v40
	v_add_f32_e32 v41, 1.0, v41
	v_rcp_f32_e32 v40, v40
	v_rcp_f32_e32 v41, v41
	s_nop 0
	v_pk_mul_f32 v[36:37], v[36:37], v[40:41]
	s_nop 0
	v_pk_mul_f32 v[36:37], v[34:35], v[36:37]
	v_cvt_pk_bf16_f32 v34, v42, v43
	v_cvt_pk_bf16_f32 v35, v36, v37
	v_mov_b64_e32 v[36:37], s[12:13]
	v_mad_i64_i32 v[36:37], s[6:7], v38, s34, v[36:37]
	v_lshl_add_u64 v[36:37], v[182:183], 1, v[36:37]
	global_store_dwordx4 v[36:37], v[32:35], off
.LBB0_313:
	s_or_b64 exec, exec, s[4:5]
	s_nop 0
	v_mul_f32_e32 v32, 0x4b800000, v185
	v_cndmask_b32_e32 v32, v185, v32, vcc
	v_rsq_f32_e32 v32, v32
	v_add_u32_e32 v80, s77, v202
	v_mov_b32_e32 v45, v209
	v_mov_b32_e32 v47, v209
	v_mul_f32_e32 v33, 0x45800000, v32
	v_cndmask_b32_e32 v32, v32, v33, vcc
	v_pk_mul_f32 v[28:29], v[28:29], v[32:33] op_sel_hi:[1,0]
	v_pk_mul_f32 v[30:31], v[30:31], v[32:33] op_sel_hi:[1,0]
	v_cmp_gt_i32_e32 vcc, 0, v80
	v_pk_mul_f32 v[34:35], v[24:25], v[32:33] op_sel_hi:[1,0]
	v_pk_mul_f32 v[24:25], v[26:27], v[32:33] op_sel_hi:[1,0]
	v_cndmask_b32_e64 v31, v31, 0, vcc
	v_cndmask_b32_e64 v30, v30, 0, vcc
	v_cndmask_b32_e64 v29, v29, 0, vcc
	v_cndmask_b32_e64 v28, v28, 0, vcc
	v_mov_b32_e32 v46, v209
	v_mov_b32_e32 v48, v209
	v_mov_b32_e32 v41, v209
	v_mov_b32_e32 v43, v209
	v_mov_b32_e32 v42, v209
	v_mov_b32_e32 v44, v209
	v_cndmask_b32_e64 v25, v25, 0, vcc
	v_cndmask_b32_e64 v24, v24, 0, vcc
	v_cndmask_b32_e64 v27, v35, 0, vcc
	v_cndmask_b32_e64 v26, v34, 0, vcc
	v_mov_b32_e32 v37, v209
	v_mov_b32_e32 v39, v209
	v_mov_b32_e32 v38, v209
	v_mov_b32_e32 v40, v209
	v_mov_b32_e32 v33, v209
	v_mov_b32_e32 v35, v209
	v_mov_b32_e32 v34, v209
	v_mov_b32_e32 v36, v209
	v_cmp_gt_i32_e32 vcc, s83, v80
	v_mov_b32_dpp v45, v28 row_ror:1 row_mask:0xf bank_mask:0xf
	v_mov_b32_dpp v47, v28 row_ror:2 row_mask:0xf bank_mask:0xf
	v_mov_b32_dpp v46, v29 row_ror:1 row_mask:0xf bank_mask:0xf
	v_mov_b32_dpp v48, v29 row_ror:2 row_mask:0xf bank_mask:0xf
	v_mov_b32_dpp v41, v30 row_ror:1 row_mask:0xf bank_mask:0xf
	v_mov_b32_dpp v43, v30 row_ror:2 row_mask:0xf bank_mask:0xf
	v_mov_b32_dpp v42, v31 row_ror:1 row_mask:0xf bank_mask:0xf
	v_mov_b32_dpp v44, v31 row_ror:2 row_mask:0xf bank_mask:0xf
	v_mov_b32_dpp v37, v26 row_ror:1 row_mask:0xf bank_mask:0xf
	v_mov_b32_dpp v39, v26 row_ror:2 row_mask:0xf bank_mask:0xf
	v_mov_b32_dpp v38, v27 row_ror:1 row_mask:0xf bank_mask:0xf
	v_mov_b32_dpp v40, v27 row_ror:2 row_mask:0xf bank_mask:0xf
	v_mov_b32_dpp v33, v24 row_ror:1 row_mask:0xf bank_mask:0xf
	v_mov_b32_dpp v35, v24 row_ror:2 row_mask:0xf bank_mask:0xf
	v_mov_b32_dpp v34, v25 row_ror:1 row_mask:0xf bank_mask:0xf
	v_mov_b32_dpp v36, v25 row_ror:2 row_mask:0xf bank_mask:0xf
	s_and_b64 s[6:7], s[52:53], vcc
	s_and_saveexec_b64 s[4:5], s[6:7]
	s_cbranch_execz .LBB0_315
; __device__ __forceinline__ u32x4 pack8(const f32x4& v0, const f32x4& v1) { u32x4 w; w.x = cvt_pk_bf16(v0[0], v0[1]); w.y = cvt_pk_bf16(v0[2], v0[3]); w.z = cvt_pk_bf16(v1[0], v1[1]); w.w = cvt_pk_bf16(v1[2], v1[3]); return w; }
; __device__ __forceinline__ float dpp_ror1(float v) { return __int_as_float(__builtin_amdgcn_update_dpp(0, __float_as_int(v), 0x121, 0xf, 0xf, false)); }
; __device__ __forceinline__ float dpp_ror2(float v) { return __int_as_float(__builtin_amdgcn_update_dpp(0, __float_as_int(v), 0x122, 0xf, 0xf, false)); }
;     __device__ __forceinline__ void operator()(const f32x4 (&acc)[2][2][4][2], const Unit& u, int wr, int wc, int fr, int fq) const {
;     ...
;                     for (int j = 0; j < 4; ++j) { const float c1 = dpp_ror1(cur[j]), c2 = dpp_ror2(cur[j]);
;                         const float p1 = fr >= 1 ? c1 : pc1[n][j], p2 = fr >= 2 ? c2 : pc2[n][j]; pc1[n][j] = c1; pc2[n][j] = c2;
;                         const float cv = bb[n][j] + w0[n][j] * p2 + w1[n][j] * p1 + w2[n][j] * cur[j];
;                         o[n][j] = gelu_t(cv) * (acc[ai][1][m][n][j] * rn[ai][m]); } }
;                 if (r >= 2 && tk < 4096) *(u32x4*)(ACT + (size_t)(b * 4096 + tk) * 2816 + f0) = pack8(o[0], o[1]); }
	v_cndmask_b32_e64 v83, v84, v40, s[44:45]
	v_cndmask_b32_e64 v82, v63, v39, s[44:45]
	v_pk_fma_f32 v[82:83], v[72:73], v[82:83], v[76:77]
	v_cndmask_b32_e64 v63, v38, v62, s[42:43]
	v_cndmask_b32_e64 v62, v37, v61, s[42:43]
	v_pk_fma_f32 v[62:63], v[64:65], v[62:63], v[82:83]
	v_pk_mul_f32 v[16:17], v[16:17], v[32:33] op_sel_hi:[1,0]
	v_pk_fma_f32 v[26:27], v[26:27], v[68:69], v[62:63]
	v_pk_mul_f32 v[22:23], v[22:23], v[32:33] op_sel_hi:[1,0]
	v_mul_f32_e32 v61, 0x3d122279, v26
	v_fmaak_f32 v61, v26, v61, 0x3f4c422a
	v_mul_f32_e32 v61, v26, v61
	v_mul_f32_e32 v61, 0xc038aa3b, v61
	v_exp_f32_e32 v61, v61
	v_pk_mul_f32 v[20:21], v[20:21], v[32:33] op_sel_hi:[1,0]
	v_pk_mul_f32 v[18:19], v[18:19], v[32:33] op_sel_hi:[1,0]
	v_add_f32_e32 v61, 1.0, v61
	v_rcp_f32_e32 v62, v61
	v_mul_f32_e32 v61, 0x3d122279, v27
	v_fmaak_f32 v61, v27, v61, 0x3f4c422a
	v_mul_f32_e32 v61, v27, v61
	v_mul_f32_e32 v61, 0xc038aa3b, v61
	v_exp_f32_e32 v61, v61
	s_nop 0
	v_add_f32_e32 v61, 1.0, v61
	v_rcp_f32_e32 v63, v61
	s_nop 0
	v_pk_mul_f32 v[26:27], v[26:27], v[62:63]
	s_nop 0
	v_pk_mul_f32 v[26:27], v[16:17], v[26:27]
	v_cndmask_b32_e64 v17, v60, v44, s[44:45]
	v_cndmask_b32_e64 v16, v59, v43, s[44:45]
	v_pk_fma_f32 v[16:17], v[98:99], v[16:17], v[102:103]
	v_cndmask_b32_e64 v59, v42, v58, s[42:43]
	v_cndmask_b32_e64 v58, v41, v57, s[42:43]
	v_pk_fma_f32 v[16:17], v[90:91], v[58:59], v[16:17]
	s_nop 0
	v_pk_fma_f32 v[16:17], v[30:31], v[94:95], v[16:17]
	s_nop 0
	v_mul_f32_e32 v30, 0x3d122279, v16
	v_mul_f32_e32 v31, 0x3d122279, v17
	v_fmaak_f32 v30, v16, v30, 0x3f4c422a
	v_fmaak_f32 v31, v17, v31, 0x3f4c422a
	v_mul_f32_e32 v30, v16, v30
	v_mul_f32_e32 v31, v17, v31
	v_mul_f32_e32 v30, 0xc038aa3b, v30
	v_mul_f32_e32 v31, 0xc038aa3b, v31
	v_exp_f32_e32 v30, v30
	v_exp_f32_e32 v31, v31
	v_add_f32_e32 v30, 1.0, v30
	v_add_f32_e32 v31, 1.0, v31
	v_rcp_f32_e32 v30, v30
	v_rcp_f32_e32 v31, v31
	s_nop 0
	v_pk_mul_f32 v[16:17], v[16:17], v[30:31]
	s_nop 0
	v_pk_mul_f32 v[22:23], v[22:23], v[16:17]
	v_cndmask_b32_e64 v17, v56, v48, s[44:45]
	v_cndmask_b32_e64 v16, v55, v47, s[44:45]
	v_pk_fma_f32 v[16:17], v[96:97], v[16:17], v[100:101]
	v_cndmask_b32_e64 v31, v46, v54, s[42:43]
	v_cndmask_b32_e64 v30, v45, v53, s[42:43]
	v_pk_fma_f32 v[16:17], v[88:89], v[30:31], v[16:17]
	s_nop 0
	v_pk_fma_f32 v[16:17], v[28:29], v[92:93], v[16:17]
	s_nop 0
	v_mul_f32_e32 v28, 0x3d122279, v16
	v_mul_f32_e32 v29, 0x3d122279, v17
	v_fmaak_f32 v28, v16, v28, 0x3f4c422a
	v_fmaak_f32 v29, v17, v29, 0x3f4c422a
	v_mul_f32_e32 v28, v16, v28
	v_mul_f32_e32 v29, v17, v29
	v_mul_f32_e32 v28, 0xc038aa3b, v28
	v_mul_f32_e32 v29, 0xc038aa3b, v29
	v_exp_f32_e32 v28, v28
	v_exp_f32_e32 v29, v29
	v_add_f32_e32 v28, 1.0, v28
	v_add_f32_e32 v29, 1.0, v29
	v_rcp_f32_e32 v28, v28
	v_rcp_f32_e32 v29, v29
	s_nop 0
	v_pk_mul_f32 v[16:17], v[16:17], v[28:29]
	s_nop 0
	v_pk_mul_f32 v[16:17], v[20:21], v[16:17]
	v_cndmask_b32_e64 v21, v52, v36, s[44:45]
	v_cndmask_b32_e64 v20, v51, v35, s[44:45]
	v_cndmask_b32_e64 v29, v34, v50, s[42:43]
	v_cndmask_b32_e64 v28, v33, v49, s[42:43]
	v_pk_fma_f32 v[20:21], v[74:75], v[20:21], v[78:79]
	v_cvt_pk_bf16_f32 v16, v16, v17
	v_pk_fma_f32 v[20:21], v[66:67], v[28:29], v[20:21]
	v_cvt_pk_bf16_f32 v17, v22, v23
	v_pk_fma_f32 v[20:21], v[24:25], v[70:71], v[20:21]
	v_add_u32_e32 v22, s71, v80
	v_mul_f32_e32 v24, 0x3d122279, v20
	v_mul_f32_e32 v25, 0x3d122279, v21
	v_fmaak_f32 v24, v20, v24, 0x3f4c422a
	v_fmaak_f32 v25, v21, v25, 0x3f4c422a
	v_mul_f32_e32 v24, v20, v24
	v_mul_f32_e32 v25, v21, v25
	v_mul_f32_e32 v24, 0xc038aa3b, v24
	v_mul_f32_e32 v25, 0xc038aa3b, v25
	v_exp_f32_e32 v24, v24
	v_exp_f32_e32 v25, v25
	v_add_f32_e32 v24, 1.0, v24
	v_add_f32_e32 v25, 1.0, v25
	v_rcp_f32_e32 v24, v24
	v_rcp_f32_e32 v25, v25
	s_nop 0
	v_pk_mul_f32 v[20:21], v[20:21], v[24:25]
	s_nop 0
	v_pk_mul_f32 v[20:21], v[18:19], v[20:21]
	v_cvt_pk_bf16_f32 v18, v26, v27
	v_cvt_pk_bf16_f32 v19, v20, v21
	v_mov_b64_e32 v[20:21], s[12:13]
	v_mad_i64_i32 v[20:21], s[6:7], v22, s34, v[20:21]
	v_lshl_add_u64 v[20:21], v[182:183], 1, v[20:21]
	global_store_dwordx4 v[20:21], v[16:19], off
; __device__ __forceinline__ u32x4 pack8(const f32x4& v0, const f32x4& v1) { u32x4 w; w.x = cvt_pk_bf16(v0[0], v0[1]); w.y = cvt_pk_bf16(v0[2], v0[3]); w.z = cvt_pk_bf16(v1[0], v1[1]); w.w = cvt_pk_bf16(v1[2], v1[3]); return w; }
; __device__ __forceinline__ float dpp_ror1(float v) { return __int_as_float(__builtin_amdgcn_update_dpp(0, __float_as_int(v), 0x121, 0xf, 0xf, false)); }
; __device__ __forceinline__ float dpp_ror2(float v) { return __int_as_float(__builtin_amdgcn_update_dpp(0, __float_as_int(v), 0x122, 0xf, 0xf, false)); }
;     __device__ __forceinline__ void operator()(const f32x4 (&acc)[2][2][4][2], const Unit& u, int wr, int wc, int fr, int fq) const {
;     ...
;             for (int m = 0; m < 4; ++m) { const int r = ai * HALF + wr * 64 + m * 16 + fr, tk = 254 * i - 2 + r;
;                 f32x4 o[2];
; #pragma unroll
;                 for (int n = 0; n < 2; ++n) { f32x4 cur = acc[ai][0][m][n] * rn[ai][m]; if (tk < 0) cur = (f32x4){0.f, 0.f, 0.f, 0.f};
; #pragma unroll
;                     for (int j = 0; j < 4; ++j) { const float c1 = dpp_ror1(cur[j]), c2 = dpp_ror2(cur[j]);
;                         const float p1 = fr >= 1 ? c1 : pc1[n][j], p2 = fr >= 2 ? c2 : pc2[n][j]; pc1[n][j] = c1; pc2[n][j] = c2;
;                         const float cv = bb[n][j] + w0[n][j] * p2 + w1[n][j] * p1 + w2[n][j] * cur[j];
;                         o[n][j] = gelu_t(cv) * (acc[ai][1][m][n][j] * rn[ai][m]); } }
;                 if (r >= 2 && tk < 4096) *(u32x4*)(ACT + (size_t)(b * 4096 + tk) * 2816 + f0) = pack8(o[0], o[1]); }
.LBB0_315:
	s_or_b64 exec, exec, s[4:5]
	s_nop 0
	v_add_u32_e32 v16, s77, v203
	v_pk_mul_f32 v[18:19], v[14:15], v[184:185] op_sel_hi:[1,0]
	v_pk_mul_f32 v[12:13], v[12:13], v[184:185] op_sel_hi:[1,0]
	v_cmp_gt_i32_e32 vcc, 0, v16
	v_pk_mul_f32 v[8:9], v[8:9], v[184:185] op_sel_hi:[1,0]
	v_mov_b32_e32 v29, v209
	v_cndmask_b32_e64 v15, v13, 0, vcc
	v_cndmask_b32_e64 v14, v12, 0, vcc
	v_cndmask_b32_e64 v13, v19, 0, vcc
	v_cndmask_b32_e64 v12, v18, 0, vcc
	v_pk_mul_f32 v[18:19], v[10:11], v[184:185] op_sel_hi:[1,0]
	v_mov_b32_e32 v31, v209
	v_mov_b32_e32 v30, v209
	v_mov_b32_e32 v32, v209
	v_mov_b32_e32 v25, v209
	v_mov_b32_e32 v27, v209
	v_mov_b32_e32 v26, v209
	v_mov_b32_e32 v28, v209
	v_cndmask_b32_e64 v11, v9, 0, vcc
	v_cndmask_b32_e64 v10, v8, 0, vcc
	v_cndmask_b32_e64 v9, v19, 0, vcc
	v_cndmask_b32_e64 v8, v18, 0, vcc
	v_mov_b32_e32 v21, v209
	v_mov_b32_e32 v23, v209
	v_mov_b32_e32 v22, v209
	v_mov_b32_e32 v24, v209
	v_mov_b32_e32 v17, v209
	v_mov_b32_e32 v19, v209
	v_mov_b32_e32 v18, v209
	v_mov_b32_e32 v20, v209
	v_cmp_gt_i32_e32 vcc, s83, v16
	v_mov_b32_dpp v29, v14 row_ror:1 row_mask:0xf bank_mask:0xf
	v_mov_b32_dpp v31, v14 row_ror:2 row_mask:0xf bank_mask:0xf
	v_mov_b32_dpp v30, v15 row_ror:1 row_mask:0xf bank_mask:0xf
	v_mov_b32_dpp v32, v15 row_ror:2 row_mask:0xf bank_mask:0xf
	v_mov_b32_dpp v25, v12 row_ror:1 row_mask:0xf bank_mask:0xf
	v_mov_b32_dpp v27, v12 row_ror:2 row_mask:0xf bank_mask:0xf
	v_mov_b32_dpp v26, v13 row_ror:1 row_mask:0xf bank_mask:0xf
	v_mov_b32_dpp v28, v13 row_ror:2 row_mask:0xf bank_mask:0xf
	v_mov_b32_dpp v21, v10 row_ror:1 row_mask:0xf bank_mask:0xf
	v_mov_b32_dpp v23, v10 row_ror:2 row_mask:0xf bank_mask:0xf
	v_mov_b32_dpp v22, v11 row_ror:1 row_mask:0xf bank_mask:0xf
	v_mov_b32_dpp v24, v11 row_ror:2 row_mask:0xf bank_mask:0xf
	v_mov_b32_dpp v17, v8 row_ror:1 row_mask:0xf bank_mask:0xf
	v_mov_b32_dpp v19, v8 row_ror:2 row_mask:0xf bank_mask:0xf
	v_mov_b32_dpp v18, v9 row_ror:1 row_mask:0xf bank_mask:0xf
	v_mov_b32_dpp v20, v9 row_ror:2 row_mask:0xf bank_mask:0xf
	s_and_b64 s[6:7], s[54:55], vcc
	s_and_saveexec_b64 s[4:5], s[6:7]
	s_cbranch_execz .LBB0_317
	v_cndmask_b32_e64 v49, v48, v32, s[44:45]
	v_cndmask_b32_e64 v48, v47, v31, s[44:45]
	v_pk_fma_f32 v[48:49], v[96:97], v[48:49], v[100:101]
	v_cndmask_b32_e64 v31, v30, v46, s[42:43]
	v_cndmask_b32_e64 v30, v29, v45, s[42:43]
	v_pk_fma_f32 v[30:31], v[88:89], v[30:31], v[48:49]
	v_pk_mul_f32 v[4:5], v[4:5], v[184:185] op_sel_hi:[1,0]
	v_pk_fma_f32 v[14:15], v[14:15], v[92:93], v[30:31]
	v_pk_mul_f32 v[6:7], v[6:7], v[184:185] op_sel_hi:[1,0]
	v_mul_f32_e32 v29, 0x3d122279, v14
	v_fmaak_f32 v29, v14, v29, 0x3f4c422a
	v_mul_f32_e32 v29, v14, v29
	v_mul_f32_e32 v29, 0xc038aa3b, v29
	v_exp_f32_e32 v29, v29
	v_pk_mul_f32 v[0:1], v[0:1], v[184:185] op_sel_hi:[1,0]
	v_pk_mul_f32 v[2:3], v[2:3], v[184:185] op_sel_hi:[1,0]
	v_add_f32_e32 v29, 1.0, v29
	v_rcp_f32_e32 v30, v29
	v_mul_f32_e32 v29, 0x3d122279, v15
	v_fmaak_f32 v29, v15, v29, 0x3f4c422a
	v_mul_f32_e32 v29, v15, v29
	v_mul_f32_e32 v29, 0xc038aa3b, v29
	v_exp_f32_e32 v29, v29
	s_nop 0
	v_add_f32_e32 v29, 1.0, v29
	v_rcp_f32_e32 v31, v29
	s_nop 0
	v_pk_mul_f32 v[14:15], v[14:15], v[30:31]
	s_nop 0
	v_pk_mul_f32 v[4:5], v[4:5], v[14:15]
	v_cndmask_b32_e64 v15, v44, v28, s[44:45]
	v_cndmask_b32_e64 v14, v43, v27, s[44:45]
	v_pk_fma_f32 v[14:15], v[98:99], v[14:15], v[102:103]
	v_cndmask_b32_e64 v27, v26, v42, s[42:43]
	v_cndmask_b32_e64 v26, v25, v41, s[42:43]
	v_pk_fma_f32 v[14:15], v[90:91], v[26:27], v[14:15]
	s_nop 0
	v_pk_fma_f32 v[12:13], v[12:13], v[94:95], v[14:15]
	s_nop 0
	v_mul_f32_e32 v14, 0x3d122279, v12
	v_mul_f32_e32 v15, 0x3d122279, v13
	v_fmaak_f32 v14, v12, v14, 0x3f4c422a
	v_fmaak_f32 v15, v13, v15, 0x3f4c422a
	v_mul_f32_e32 v14, v12, v14
	v_mul_f32_e32 v15, v13, v15
	v_mul_f32_e32 v14, 0xc038aa3b, v14
	v_mul_f32_e32 v15, 0xc038aa3b, v15
	v_exp_f32_e32 v14, v14
	v_exp_f32_e32 v15, v15
	v_add_f32_e32 v14, 1.0, v14
	v_add_f32_e32 v15, 1.0, v15
	v_rcp_f32_e32 v14, v14
	v_rcp_f32_e32 v15, v15
	s_nop 0
	v_pk_mul_f32 v[12:13], v[12:13], v[14:15]
	s_nop 0
	v_pk_mul_f32 v[6:7], v[6:7], v[12:13]
	v_cndmask_b32_e64 v13, v40, v24, s[44:45]
	v_cndmask_b32_e64 v12, v39, v23, s[44:45]
	v_pk_fma_f32 v[12:13], v[72:73], v[12:13], v[76:77]
	v_cndmask_b32_e64 v15, v22, v38, s[42:43]
	v_cndmask_b32_e64 v14, v21, v37, s[42:43]
	v_pk_fma_f32 v[12:13], v[64:65], v[14:15], v[12:13]
	s_nop 0
	v_pk_fma_f32 v[10:11], v[10:11], v[68:69], v[12:13]
	s_nop 0
	v_mul_f32_e32 v12, 0x3d122279, v10
	v_mul_f32_e32 v13, 0x3d122279, v11
	v_fmaak_f32 v12, v10, v12, 0x3f4c422a
	v_fmaak_f32 v13, v11, v13, 0x3f4c422a
	v_mul_f32_e32 v12, v10, v12
	v_mul_f32_e32 v13, v11, v13
	v_mul_f32_e32 v12, 0xc038aa3b, v12
	v_mul_f32_e32 v13, 0xc038aa3b, v13
	v_exp_f32_e32 v12, v12
	v_exp_f32_e32 v13, v13
	v_add_f32_e32 v12, 1.0, v12
	v_add_f32_e32 v13, 1.0, v13
	v_rcp_f32_e32 v12, v12
	v_rcp_f32_e32 v13, v13
	s_nop 0
	v_pk_mul_f32 v[10:11], v[10:11], v[12:13]
	s_nop 0
	v_pk_mul_f32 v[10:11], v[0:1], v[10:11]
	v_cndmask_b32_e64 v1, v36, v20, s[44:45]
	v_cndmask_b32_e64 v0, v35, v19, s[44:45]
	v_cndmask_b32_e64 v13, v18, v34, s[42:43]
	v_cndmask_b32_e64 v12, v17, v33, s[42:43]
	v_pk_fma_f32 v[0:1], v[74:75], v[0:1], v[78:79]
	s_nop 0
	v_pk_fma_f32 v[0:1], v[66:67], v[12:13], v[0:1]
	s_nop 0
	v_pk_fma_f32 v[0:1], v[8:9], v[70:71], v[0:1]
	s_nop 0
	v_mul_f32_e32 v8, 0x3d122279, v0
	v_mul_f32_e32 v9, 0x3d122279, v1
	v_fmaak_f32 v8, v0, v8, 0x3f4c422a
	v_fmaak_f32 v9, v1, v9, 0x3f4c422a
	v_mul_f32_e32 v8, v0, v8
	v_mul_f32_e32 v9, v1, v9
	v_mul_f32_e32 v8, 0xc038aa3b, v8
	v_mul_f32_e32 v9, 0xc038aa3b, v9
	v_exp_f32_e32 v8, v8
	v_exp_f32_e32 v9, v9
	v_add_f32_e32 v8, 1.0, v8
	v_add_f32_e32 v9, 1.0, v9
	v_rcp_f32_e32 v8, v8
	v_rcp_f32_e32 v9, v9
	s_nop 0
	v_pk_mul_f32 v[0:1], v[0:1], v[8:9]
	s_nop 0
	v_pk_mul_f32 v[8:9], v[2:3], v[0:1]
	v_cvt_pk_bf16_f32 v0, v4, v5
	v_cvt_pk_bf16_f32 v1, v6, v7
	v_add_u32_e32 v6, s71, v16
	v_mov_b64_e32 v[4:5], s[12:13]
	v_mad_i64_i32 v[4:5], s[6:7], v6, s34, v[4:5]
	v_cvt_pk_bf16_f32 v2, v10, v11
	v_cvt_pk_bf16_f32 v3, v8, v9
	v_lshl_add_u64 v[4:5], v[182:183], 1, v[4:5]
	global_store_dwordx4 v[4:5], v[0:3], off

; __device__ __forceinline__ float row_rstd(const float* rss, long row, int fq) {
;     const f32x4 p = *(const f32x4*)(rss + row * 16 + fq * 4); float s = (p[0] + p[1]) + (p[2] + p[3]); s += __shfl_xor(s, 16); s += __shfl_xor(s, 32);
;     return rsqrtf(s * (1.0f / 1024.0f) + 1e-6f);
;     __device__ __forceinline__ void operator()(const f32x4 (&acc)[2][2][4][2], const Unit& u, int wr, int wc, int fr, int fq) const {
;         const int t = u.pn >> 2, row0 = u.pm * BM + wr * 64 + fr, col0 = (u.pn & 3) * BM + wc * 32 + 8 * fq;
;         bf16_t* base = (t == 4) ? O4 : O0 + (size_t)t * stride;
;         const float sc = (t == 2) ? qscale : 1.f;
; #pragma unroll
;         for (int ai = 0; ai < 2; ++ai)
; #pragma unroll
;             for (int m = 0; m < 4; ++m) { const int row = row0 + ai * HALF + m * 16; bf16_t* rowp = base + (size_t)row * 1024 + col0; float ss = 0.f; const float rn = row_rstd(rss, row, fq);
; #pragma unroll
;                 for (int bj = 0; bj < 2; ++bj) { f32x4 v0 = acc[ai][bj][m][0] * rn, v1 = acc[ai][bj][m][1] * rn;
;                     if (t <= 1) {
; #pragma unroll
;                         for (int j = 0; j < 4; ++j) { v0[j] = gelu_t(v0[j]); v1[j] = gelu_t(v1[j]); }
; #pragma unroll
;                         for (int j = 0; j < 4; ++j) ss += v0[j] * v0[j] + v1[j] * v1[j];
.LBB0_337:
	v_lshl_add_u32 v142, s4, 8, v154
	v_ashrrev_i32_e32 v143, 31, v142
	v_lshlrev_b64 v[144:145], 6, v[142:143]
	v_lshl_add_u64 v[146:147], v[136:137], 0, v[144:145]
	v_mov_b32_e32 v194, v146
	v_mov_b32_e32 v195, v147
	v_add_co_u32_e32 v192, vcc, 0x2000, v146
	s_nop 1
	v_addc_co_u32_e32 v193, vcc, 0, v147, vcc
	global_load_dwordx4 v[146:149], v[146:147], off
	global_load_dwordx4 v[164:167], v[194:195], off offset:1024
	global_load_dwordx4 v[168:171], v[194:195], off offset:2048
	global_load_dwordx4 v[172:175], v[194:195], off offset:3072
	global_load_dwordx4 v[176:179], v[192:193], off
	global_load_dwordx4 v[180:183], v[192:193], off offset:1024
	global_load_dwordx4 v[184:187], v[192:193], off offset:2048
	global_load_dwordx4 v[188:191], v[192:193], off offset:3072
	v_cmp_lt_i32_e32 vcc, v251, v246
	s_ashr_i32 s6, s10, 2
	s_cmp_lt_i32 s6, 2
	v_cndmask_b32_e32 v150, v245, v251, vcc
	v_lshlrev_b32_e32 v158, 2, v150
	v_cmp_lt_i32_e32 vcc, v252, v246
	s_cselect_b64 s[8:9], -1, 0
	s_cmp_gt_i32 s6, 1
	v_mov_b32_e32 v160, 0
	s_waitcnt vmcnt(7)
	v_mov_b32_e32 v150, v147
	v_mov_b32_e32 v151, v148
	v_mov_b32_e32 v147, v149
	v_pk_add_f32 v[146:147], v[150:151], v[146:147]
	v_cndmask_b32_e32 v148, v245, v252, vcc
	v_add_f32_e32 v146, v146, v147
	ds_bpermute_b32 v147, v158, v146
	v_lshlrev_b32_e32 v159, 2, v148
	s_waitcnt lgkmcnt(0)
	v_add_f32_e32 v146, v146, v147
	ds_bpermute_b32 v147, v159, v146
	s_waitcnt lgkmcnt(0)
	v_add_f32_e32 v146, v146, v147
	v_fmamk_f32 v146, v146, 0x3a800000, v210
	v_mul_f32_e32 v147, 0x4b800000, v146
	v_cmp_gt_f32_e32 vcc, s39, v146
	s_nop 1
	v_cndmask_b32_e32 v146, v146, v147, vcc
	v_rsq_f32_e32 v146, v146
	s_nop 0
	v_mul_f32_e32 v147, 0x45800000, v146
	v_cndmask_b32_e32 v146, v146, v147, vcc
	v_pk_mul_f32 v[148:149], v[126:127], v[146:147] op_sel_hi:[1,0]
	v_pk_mul_f32 v[126:127], v[124:125], v[146:147] op_sel_hi:[1,0]
	v_pk_mul_f32 v[152:153], v[122:123], v[146:147] op_sel_hi:[1,0]
	v_pk_mul_f32 v[150:151], v[120:121], v[146:147] op_sel_hi:[1,0]
	s_cbranch_scc1 .LBB0_339
	v_mul_f32_e32 v122, 0x3d122279, v127
	v_fmaak_f32 v122, v127, v122, 0x3f4c422a
	v_mul_f32_e32 v122, v127, v122
	v_mul_f32_e32 v121, 0x3d122279, v150
	v_mul_f32_e32 v122, 0xc038aa3b, v122
	v_fmaak_f32 v121, v150, v121, 0x3f4c422a
	v_exp_f32_e32 v123, v122
	v_mul_f32_e32 v122, 0x3d122279, v151
	v_mul_f32_e32 v121, v150, v121
	v_fmaak_f32 v122, v151, v122, 0x3f4c422a
	v_mul_f32_e32 v121, 0xc038aa3b, v121
	v_mul_f32_e32 v122, v151, v122
	v_exp_f32_e32 v121, v121
	v_mul_f32_e32 v122, 0xc038aa3b, v122
	v_exp_f32_e32 v124, v122
	v_mul_f32_e32 v125, 0x3d122279, v152
	v_mul_f32_e32 v120, 0x3d122279, v126
	v_add_f32_e32 v121, 1.0, v121
	v_fmaak_f32 v125, v152, v125, 0x3f4c422a
	v_mul_f32_e32 v147, 0x3d122279, v149
	v_mul_f32_e32 v160, 0x3d122279, v153
	v_fmaak_f32 v120, v126, v120, 0x3f4c422a
	v_rcp_f32_e32 v122, v121
	v_add_f32_e32 v121, 1.0, v123
	v_add_f32_e32 v123, 1.0, v124
	v_mul_f32_e32 v124, 0x3d122279, v148
	v_mul_f32_e32 v125, v152, v125
	v_fmaak_f32 v147, v149, v147, 0x3f4c422a
	v_fmaak_f32 v160, v153, v160, 0x3f4c422a
	v_mul_f32_e32 v120, v126, v120
	v_fmaak_f32 v124, v148, v124, 0x3f4c422a
	v_mul_f32_e32 v125, 0xc038aa3b, v125
	v_mul_f32_e32 v147, v149, v147
	v_mul_f32_e32 v160, v153, v160
	v_mul_f32_e32 v120, 0xc038aa3b, v120
	v_mul_f32_e32 v124, v148, v124
	v_exp_f32_e32 v125, v125
	v_mul_f32_e32 v147, 0xc038aa3b, v147
	v_mul_f32_e32 v160, 0xc038aa3b, v160
	v_exp_f32_e32 v120, v120
	v_mul_f32_e32 v124, 0xc038aa3b, v124
	v_exp_f32_e32 v147, v147
	v_exp_f32_e32 v161, v160
	v_exp_f32_e32 v124, v124
	v_add_f32_e32 v125, 1.0, v125
	v_add_f32_e32 v120, 1.0, v120
	v_rcp_f32_e32 v123, v123
	v_rcp_f32_e32 v160, v125
	v_add_f32_e32 v125, 1.0, v147
	v_add_f32_e32 v147, 1.0, v161
	v_rcp_f32_e32 v120, v120
	v_rcp_f32_e32 v121, v121
	v_add_f32_e32 v124, 1.0, v124
	v_rcp_f32_e32 v161, v147
	v_rcp_f32_e32 v124, v124
	v_rcp_f32_e32 v125, v125
	v_pk_mul_f32 v[150:151], v[150:151], v[122:123]
	v_pk_mul_f32 v[126:127], v[126:127], v[120:121]
	v_pk_mul_f32 v[120:121], v[150:151], v[150:151]
	v_pk_mul_f32 v[152:153], v[152:153], v[160:161]
	v_pk_fma_f32 v[120:121], v[126:127], v[126:127], v[120:121]
	v_pk_mul_f32 v[148:149], v[148:149], v[124:125]
	v_pk_mul_f32 v[122:123], v[152:153], v[152:153]
	v_add_f32_e32 v120, v120, v121
	v_pk_fma_f32 v[122:123], v[148:149], v[148:149], v[122:123]
	s_nop 0
	v_add_f32_e32 v120, v122, v120
	v_add_f32_e32 v160, v123, v120

; __device__ __forceinline__ float row_rstd(const float* rss, long row, int fq) {
;     const f32x4 p = *(const f32x4*)(rss + row * 16 + fq * 4); float s = (p[0] + p[1]) + (p[2] + p[3]); s += __shfl_xor(s, 16); s += __shfl_xor(s, 32);
;     return rsqrtf(s * (1.0f / 1024.0f) + 1e-6f);
;     __device__ __forceinline__ void operator()(const f32x4 (&acc)[2][2][4][2], const Unit& u, int wr, int wc, int fr, int fq) const {
;     ...
;             for (int m = 0; m < 4; ++m) { const int row = row0 + ai * HALF + m * 16; bf16_t* rowp = base + (size_t)row * 1024 + col0; float ss = 0.f; const float rn = row_rstd(rss, row, fq);
; #pragma unroll
;                 for (int bj = 0; bj < 2; ++bj) { f32x4 v0 = acc[ai][bj][m][0] * rn, v1 = acc[ai][bj][m][1] * rn;
;                     if (t <= 1) {
; #pragma unroll
;                         for (int j = 0; j < 4; ++j) { v0[j] = gelu_t(v0[j]); v1[j] = gelu_t(v1[j]); }
; #pragma unroll
;                         for (int j = 0; j < 4; ++j) ss += v0[j] * v0[j] + v1[j] * v1[j];
.LBB0_345:
	s_nop 0
	v_or_b32_e32 v114, 16, v142
	v_ashrrev_i32_e32 v115, 31, v114
	s_waitcnt lgkmcnt(0)
	v_lshlrev_b64 v[112:113], 6, v[114:115]
	s_and_b64 vcc, exec, s[4:5]
	v_mov_b32_e32 v126, 0
	s_waitcnt vmcnt(8)
	v_mov_b32_e32 v124, v165
	v_mov_b32_e32 v125, v166
	v_mov_b32_e32 v117, v167
	v_mov_b32_e32 v116, v164
	v_pk_add_f32 v[116:117], v[124:125], v[116:117]
	s_nop 0
	v_add_f32_e32 v116, v116, v117
	ds_bpermute_b32 v117, v158, v116
	s_waitcnt lgkmcnt(0)
	v_add_f32_e32 v116, v116, v117
	ds_bpermute_b32 v117, v159, v116
	s_waitcnt lgkmcnt(0)
	v_add_f32_e32 v116, v116, v117
	v_fmamk_f32 v116, v116, 0x3a800000, v210
	v_mul_f32_e32 v117, 0x4b800000, v116
	v_cmp_gt_f32_e64 s[6:7], s39, v116
	s_nop 1
	v_cndmask_b32_e64 v116, v116, v117, s[6:7]
	v_rsq_f32_e32 v116, v116
	s_nop 0
	v_mul_f32_e32 v117, 0x45800000, v116
	v_cndmask_b32_e64 v116, v116, v117, s[6:7]
	v_pk_mul_f32 v[124:125], v[110:111], v[116:117] op_sel_hi:[1,0]
	v_pk_mul_f32 v[118:119], v[108:109], v[116:117] op_sel_hi:[1,0]
	v_pk_mul_f32 v[110:111], v[106:107], v[116:117] op_sel_hi:[1,0]
	v_pk_mul_f32 v[108:109], v[104:105], v[116:117] op_sel_hi:[1,0]
	s_cbranch_vccnz .LBB0_347
	v_mul_f32_e32 v106, 0x3d122279, v119
	v_fmaak_f32 v106, v119, v106, 0x3f4c422a
	v_mul_f32_e32 v106, v119, v106
	v_mul_f32_e32 v105, 0x3d122279, v108
	v_mul_f32_e32 v106, 0xc038aa3b, v106
	v_fmaak_f32 v105, v108, v105, 0x3f4c422a
	v_exp_f32_e32 v107, v106
	v_mul_f32_e32 v106, 0x3d122279, v109
	v_mul_f32_e32 v105, v108, v105
	v_fmaak_f32 v106, v109, v106, 0x3f4c422a
	v_mul_f32_e32 v105, 0xc038aa3b, v105
	v_mul_f32_e32 v106, v109, v106
	v_exp_f32_e32 v105, v105
	v_mul_f32_e32 v106, 0xc038aa3b, v106
	v_exp_f32_e32 v117, v106
	v_mul_f32_e32 v126, 0x3d122279, v110
	v_add_f32_e32 v105, 1.0, v105
	v_rcp_f32_e32 v106, v105
	v_add_f32_e32 v105, 1.0, v107
	v_add_f32_e32 v107, 1.0, v117
	v_mul_f32_e32 v117, 0x3d122279, v124
	v_fmaak_f32 v117, v124, v117, 0x3f4c422a
	v_mul_f32_e32 v117, v124, v117
	v_fmaak_f32 v126, v110, v126, 0x3f4c422a
	v_mul_f32_e32 v117, 0xc038aa3b, v117
	v_mul_f32_e32 v126, v110, v126
	v_exp_f32_e32 v117, v117
	v_mul_f32_e32 v126, 0xc038aa3b, v126
	v_exp_f32_e32 v127, v126
	v_mul_f32_e32 v104, 0x3d122279, v118
	v_add_f32_e32 v117, 1.0, v117
	v_rcp_f32_e32 v126, v117
	v_add_f32_e32 v117, 1.0, v127
	v_mul_f32_e32 v127, 0x3d122279, v125
	v_fmaak_f32 v127, v125, v127, 0x3f4c422a
	v_mul_f32_e32 v143, 0x3d122279, v111
	v_fmaak_f32 v104, v118, v104, 0x3f4c422a
	v_mul_f32_e32 v127, v125, v127
	v_fmaak_f32 v143, v111, v143, 0x3f4c422a
	v_mul_f32_e32 v104, v118, v104
	v_mul_f32_e32 v127, 0xc038aa3b, v127
	v_mul_f32_e32 v143, v111, v143
	v_mul_f32_e32 v104, 0xc038aa3b, v104
	v_exp_f32_e32 v127, v127
	v_mul_f32_e32 v143, 0xc038aa3b, v143
	v_exp_f32_e32 v104, v104
	v_exp_f32_e32 v143, v143
	v_rcp_f32_e32 v144, v117
	v_add_f32_e32 v117, 1.0, v127
	v_add_f32_e32 v104, 1.0, v104
	v_rcp_f32_e32 v107, v107
	v_rcp_f32_e32 v127, v117
	v_add_f32_e32 v117, 1.0, v143
	v_rcp_f32_e32 v104, v104
	v_rcp_f32_e32 v105, v105
	v_rcp_f32_e32 v145, v117
	v_pk_mul_f32 v[108:109], v[108:109], v[106:107]
	v_pk_mul_f32 v[124:125], v[124:125], v[126:127]
	v_pk_mul_f32 v[118:119], v[118:119], v[104:105]
	v_pk_mul_f32 v[104:105], v[108:109], v[108:109]
	v_pk_mul_f32 v[110:111], v[110:111], v[144:145]
	v_pk_fma_f32 v[104:105], v[118:119], v[118:119], v[104:105]
	v_pk_mul_f32 v[106:107], v[110:111], v[110:111]
	v_add_f32_e32 v104, v104, v105
	v_pk_fma_f32 v[106:107], v[124:125], v[124:125], v[106:107]
	s_nop 0
	v_add_f32_e32 v104, v106, v104
	v_add_f32_e32 v126, v107, v104

; __device__ __forceinline__ float row_rstd(const float* rss, long row, int fq) {
;     const f32x4 p = *(const f32x4*)(rss + row * 16 + fq * 4); float s = (p[0] + p[1]) + (p[2] + p[3]); s += __shfl_xor(s, 16); s += __shfl_xor(s, 32);
;     return rsqrtf(s * (1.0f / 1024.0f) + 1e-6f);
;     __device__ __forceinline__ void operator()(const f32x4 (&acc)[2][2][4][2], const Unit& u, int wr, int wc, int fr, int fq) const {
;     ...
;             for (int m = 0; m < 4; ++m) { const int row = row0 + ai * HALF + m * 16; bf16_t* rowp = base + (size_t)row * 1024 + col0; float ss = 0.f; const float rn = row_rstd(rss, row, fq);
; #pragma unroll
;                 for (int bj = 0; bj < 2; ++bj) { f32x4 v0 = acc[ai][bj][m][0] * rn, v1 = acc[ai][bj][m][1] * rn;
;                     if (t <= 1) {
; #pragma unroll
;                         for (int j = 0; j < 4; ++j) { v0[j] = gelu_t(v0[j]); v1[j] = gelu_t(v1[j]); }
; #pragma unroll
;                         for (int j = 0; j < 4; ++j) ss += v0[j] * v0[j] + v1[j] * v1[j];
.LBB0_353:
	s_nop 0
	v_or_b32_e32 v98, 32, v142
	v_ashrrev_i32_e32 v99, 31, v98
	s_waitcnt lgkmcnt(0)
	v_lshlrev_b64 v[96:97], 6, v[98:99]
	s_and_b64 vcc, exec, s[4:5]
	v_mov_b32_e32 v106, 0
	s_waitcnt vmcnt(9)
	v_mov_b32_e32 v104, v169
	v_mov_b32_e32 v105, v170
	v_mov_b32_e32 v101, v171
	v_mov_b32_e32 v100, v168
	v_pk_add_f32 v[100:101], v[104:105], v[100:101]
	s_nop 0
	v_add_f32_e32 v100, v100, v101
	ds_bpermute_b32 v101, v158, v100
	s_waitcnt lgkmcnt(0)
	v_add_f32_e32 v100, v100, v101
	ds_bpermute_b32 v101, v159, v100
	s_waitcnt lgkmcnt(0)
	v_add_f32_e32 v100, v100, v101
	v_fmamk_f32 v100, v100, 0x3a800000, v210
	v_mul_f32_e32 v101, 0x4b800000, v100
	v_cmp_gt_f32_e64 s[8:9], s39, v100
	s_nop 1
	v_cndmask_b32_e64 v100, v100, v101, s[8:9]
	v_rsq_f32_e32 v100, v100
	s_nop 0
	v_mul_f32_e32 v101, 0x45800000, v100
	v_cndmask_b32_e64 v100, v100, v101, s[8:9]
	v_pk_mul_f32 v[104:105], v[94:95], v[100:101] op_sel_hi:[1,0]
	v_pk_mul_f32 v[102:103], v[92:93], v[100:101] op_sel_hi:[1,0]
	v_pk_mul_f32 v[94:95], v[90:91], v[100:101] op_sel_hi:[1,0]
	v_pk_mul_f32 v[92:93], v[88:89], v[100:101] op_sel_hi:[1,0]
	s_cbranch_vccnz .LBB0_355
	v_mul_f32_e32 v90, 0x3d122279, v103
	v_fmaak_f32 v90, v103, v90, 0x3f4c422a
	v_mul_f32_e32 v90, v103, v90
	v_mul_f32_e32 v89, 0x3d122279, v92
	v_mul_f32_e32 v90, 0xc038aa3b, v90
	v_fmaak_f32 v89, v92, v89, 0x3f4c422a
	v_exp_f32_e32 v91, v90
	v_mul_f32_e32 v90, 0x3d122279, v93
	v_mul_f32_e32 v89, v92, v89
	v_fmaak_f32 v90, v93, v90, 0x3f4c422a
	v_mul_f32_e32 v89, 0xc038aa3b, v89
	v_mul_f32_e32 v90, v93, v90
	v_exp_f32_e32 v89, v89
	v_mul_f32_e32 v90, 0xc038aa3b, v90
	v_exp_f32_e32 v101, v90
	v_mul_f32_e32 v106, 0x3d122279, v94
	v_add_f32_e32 v89, 1.0, v89
	v_rcp_f32_e32 v90, v89
	v_add_f32_e32 v89, 1.0, v91
	v_add_f32_e32 v91, 1.0, v101
	v_mul_f32_e32 v101, 0x3d122279, v104
	v_fmaak_f32 v101, v104, v101, 0x3f4c422a
	v_mul_f32_e32 v101, v104, v101
	v_fmaak_f32 v106, v94, v106, 0x3f4c422a
	v_mul_f32_e32 v101, 0xc038aa3b, v101
	v_mul_f32_e32 v106, v94, v106
	v_exp_f32_e32 v101, v101
	v_mul_f32_e32 v106, 0xc038aa3b, v106
	v_exp_f32_e32 v107, v106
	v_mul_f32_e32 v88, 0x3d122279, v102
	v_add_f32_e32 v101, 1.0, v101
	v_rcp_f32_e32 v106, v101
	v_add_f32_e32 v101, 1.0, v107
	v_mul_f32_e32 v107, 0x3d122279, v105
	v_fmaak_f32 v107, v105, v107, 0x3f4c422a
	v_mul_f32_e32 v108, 0x3d122279, v95
	v_fmaak_f32 v88, v102, v88, 0x3f4c422a
	v_mul_f32_e32 v107, v105, v107
	v_fmaak_f32 v108, v95, v108, 0x3f4c422a
	v_mul_f32_e32 v88, v102, v88
	v_mul_f32_e32 v107, 0xc038aa3b, v107
	v_mul_f32_e32 v108, v95, v108
	v_mul_f32_e32 v88, 0xc038aa3b, v88
	v_exp_f32_e32 v107, v107
	v_mul_f32_e32 v108, 0xc038aa3b, v108
	v_exp_f32_e32 v88, v88
	v_exp_f32_e32 v109, v108
	v_rcp_f32_e32 v108, v101
	v_add_f32_e32 v101, 1.0, v107
	v_add_f32_e32 v88, 1.0, v88
	v_rcp_f32_e32 v91, v91
	v_rcp_f32_e32 v107, v101
	v_add_f32_e32 v101, 1.0, v109
	v_rcp_f32_e32 v88, v88
	v_rcp_f32_e32 v89, v89
	v_rcp_f32_e32 v109, v101
	v_pk_mul_f32 v[92:93], v[92:93], v[90:91]
	v_pk_mul_f32 v[104:105], v[104:105], v[106:107]
	v_pk_mul_f32 v[102:103], v[102:103], v[88:89]
	v_pk_mul_f32 v[88:89], v[92:93], v[92:93]
	v_pk_mul_f32 v[94:95], v[94:95], v[108:109]
	v_pk_fma_f32 v[88:89], v[102:103], v[102:103], v[88:89]
	v_pk_mul_f32 v[90:91], v[94:95], v[94:95]
	v_add_f32_e32 v88, v88, v89
	v_pk_fma_f32 v[90:91], v[104:105], v[104:105], v[90:91]
	s_nop 0
	v_add_f32_e32 v88, v90, v88
	v_add_f32_e32 v106, v91, v88

; __device__ __forceinline__ float row_rstd(const float* rss, long row, int fq) {
;     const f32x4 p = *(const f32x4*)(rss + row * 16 + fq * 4); float s = (p[0] + p[1]) + (p[2] + p[3]); s += __shfl_xor(s, 16); s += __shfl_xor(s, 32);
;     return rsqrtf(s * (1.0f / 1024.0f) + 1e-6f);
;     __device__ __forceinline__ void operator()(const f32x4 (&acc)[2][2][4][2], const Unit& u, int wr, int wc, int fr, int fq) const {
;     ...
;             for (int m = 0; m < 4; ++m) { const int row = row0 + ai * HALF + m * 16; bf16_t* rowp = base + (size_t)row * 1024 + col0; float ss = 0.f; const float rn = row_rstd(rss, row, fq);
; #pragma unroll
;                 for (int bj = 0; bj < 2; ++bj) { f32x4 v0 = acc[ai][bj][m][0] * rn, v1 = acc[ai][bj][m][1] * rn;
;                     if (t <= 1) {
; #pragma unroll
;                         for (int j = 0; j < 4; ++j) { v0[j] = gelu_t(v0[j]); v1[j] = gelu_t(v1[j]); }
; #pragma unroll
;                         for (int j = 0; j < 4; ++j) ss += v0[j] * v0[j] + v1[j] * v1[j];
.LBB0_361:
	s_nop 0
	v_or_b32_e32 v82, 48, v142
	v_ashrrev_i32_e32 v83, 31, v82
	s_waitcnt lgkmcnt(0)
	v_lshlrev_b64 v[80:81], 6, v[82:83]
	s_and_b64 vcc, exec, s[4:5]
	v_mov_b32_e32 v90, 0
	s_waitcnt vmcnt(10)
	v_mov_b32_e32 v88, v173
	v_mov_b32_e32 v89, v174
	v_mov_b32_e32 v85, v175
	v_mov_b32_e32 v84, v172
	v_pk_add_f32 v[84:85], v[88:89], v[84:85]
	s_nop 0
	v_add_f32_e32 v84, v84, v85
	ds_bpermute_b32 v85, v158, v84
	s_waitcnt lgkmcnt(0)
	v_add_f32_e32 v84, v84, v85
	ds_bpermute_b32 v85, v159, v84
	s_waitcnt lgkmcnt(0)
	v_add_f32_e32 v84, v84, v85
	v_fmamk_f32 v84, v84, 0x3a800000, v210
	v_mul_f32_e32 v85, 0x4b800000, v84
	v_cmp_gt_f32_e64 s[8:9], s39, v84
	s_nop 1
	v_cndmask_b32_e64 v84, v84, v85, s[8:9]
	v_rsq_f32_e32 v84, v84
	s_nop 0
	v_mul_f32_e32 v85, 0x45800000, v84
	v_cndmask_b32_e64 v84, v84, v85, s[8:9]
	v_pk_mul_f32 v[88:89], v[78:79], v[84:85] op_sel_hi:[1,0]
	v_pk_mul_f32 v[86:87], v[76:77], v[84:85] op_sel_hi:[1,0]
	v_pk_mul_f32 v[78:79], v[74:75], v[84:85] op_sel_hi:[1,0]
	v_pk_mul_f32 v[76:77], v[72:73], v[84:85] op_sel_hi:[1,0]
	s_cbranch_vccnz .LBB0_363
	v_mul_f32_e32 v74, 0x3d122279, v87
	v_fmaak_f32 v74, v87, v74, 0x3f4c422a
	v_mul_f32_e32 v74, v87, v74
	v_mul_f32_e32 v73, 0x3d122279, v76
	v_mul_f32_e32 v74, 0xc038aa3b, v74
	v_fmaak_f32 v73, v76, v73, 0x3f4c422a
	v_exp_f32_e32 v75, v74
	v_mul_f32_e32 v74, 0x3d122279, v77
	v_mul_f32_e32 v73, v76, v73
	v_fmaak_f32 v74, v77, v74, 0x3f4c422a
	v_mul_f32_e32 v73, 0xc038aa3b, v73
	v_mul_f32_e32 v74, v77, v74
	v_exp_f32_e32 v73, v73
	v_mul_f32_e32 v74, 0xc038aa3b, v74
	v_exp_f32_e32 v85, v74
	v_mul_f32_e32 v90, 0x3d122279, v78
	v_add_f32_e32 v73, 1.0, v73
	v_rcp_f32_e32 v74, v73
	v_add_f32_e32 v73, 1.0, v75
	v_add_f32_e32 v75, 1.0, v85
	v_mul_f32_e32 v85, 0x3d122279, v88
	v_fmaak_f32 v85, v88, v85, 0x3f4c422a
	v_mul_f32_e32 v85, v88, v85
	v_fmaak_f32 v90, v78, v90, 0x3f4c422a
	v_mul_f32_e32 v85, 0xc038aa3b, v85
	v_mul_f32_e32 v90, v78, v90
	v_exp_f32_e32 v85, v85
	v_mul_f32_e32 v90, 0xc038aa3b, v90
	v_exp_f32_e32 v91, v90
	v_mul_f32_e32 v72, 0x3d122279, v86
	v_add_f32_e32 v85, 1.0, v85
	v_rcp_f32_e32 v90, v85
	v_add_f32_e32 v85, 1.0, v91
	v_mul_f32_e32 v91, 0x3d122279, v89
	v_fmaak_f32 v91, v89, v91, 0x3f4c422a
	v_mul_f32_e32 v92, 0x3d122279, v79
	v_fmaak_f32 v72, v86, v72, 0x3f4c422a
	v_mul_f32_e32 v91, v89, v91
	v_fmaak_f32 v92, v79, v92, 0x3f4c422a
	v_mul_f32_e32 v72, v86, v72
	v_mul_f32_e32 v91, 0xc038aa3b, v91
	v_mul_f32_e32 v92, v79, v92
	v_mul_f32_e32 v72, 0xc038aa3b, v72
	v_exp_f32_e32 v91, v91
	v_mul_f32_e32 v92, 0xc038aa3b, v92
	v_exp_f32_e32 v72, v72
	v_exp_f32_e32 v93, v92
	v_rcp_f32_e32 v92, v85
	v_add_f32_e32 v85, 1.0, v91
	v_add_f32_e32 v72, 1.0, v72
	v_rcp_f32_e32 v75, v75
	v_rcp_f32_e32 v91, v85
	v_add_f32_e32 v85, 1.0, v93
	v_rcp_f32_e32 v72, v72
	v_rcp_f32_e32 v73, v73
	v_rcp_f32_e32 v93, v85
	v_pk_mul_f32 v[76:77], v[76:77], v[74:75]
	v_pk_mul_f32 v[88:89], v[88:89], v[90:91]
	v_pk_mul_f32 v[86:87], v[86:87], v[72:73]
	v_pk_mul_f32 v[72:73], v[76:77], v[76:77]
	v_pk_mul_f32 v[78:79], v[78:79], v[92:93]
	v_pk_fma_f32 v[72:73], v[86:87], v[86:87], v[72:73]
	v_pk_mul_f32 v[74:75], v[78:79], v[78:79]
	v_add_f32_e32 v72, v72, v73
	v_pk_fma_f32 v[74:75], v[88:89], v[88:89], v[74:75]
	s_nop 0
	v_add_f32_e32 v72, v74, v72
	v_add_f32_e32 v90, v75, v72

; __device__ __forceinline__ float row_rstd(const float* rss, long row, int fq) {
;     const f32x4 p = *(const f32x4*)(rss + row * 16 + fq * 4); float s = (p[0] + p[1]) + (p[2] + p[3]); s += __shfl_xor(s, 16); s += __shfl_xor(s, 32);
;     return rsqrtf(s * (1.0f / 1024.0f) + 1e-6f);
;     __device__ __forceinline__ void operator()(const f32x4 (&acc)[2][2][4][2], const Unit& u, int wr, int wc, int fr, int fq) const {
;     ...
;             for (int m = 0; m < 4; ++m) { const int row = row0 + ai * HALF + m * 16; bf16_t* rowp = base + (size_t)row * 1024 + col0; float ss = 0.f; const float rn = row_rstd(rss, row, fq);
; #pragma unroll
;                 for (int bj = 0; bj < 2; ++bj) { f32x4 v0 = acc[ai][bj][m][0] * rn, v1 = acc[ai][bj][m][1] * rn;
;                     if (t <= 1) {
; #pragma unroll
;                         for (int j = 0; j < 4; ++j) { v0[j] = gelu_t(v0[j]); v1[j] = gelu_t(v1[j]); }
; #pragma unroll
;                         for (int j = 0; j < 4; ++j) ss += v0[j] * v0[j] + v1[j] * v1[j];
.LBB0_369:
	s_nop 0
	v_add_u32_e32 v66, 0x80, v142
	v_ashrrev_i32_e32 v67, 31, v66
	s_waitcnt lgkmcnt(0)
	v_lshlrev_b64 v[64:65], 6, v[66:67]
	s_and_b64 vcc, exec, s[4:5]
	v_mov_b32_e32 v74, 0
	s_waitcnt vmcnt(11)
	v_mov_b32_e32 v72, v177
	v_mov_b32_e32 v73, v178
	v_mov_b32_e32 v69, v179
	v_mov_b32_e32 v68, v176
	v_pk_add_f32 v[68:69], v[72:73], v[68:69]
	s_nop 0
	v_add_f32_e32 v68, v68, v69
	ds_bpermute_b32 v69, v158, v68
	s_waitcnt lgkmcnt(0)
	v_add_f32_e32 v68, v68, v69
	ds_bpermute_b32 v69, v159, v68
	s_waitcnt lgkmcnt(0)
	v_add_f32_e32 v68, v68, v69
	v_fmamk_f32 v68, v68, 0x3a800000, v210
	v_mul_f32_e32 v69, 0x4b800000, v68
	v_cmp_gt_f32_e64 s[8:9], s39, v68
	s_nop 1
	v_cndmask_b32_e64 v68, v68, v69, s[8:9]
	v_rsq_f32_e32 v68, v68
	s_nop 0
	v_mul_f32_e32 v69, 0x45800000, v68
	v_cndmask_b32_e64 v68, v68, v69, s[8:9]
	v_pk_mul_f32 v[72:73], v[62:63], v[68:69] op_sel_hi:[1,0]
	v_pk_mul_f32 v[70:71], v[60:61], v[68:69] op_sel_hi:[1,0]
	v_pk_mul_f32 v[62:63], v[58:59], v[68:69] op_sel_hi:[1,0]
	v_pk_mul_f32 v[60:61], v[56:57], v[68:69] op_sel_hi:[1,0]
	s_cbranch_vccnz .LBB0_371
	v_mul_f32_e32 v58, 0x3d122279, v71
	v_fmaak_f32 v58, v71, v58, 0x3f4c422a
	v_mul_f32_e32 v58, v71, v58
	v_mul_f32_e32 v57, 0x3d122279, v60
	v_mul_f32_e32 v58, 0xc038aa3b, v58
	v_fmaak_f32 v57, v60, v57, 0x3f4c422a
	v_exp_f32_e32 v59, v58
	v_mul_f32_e32 v58, 0x3d122279, v61
	v_mul_f32_e32 v57, v60, v57
	v_fmaak_f32 v58, v61, v58, 0x3f4c422a
	v_mul_f32_e32 v57, 0xc038aa3b, v57
	v_mul_f32_e32 v58, v61, v58
	v_exp_f32_e32 v57, v57
	v_mul_f32_e32 v58, 0xc038aa3b, v58
	v_exp_f32_e32 v69, v58
	v_mul_f32_e32 v74, 0x3d122279, v62
	v_add_f32_e32 v57, 1.0, v57
	v_rcp_f32_e32 v58, v57
	v_add_f32_e32 v57, 1.0, v59
	v_add_f32_e32 v59, 1.0, v69
	v_mul_f32_e32 v69, 0x3d122279, v72
	v_fmaak_f32 v69, v72, v69, 0x3f4c422a
	v_mul_f32_e32 v69, v72, v69
	v_fmaak_f32 v74, v62, v74, 0x3f4c422a
	v_mul_f32_e32 v69, 0xc038aa3b, v69
	v_mul_f32_e32 v74, v62, v74
	v_exp_f32_e32 v69, v69
	v_mul_f32_e32 v74, 0xc038aa3b, v74
	v_exp_f32_e32 v75, v74
	v_mul_f32_e32 v56, 0x3d122279, v70
	v_add_f32_e32 v69, 1.0, v69
	v_rcp_f32_e32 v74, v69
	v_add_f32_e32 v69, 1.0, v75
	v_mul_f32_e32 v75, 0x3d122279, v73
	v_fmaak_f32 v75, v73, v75, 0x3f4c422a
	v_mul_f32_e32 v76, 0x3d122279, v63
	v_fmaak_f32 v56, v70, v56, 0x3f4c422a
	v_mul_f32_e32 v75, v73, v75
	v_fmaak_f32 v76, v63, v76, 0x3f4c422a
	v_mul_f32_e32 v56, v70, v56
	v_mul_f32_e32 v75, 0xc038aa3b, v75
	v_mul_f32_e32 v76, v63, v76
	v_mul_f32_e32 v56, 0xc038aa3b, v56
	v_exp_f32_e32 v75, v75
	v_mul_f32_e32 v76, 0xc038aa3b, v76
	v_exp_f32_e32 v56, v56
	v_exp_f32_e32 v77, v76
	v_rcp_f32_e32 v76, v69
	v_add_f32_e32 v69, 1.0, v75
	v_add_f32_e32 v56, 1.0, v56
	v_rcp_f32_e32 v59, v59
	v_rcp_f32_e32 v75, v69
	v_add_f32_e32 v69, 1.0, v77
	v_rcp_f32_e32 v56, v56
	v_rcp_f32_e32 v57, v57
	v_rcp_f32_e32 v77, v69
	v_pk_mul_f32 v[60:61], v[60:61], v[58:59]
	v_pk_mul_f32 v[72:73], v[72:73], v[74:75]
	v_pk_mul_f32 v[70:71], v[70:71], v[56:57]
	v_pk_mul_f32 v[56:57], v[60:61], v[60:61]
	v_pk_mul_f32 v[62:63], v[62:63], v[76:77]
	v_pk_fma_f32 v[56:57], v[70:71], v[70:71], v[56:57]
	v_pk_mul_f32 v[58:59], v[62:63], v[62:63]
	v_add_f32_e32 v56, v56, v57
	v_pk_fma_f32 v[58:59], v[72:73], v[72:73], v[58:59]
	s_nop 0
	v_add_f32_e32 v56, v58, v56
	v_add_f32_e32 v74, v59, v56

; __device__ __forceinline__ float row_rstd(const float* rss, long row, int fq) {
;     const f32x4 p = *(const f32x4*)(rss + row * 16 + fq * 4); float s = (p[0] + p[1]) + (p[2] + p[3]); s += __shfl_xor(s, 16); s += __shfl_xor(s, 32);
;     return rsqrtf(s * (1.0f / 1024.0f) + 1e-6f);
;     __device__ __forceinline__ void operator()(const f32x4 (&acc)[2][2][4][2], const Unit& u, int wr, int wc, int fr, int fq) const {
;     ...
;             for (int m = 0; m < 4; ++m) { const int row = row0 + ai * HALF + m * 16; bf16_t* rowp = base + (size_t)row * 1024 + col0; float ss = 0.f; const float rn = row_rstd(rss, row, fq);
; #pragma unroll
;                 for (int bj = 0; bj < 2; ++bj) { f32x4 v0 = acc[ai][bj][m][0] * rn, v1 = acc[ai][bj][m][1] * rn;
;                     if (t <= 1) {
; #pragma unroll
;                         for (int j = 0; j < 4; ++j) { v0[j] = gelu_t(v0[j]); v1[j] = gelu_t(v1[j]); }
; #pragma unroll
;                         for (int j = 0; j < 4; ++j) ss += v0[j] * v0[j] + v1[j] * v1[j];
.LBB0_377:
	s_nop 0
	v_add_u32_e32 v50, 0x90, v142
	v_ashrrev_i32_e32 v51, 31, v50
	s_waitcnt lgkmcnt(0)
	v_lshlrev_b64 v[48:49], 6, v[50:51]
	s_and_b64 vcc, exec, s[4:5]
	v_mov_b32_e32 v58, 0
	s_waitcnt vmcnt(12)
	v_mov_b32_e32 v56, v181
	v_mov_b32_e32 v57, v182
	v_mov_b32_e32 v53, v183
	v_mov_b32_e32 v52, v180
	v_pk_add_f32 v[52:53], v[56:57], v[52:53]
	s_nop 0
	v_add_f32_e32 v52, v52, v53
	ds_bpermute_b32 v53, v158, v52
	s_waitcnt lgkmcnt(0)
	v_add_f32_e32 v52, v52, v53
	ds_bpermute_b32 v53, v159, v52
	s_waitcnt lgkmcnt(0)
	v_add_f32_e32 v52, v52, v53
	v_fmamk_f32 v52, v52, 0x3a800000, v210
	v_mul_f32_e32 v53, 0x4b800000, v52
	v_cmp_gt_f32_e64 s[8:9], s39, v52
	s_nop 1
	v_cndmask_b32_e64 v52, v52, v53, s[8:9]
	v_rsq_f32_e32 v52, v52
	s_nop 0
	v_mul_f32_e32 v53, 0x45800000, v52
	v_cndmask_b32_e64 v52, v52, v53, s[8:9]
	v_pk_mul_f32 v[56:57], v[46:47], v[52:53] op_sel_hi:[1,0]
	v_pk_mul_f32 v[54:55], v[44:45], v[52:53] op_sel_hi:[1,0]
	v_pk_mul_f32 v[46:47], v[42:43], v[52:53] op_sel_hi:[1,0]
	v_pk_mul_f32 v[44:45], v[40:41], v[52:53] op_sel_hi:[1,0]
	s_cbranch_vccnz .LBB0_379
	v_mul_f32_e32 v42, 0x3d122279, v55
	v_fmaak_f32 v42, v55, v42, 0x3f4c422a
	v_mul_f32_e32 v42, v55, v42
	v_mul_f32_e32 v41, 0x3d122279, v44
	v_mul_f32_e32 v42, 0xc038aa3b, v42
	v_fmaak_f32 v41, v44, v41, 0x3f4c422a
	v_exp_f32_e32 v43, v42
	v_mul_f32_e32 v42, 0x3d122279, v45
	v_mul_f32_e32 v41, v44, v41
	v_fmaak_f32 v42, v45, v42, 0x3f4c422a
	v_mul_f32_e32 v41, 0xc038aa3b, v41
	v_mul_f32_e32 v42, v45, v42
	v_exp_f32_e32 v41, v41
	v_mul_f32_e32 v42, 0xc038aa3b, v42
	v_exp_f32_e32 v53, v42
	v_mul_f32_e32 v58, 0x3d122279, v46
	v_add_f32_e32 v41, 1.0, v41
	v_rcp_f32_e32 v42, v41
	v_add_f32_e32 v41, 1.0, v43
	v_add_f32_e32 v43, 1.0, v53
	v_mul_f32_e32 v53, 0x3d122279, v56
	v_fmaak_f32 v53, v56, v53, 0x3f4c422a
	v_mul_f32_e32 v53, v56, v53
	v_fmaak_f32 v58, v46, v58, 0x3f4c422a
	v_mul_f32_e32 v53, 0xc038aa3b, v53
	v_mul_f32_e32 v58, v46, v58
	v_exp_f32_e32 v53, v53
	v_mul_f32_e32 v58, 0xc038aa3b, v58
	v_exp_f32_e32 v59, v58
	v_mul_f32_e32 v40, 0x3d122279, v54
	v_add_f32_e32 v53, 1.0, v53
	v_rcp_f32_e32 v58, v53
	v_add_f32_e32 v53, 1.0, v59
	v_mul_f32_e32 v59, 0x3d122279, v57
	v_fmaak_f32 v59, v57, v59, 0x3f4c422a
	v_mul_f32_e32 v60, 0x3d122279, v47
	v_fmaak_f32 v40, v54, v40, 0x3f4c422a
	v_mul_f32_e32 v59, v57, v59
	v_fmaak_f32 v60, v47, v60, 0x3f4c422a
	v_mul_f32_e32 v40, v54, v40
	v_mul_f32_e32 v59, 0xc038aa3b, v59
	v_mul_f32_e32 v60, v47, v60
	v_mul_f32_e32 v40, 0xc038aa3b, v40
	v_exp_f32_e32 v59, v59
	v_mul_f32_e32 v60, 0xc038aa3b, v60
	v_exp_f32_e32 v40, v40
	v_exp_f32_e32 v61, v60
	v_rcp_f32_e32 v60, v53
	v_add_f32_e32 v53, 1.0, v59
	v_add_f32_e32 v40, 1.0, v40
	v_rcp_f32_e32 v43, v43
	v_rcp_f32_e32 v59, v53
	v_add_f32_e32 v53, 1.0, v61
	v_rcp_f32_e32 v40, v40
	v_rcp_f32_e32 v41, v41
	v_rcp_f32_e32 v61, v53
	v_pk_mul_f32 v[44:45], v[44:45], v[42:43]
	v_pk_mul_f32 v[56:57], v[56:57], v[58:59]
	v_pk_mul_f32 v[54:55], v[54:55], v[40:41]
	v_pk_mul_f32 v[40:41], v[44:45], v[44:45]
	v_pk_mul_f32 v[46:47], v[46:47], v[60:61]
	v_pk_fma_f32 v[40:41], v[54:55], v[54:55], v[40:41]
	v_pk_mul_f32 v[42:43], v[46:47], v[46:47]
	v_add_f32_e32 v40, v40, v41
	v_pk_fma_f32 v[42:43], v[56:57], v[56:57], v[42:43]
	s_nop 0
	v_add_f32_e32 v40, v42, v40
	v_add_f32_e32 v58, v43, v40

; __device__ __forceinline__ float row_rstd(const float* rss, long row, int fq) {
;     const f32x4 p = *(const f32x4*)(rss + row * 16 + fq * 4); float s = (p[0] + p[1]) + (p[2] + p[3]); s += __shfl_xor(s, 16); s += __shfl_xor(s, 32);
;     return rsqrtf(s * (1.0f / 1024.0f) + 1e-6f);
;     __device__ __forceinline__ void operator()(const f32x4 (&acc)[2][2][4][2], const Unit& u, int wr, int wc, int fr, int fq) const {
;     ...
;             for (int m = 0; m < 4; ++m) { const int row = row0 + ai * HALF + m * 16; bf16_t* rowp = base + (size_t)row * 1024 + col0; float ss = 0.f; const float rn = row_rstd(rss, row, fq);
; #pragma unroll
;                 for (int bj = 0; bj < 2; ++bj) { f32x4 v0 = acc[ai][bj][m][0] * rn, v1 = acc[ai][bj][m][1] * rn;
;                     if (t <= 1) {
; #pragma unroll
;                         for (int j = 0; j < 4; ++j) { v0[j] = gelu_t(v0[j]); v1[j] = gelu_t(v1[j]); }
; #pragma unroll
;                         for (int j = 0; j < 4; ++j) ss += v0[j] * v0[j] + v1[j] * v1[j];
.LBB0_385:
	s_nop 0
	v_add_u32_e32 v34, 0xa0, v142
	v_ashrrev_i32_e32 v35, 31, v34
	s_waitcnt lgkmcnt(0)
	v_lshlrev_b64 v[32:33], 6, v[34:35]
	s_and_b64 vcc, exec, s[4:5]
	v_mov_b32_e32 v42, 0
	s_waitcnt vmcnt(13)
	v_mov_b32_e32 v40, v185
	v_mov_b32_e32 v41, v186
	v_mov_b32_e32 v37, v187
	v_mov_b32_e32 v36, v184
	v_pk_add_f32 v[36:37], v[40:41], v[36:37]
	s_nop 0
	v_add_f32_e32 v36, v36, v37
	ds_bpermute_b32 v37, v158, v36
	s_waitcnt lgkmcnt(0)
	v_add_f32_e32 v36, v36, v37
	ds_bpermute_b32 v37, v159, v36
	s_waitcnt lgkmcnt(0)
	v_add_f32_e32 v36, v36, v37
	v_fmamk_f32 v36, v36, 0x3a800000, v210
	v_mul_f32_e32 v37, 0x4b800000, v36
	v_cmp_gt_f32_e64 s[8:9], s39, v36
	s_nop 1
	v_cndmask_b32_e64 v36, v36, v37, s[8:9]
	v_rsq_f32_e32 v36, v36
	s_nop 0
	v_mul_f32_e32 v37, 0x45800000, v36
	v_cndmask_b32_e64 v36, v36, v37, s[8:9]
	v_pk_mul_f32 v[40:41], v[30:31], v[36:37] op_sel_hi:[1,0]
	v_pk_mul_f32 v[38:39], v[28:29], v[36:37] op_sel_hi:[1,0]
	v_pk_mul_f32 v[30:31], v[26:27], v[36:37] op_sel_hi:[1,0]
	v_pk_mul_f32 v[28:29], v[24:25], v[36:37] op_sel_hi:[1,0]
	s_cbranch_vccnz .LBB0_387
	v_mul_f32_e32 v26, 0x3d122279, v39
	v_fmaak_f32 v26, v39, v26, 0x3f4c422a
	v_mul_f32_e32 v26, v39, v26
	v_mul_f32_e32 v25, 0x3d122279, v28
	v_mul_f32_e32 v26, 0xc038aa3b, v26
	v_fmaak_f32 v25, v28, v25, 0x3f4c422a
	v_exp_f32_e32 v27, v26
	v_mul_f32_e32 v26, 0x3d122279, v29
	v_mul_f32_e32 v25, v28, v25
	v_fmaak_f32 v26, v29, v26, 0x3f4c422a
	v_mul_f32_e32 v25, 0xc038aa3b, v25
	v_mul_f32_e32 v26, v29, v26
	v_exp_f32_e32 v25, v25
	v_mul_f32_e32 v26, 0xc038aa3b, v26
	v_exp_f32_e32 v37, v26
	v_mul_f32_e32 v42, 0x3d122279, v30
	v_add_f32_e32 v25, 1.0, v25
	v_rcp_f32_e32 v26, v25
	v_add_f32_e32 v25, 1.0, v27
	v_add_f32_e32 v27, 1.0, v37
	v_mul_f32_e32 v37, 0x3d122279, v40
	v_fmaak_f32 v37, v40, v37, 0x3f4c422a
	v_mul_f32_e32 v37, v40, v37
	v_fmaak_f32 v42, v30, v42, 0x3f4c422a
	v_mul_f32_e32 v37, 0xc038aa3b, v37
	v_mul_f32_e32 v42, v30, v42
	v_exp_f32_e32 v37, v37
	v_mul_f32_e32 v42, 0xc038aa3b, v42
	v_exp_f32_e32 v43, v42
	v_mul_f32_e32 v24, 0x3d122279, v38
	v_add_f32_e32 v37, 1.0, v37
	v_rcp_f32_e32 v42, v37
	v_add_f32_e32 v37, 1.0, v43
	v_mul_f32_e32 v43, 0x3d122279, v41
	v_fmaak_f32 v43, v41, v43, 0x3f4c422a
	v_mul_f32_e32 v44, 0x3d122279, v31
	v_fmaak_f32 v24, v38, v24, 0x3f4c422a
	v_mul_f32_e32 v43, v41, v43
	v_fmaak_f32 v44, v31, v44, 0x3f4c422a
	v_mul_f32_e32 v24, v38, v24
	v_mul_f32_e32 v43, 0xc038aa3b, v43
	v_mul_f32_e32 v44, v31, v44
	v_mul_f32_e32 v24, 0xc038aa3b, v24
	v_exp_f32_e32 v43, v43
	v_mul_f32_e32 v44, 0xc038aa3b, v44
	v_exp_f32_e32 v24, v24
	v_exp_f32_e32 v45, v44
	v_rcp_f32_e32 v44, v37
	v_add_f32_e32 v37, 1.0, v43
	v_add_f32_e32 v24, 1.0, v24
	v_rcp_f32_e32 v27, v27
	v_rcp_f32_e32 v43, v37
	v_add_f32_e32 v37, 1.0, v45
	v_rcp_f32_e32 v24, v24
	v_rcp_f32_e32 v25, v25
	v_rcp_f32_e32 v45, v37
	v_pk_mul_f32 v[28:29], v[28:29], v[26:27]
	v_pk_mul_f32 v[40:41], v[40:41], v[42:43]
	v_pk_mul_f32 v[38:39], v[38:39], v[24:25]
	v_pk_mul_f32 v[24:25], v[28:29], v[28:29]
	v_pk_mul_f32 v[30:31], v[30:31], v[44:45]
	v_pk_fma_f32 v[24:25], v[38:39], v[38:39], v[24:25]
	v_pk_mul_f32 v[26:27], v[30:31], v[30:31]
	v_add_f32_e32 v24, v24, v25
	v_pk_fma_f32 v[26:27], v[40:41], v[40:41], v[26:27]
	s_nop 0
	v_add_f32_e32 v24, v26, v24
	v_add_f32_e32 v42, v27, v24

; __device__ __forceinline__ float row_rstd(const float* rss, long row, int fq) {
;     const f32x4 p = *(const f32x4*)(rss + row * 16 + fq * 4); float s = (p[0] + p[1]) + (p[2] + p[3]); s += __shfl_xor(s, 16); s += __shfl_xor(s, 32);
;     return rsqrtf(s * (1.0f / 1024.0f) + 1e-6f);
;     __device__ __forceinline__ void operator()(const f32x4 (&acc)[2][2][4][2], const Unit& u, int wr, int wc, int fr, int fq) const {
;     ...
;             for (int m = 0; m < 4; ++m) { const int row = row0 + ai * HALF + m * 16; bf16_t* rowp = base + (size_t)row * 1024 + col0; float ss = 0.f; const float rn = row_rstd(rss, row, fq);
; #pragma unroll
;                 for (int bj = 0; bj < 2; ++bj) { f32x4 v0 = acc[ai][bj][m][0] * rn, v1 = acc[ai][bj][m][1] * rn;
;                     if (t <= 1) {
; #pragma unroll
;                         for (int j = 0; j < 4; ++j) { v0[j] = gelu_t(v0[j]); v1[j] = gelu_t(v1[j]); }
; #pragma unroll
;                         for (int j = 0; j < 4; ++j) ss += v0[j] * v0[j] + v1[j] * v1[j];
.LBB0_393:
	s_nop 0
	v_add_u32_e32 v18, 0xb0, v142
	v_ashrrev_i32_e32 v19, 31, v18
	s_waitcnt lgkmcnt(0)
	v_lshlrev_b64 v[16:17], 6, v[18:19]
	s_and_b64 vcc, exec, s[4:5]
	v_mov_b32_e32 v26, 0
	s_waitcnt vmcnt(14)
	v_mov_b32_e32 v24, v189
	v_mov_b32_e32 v25, v190
	v_mov_b32_e32 v21, v191
	v_mov_b32_e32 v20, v188
	v_pk_add_f32 v[20:21], v[24:25], v[20:21]
	s_nop 0
	v_add_f32_e32 v20, v20, v21
	ds_bpermute_b32 v21, v158, v20
	s_waitcnt lgkmcnt(0)
	v_add_f32_e32 v20, v20, v21
	ds_bpermute_b32 v21, v159, v20
	s_waitcnt lgkmcnt(0)
	v_add_f32_e32 v20, v20, v21
	v_fmamk_f32 v20, v20, 0x3a800000, v210
	v_mul_f32_e32 v21, 0x4b800000, v20
	v_cmp_gt_f32_e64 s[8:9], s39, v20
	s_nop 1
	v_cndmask_b32_e64 v20, v20, v21, s[8:9]
	v_rsq_f32_e32 v20, v20
	s_nop 0
	v_mul_f32_e32 v21, 0x45800000, v20
	v_cndmask_b32_e64 v20, v20, v21, s[8:9]
	v_pk_mul_f32 v[24:25], v[14:15], v[20:21] op_sel_hi:[1,0]
	v_pk_mul_f32 v[22:23], v[12:13], v[20:21] op_sel_hi:[1,0]
	v_pk_mul_f32 v[14:15], v[10:11], v[20:21] op_sel_hi:[1,0]
	v_pk_mul_f32 v[12:13], v[8:9], v[20:21] op_sel_hi:[1,0]
	s_cbranch_vccnz .LBB0_395
	v_mul_f32_e32 v10, 0x3d122279, v23
	v_fmaak_f32 v10, v23, v10, 0x3f4c422a
	v_mul_f32_e32 v10, v23, v10
	v_mul_f32_e32 v9, 0x3d122279, v12
	v_mul_f32_e32 v10, 0xc038aa3b, v10
	v_fmaak_f32 v9, v12, v9, 0x3f4c422a
	v_exp_f32_e32 v11, v10
	v_mul_f32_e32 v10, 0x3d122279, v13
	v_mul_f32_e32 v9, v12, v9
	v_fmaak_f32 v10, v13, v10, 0x3f4c422a
	v_mul_f32_e32 v9, 0xc038aa3b, v9
	v_mul_f32_e32 v10, v13, v10
	v_exp_f32_e32 v9, v9
	v_mul_f32_e32 v10, 0xc038aa3b, v10
	v_exp_f32_e32 v21, v10
	v_mul_f32_e32 v26, 0x3d122279, v14
	v_add_f32_e32 v9, 1.0, v9
	v_rcp_f32_e32 v10, v9
	v_add_f32_e32 v9, 1.0, v11
	v_add_f32_e32 v11, 1.0, v21
	v_mul_f32_e32 v21, 0x3d122279, v24
	v_fmaak_f32 v21, v24, v21, 0x3f4c422a
	v_mul_f32_e32 v21, v24, v21
	v_fmaak_f32 v26, v14, v26, 0x3f4c422a
	v_mul_f32_e32 v21, 0xc038aa3b, v21
	v_mul_f32_e32 v26, v14, v26
	v_exp_f32_e32 v21, v21
	v_mul_f32_e32 v26, 0xc038aa3b, v26
	v_exp_f32_e32 v27, v26
	v_mul_f32_e32 v8, 0x3d122279, v22
	v_add_f32_e32 v21, 1.0, v21
	v_rcp_f32_e32 v26, v21
	v_add_f32_e32 v21, 1.0, v27
	v_mul_f32_e32 v27, 0x3d122279, v25
	v_fmaak_f32 v27, v25, v27, 0x3f4c422a
	v_mul_f32_e32 v28, 0x3d122279, v15
	v_fmaak_f32 v8, v22, v8, 0x3f4c422a
	v_mul_f32_e32 v27, v25, v27
	v_fmaak_f32 v28, v15, v28, 0x3f4c422a
	v_mul_f32_e32 v8, v22, v8
	v_mul_f32_e32 v27, 0xc038aa3b, v27
	v_mul_f32_e32 v28, v15, v28
	v_mul_f32_e32 v8, 0xc038aa3b, v8
	v_exp_f32_e32 v27, v27
	v_mul_f32_e32 v28, 0xc038aa3b, v28
	v_exp_f32_e32 v8, v8
	v_exp_f32_e32 v29, v28
	v_rcp_f32_e32 v28, v21
	v_add_f32_e32 v21, 1.0, v27
	v_add_f32_e32 v8, 1.0, v8
	v_rcp_f32_e32 v11, v11
	v_rcp_f32_e32 v27, v21
	v_add_f32_e32 v21, 1.0, v29
	v_rcp_f32_e32 v8, v8
	v_rcp_f32_e32 v9, v9
	v_rcp_f32_e32 v29, v21
	v_pk_mul_f32 v[12:13], v[12:13], v[10:11]
	v_pk_mul_f32 v[24:25], v[24:25], v[26:27]
	v_pk_mul_f32 v[22:23], v[22:23], v[8:9]
	v_pk_mul_f32 v[8:9], v[12:13], v[12:13]
	v_pk_mul_f32 v[14:15], v[14:15], v[28:29]
	v_pk_fma_f32 v[8:9], v[22:23], v[22:23], v[8:9]
	v_pk_mul_f32 v[10:11], v[14:15], v[14:15]
	v_add_f32_e32 v8, v8, v9
	v_pk_fma_f32 v[10:11], v[24:25], v[24:25], v[10:11]
	s_nop 0
	v_add_f32_e32 v8, v10, v8
	v_add_f32_e32 v26, v11, v8

; __global__ void __launch_bounds__(NWAVES * 64, 2) mk_fwd(Args args) {
	.amdhsa_kernel _Z6mk_fwd4Args
		.amdhsa_group_segment_fixed_size 0
		.amdhsa_private_segment_fixed_size 0
		.amdhsa_kernarg_size 456
		.amdhsa_user_sgpr_count 2
		.amdhsa_user_sgpr_dispatch_ptr 0
		.amdhsa_user_sgpr_queue_ptr 0
		.amdhsa_user_sgpr_kernarg_segment_ptr 1
		.amdhsa_user_sgpr_dispatch_id 0
		.amdhsa_user_sgpr_kernarg_preload_length 0
		.amdhsa_user_sgpr_kernarg_preload_offset 0
		.amdhsa_user_sgpr_private_segment_size 0
		.amdhsa_uses_dynamic_stack 0
		.amdhsa_enable_private_segment 0
		.amdhsa_system_sgpr_workgroup_id_x 1
		.amdhsa_system_sgpr_workgroup_id_y 0
		.amdhsa_system_sgpr_workgroup_id_z 0
		.amdhsa_system_sgpr_workgroup_info 0
		.amdhsa_system_vgpr_workitem_id 2
		.amdhsa_next_free_vgpr 256
		.amdhsa_next_free_sgpr 98
		.amdhsa_accum_offset 256
		.amdhsa_reserve_vcc 1
		.amdhsa_float_round_mode_32 0
		.amdhsa_float_round_mode_16_64 0
		.amdhsa_float_denorm_mode_32 3
		.amdhsa_float_denorm_mode_16_64 3
		.amdhsa_dx10_clamp 1
		.amdhsa_ieee_mode 1
		.amdhsa_fp16_overflow 0
		.amdhsa_tg_split 0
		.amdhsa_exception_fp_ieee_invalid_op 0
		.amdhsa_exception_fp_denorm_src 0
		.amdhsa_exception_fp_ieee_div_zero 0
		.amdhsa_exception_fp_ieee_overflow 0
		.amdhsa_exception_fp_ieee_underflow 0
		.amdhsa_exception_fp_ieee_inexact 0
		.amdhsa_exception_int_div_zero 0
	.end_amdhsa_kernel

; __global__ void __launch_bounds__(NWAVES * 64, 2) mk_fwd(Args args) {
amdhsa.kernels:
  - .agpr_count:     0
    .args:
      - .offset:         0
        .size:           200
        .value_kind:     by_value
      - .offset:         200
        .size:           4
        .value_kind:     hidden_block_count_x
      - .offset:         204
        .size:           4
        .value_kind:     hidden_block_count_y
      - .offset:         208
        .size:           4
        .value_kind:     hidden_block_count_z
      - .offset:         212
        .size:           2
        .value_kind:     hidden_group_size_x
      - .offset:         214
        .size:           2
        .value_kind:     hidden_group_size_y
      - .offset:         216
        .size:           2
        .value_kind:     hidden_group_size_z
      - .offset:         218
        .size:           2
        .value_kind:     hidden_remainder_x
      - .offset:         220
        .size:           2
        .value_kind:     hidden_remainder_y
      - .offset:         222
        .size:           2
        .value_kind:     hidden_remainder_z
      - .offset:         240
        .size:           8
        .value_kind:     hidden_global_offset_x
      - .offset:         248
        .size:           8
        .value_kind:     hidden_global_offset_y
      - .offset:         256
        .size:           8
        .value_kind:     hidden_global_offset_z
      - .offset:         264
        .size:           2
        .value_kind:     hidden_grid_dims
      - .offset:         288
        .size:           8
        .value_kind:     hidden_multigrid_sync_arg
      - .offset:         320
        .size:           4
        .value_kind:     hidden_dynamic_lds_size
    .group_segment_fixed_size: 0
    .kernarg_segment_align: 8
    .kernarg_segment_size: 456
    .language:       OpenCL C
    .language_version:
      - 2
      - 0
    .max_flat_workgroup_size: 512
    .name:           _Z6mk_fwd4Args
    .private_segment_fixed_size: 0
    .sgpr_count:     104
    .sgpr_spill_count: 153
    .symbol:         _Z6mk_fwd4Args.kd
    .uniform_work_group_size: 1
    .uses_dynamic_stack: false
    .vgpr_count:     256
    .vgpr_spill_count: 0
    .wavefront_size: 64
